# mem_attn softmax: wave-uniform fast path skipping expf denormal-range fixup when no element needs it (bit-identical), on top of c13; dtype comment added
# baseline (speedup 1.0000x reference)
; DI f32x4 mfma16(bf16x8 a, bf16x8 b, f32x4 c) { return __builtin_amdgcn_mfma_f32_16x16x32_bf16(a, b, c, 0, 0, 0); }
; DI void mem_attn_item(ldsp lds, const bf16_t* proj, int ldp, int qmcol, int gatecol, const bf16_t* kv, bf16_t* branch, int b0, int item, int tid, int wid, int lane, const bool stage = true) {
;     ...
;     const int li = lane & 15, quad = lane >> 4;
;     const int tq = 128 * qt + 16 * wid + li;
;     const size_t prow = (size_t)bl * 2048 + tq;
;     bf16x8 qf[2];
; #pragma unroll
;     for (int ks = 0; ks < 2; ++ks) qf[ks] = *(const bf16x8*)(proj + prow * ldp + qmcol + hm * 64 + ks * 32 + quad * 8);
;     u32x2 gtv[4];
; #pragma unroll
;     for (int dt = 0; dt < 4; ++dt) gtv[dt] = *(const u32x2*)(proj + prow * ldp + gatecol + 768 + hm * 64 + quad * 4 + dt * 16);
;     __syncthreads();
;     f32x4 sacc[16];
; #pragma unroll
;     for (int t = 0; t < 16; ++t) {
;         sacc[t] = (f32x4){0.f, 0.f, 0.f, 0.f};
;         const ldsp ka = Kb + (16 * t + li) * KS + quad * 16;
; #pragma unroll
;         for (int ks = 0; ks < 2; ++ks) sacc[t] = mfma16(lds_rd8(ka + ks * 64), qf[ks], sacc[t]);
;     }
.LBB0_444:
	v_readlane_b32 s15, v252, 2
	s_or_b32 s14, s14, s15
	s_lshl_b32 s14, s14, 7
	s_and_b32 s14, s14, 0x780
	v_add_u32_e32 v94, s14, v13
	v_ashrrev_i32_e32 v95, 31, v94
	v_lshlrev_b64 v[0:1], 14, v[94:95]
	v_lshl_add_u64 v[0:1], s[38:39], 0, v[0:1]
	v_lshlrev_b32_e32 v2, 1, v30
	v_mov_b32_e32 v3, v12
	v_lshl_add_u64 v[4:5], v[0:1], 0, s[0:1]
	v_lshl_add_u64 v[0:1], v[4:5], 0, v[2:3]
	s_movk_i32 s15, 0x3000
	v_lshl_add_u64 v[2:3], v[0:1], 0, s[76:77]
	v_add_co_u32_e32 v0, vcc, s15, v0
	v_mov_b32_e32 v85, v12
	s_nop 0
	v_addc_co_u32_e32 v1, vcc, 0, v1, vcc
	global_load_dwordx4 v[70:73], v[0:1], off offset:1536
	s_nop 0
	global_load_dwordx4 v[0:3], v[2:3], off offset:64
	v_lshl_add_u64 v[4:5], v[4:5], 0, v[84:85]
	v_lshl_add_u64 v[6:7], v[4:5], 0, s[80:81]
	v_add_co_u32_e32 v4, vcc, s15, v4
	s_mov_b32 s15, 0xff800000
	s_nop 0
	v_addc_co_u32_e32 v5, vcc, 0, v5, vcc
	global_load_dwordx2 v[92:93], v[4:5], off offset:3584
	global_load_dwordx2 v[90:91], v[6:7], off offset:32
	global_load_dwordx2 v[88:89], v[6:7], off offset:64
	global_load_dwordx2 v[86:87], v[6:7], off offset:96
	s_waitcnt lgkmcnt(0)
	s_barrier
	ds_read_b128 v[4:7], v102
	ds_read_b128 v[8:11], v102 offset:64
	s_mov_b32 s14, 1
	s_waitcnt vmcnt(5) lgkmcnt(1)
	v_mfma_f32_16x16x32_bf16 v[4:7], v[4:7], v[70:73], 0
	ds_read_b128 v[108:111], v102 offset:32320
	s_waitcnt vmcnt(4) lgkmcnt(1)
	v_mfma_f32_16x16x32_bf16 v[66:69], v[8:11], v[0:3], v[4:7]
	ds_read_b128 v[8:11], v102 offset:2368
	s_nop 3
	ds_read_b128 v[4:7], v102 offset:2304
	s_waitcnt lgkmcnt(0)
	v_mfma_f32_16x16x32_bf16 v[4:7], v[4:7], v[70:73], 0
	v_mfma_f32_16x16x32_bf16 v[62:65], v[8:11], v[0:3], v[4:7]
	ds_read_b128 v[8:11], v102 offset:4672
	s_nop 5
	ds_read_b128 v[4:7], v102 offset:4608
	s_waitcnt lgkmcnt(0)
	v_mfma_f32_16x16x32_bf16 v[4:7], v[4:7], v[70:73], 0
	v_mfma_f32_16x16x32_bf16 v[58:61], v[8:11], v[0:3], v[4:7]
	ds_read_b128 v[8:11], v103 offset:64
	s_nop 5
	ds_read_b128 v[4:7], v103
	s_waitcnt lgkmcnt(0)
	v_mfma_f32_16x16x32_bf16 v[4:7], v[4:7], v[70:73], 0
	v_mfma_f32_16x16x32_bf16 v[54:57], v[8:11], v[0:3], v[4:7]
	ds_read_b128 v[8:11], v102 offset:9280
	s_nop 5
	ds_read_b128 v[4:7], v102 offset:9216
	s_waitcnt lgkmcnt(0)
	v_mfma_f32_16x16x32_bf16 v[4:7], v[4:7], v[70:73], 0
	v_mfma_f32_16x16x32_bf16 v[50:53], v[8:11], v[0:3], v[4:7]
	ds_read_b128 v[8:11], v102 offset:11584
	s_nop 5
	ds_read_b128 v[4:7], v102 offset:11520
	s_waitcnt lgkmcnt(0)
	v_mfma_f32_16x16x32_bf16 v[4:7], v[4:7], v[70:73], 0
	v_mfma_f32_16x16x32_bf16 v[46:49], v[8:11], v[0:3], v[4:7]
	ds_read_b128 v[8:11], v102 offset:13888
	s_nop 5
	ds_read_b128 v[4:7], v102 offset:13824
	s_waitcnt lgkmcnt(0)
	v_mfma_f32_16x16x32_bf16 v[4:7], v[4:7], v[70:73], 0
	v_mfma_f32_16x16x32_bf16 v[42:45], v[8:11], v[0:3], v[4:7]
	ds_read_b128 v[8:11], v104 offset:64
	s_nop 5
	ds_read_b128 v[4:7], v104
	s_waitcnt lgkmcnt(0)
	v_mfma_f32_16x16x32_bf16 v[4:7], v[4:7], v[70:73], 0
	v_mfma_f32_16x16x32_bf16 v[38:41], v[8:11], v[0:3], v[4:7]
	ds_read_b128 v[8:11], v102 offset:18496
	s_nop 5
	ds_read_b128 v[4:7], v102 offset:18432
	s_waitcnt lgkmcnt(0)
	v_mfma_f32_16x16x32_bf16 v[4:7], v[4:7], v[70:73], 0
	v_mfma_f32_16x16x32_bf16 v[34:37], v[8:11], v[0:3], v[4:7]
	ds_read_b128 v[8:11], v102 offset:20800
	s_nop 5
	ds_read_b128 v[4:7], v102 offset:20736
	s_waitcnt lgkmcnt(0)
	v_mfma_f32_16x16x32_bf16 v[4:7], v[4:7], v[70:73], 0
	v_mfma_f32_16x16x32_bf16 v[26:29], v[8:11], v[0:3], v[4:7]
	ds_read_b128 v[8:11], v102 offset:23104
	s_nop 5
	ds_read_b128 v[4:7], v102 offset:23040
	s_waitcnt lgkmcnt(0)
	v_mfma_f32_16x16x32_bf16 v[4:7], v[4:7], v[70:73], 0
	v_mfma_f32_16x16x32_bf16 v[22:25], v[8:11], v[0:3], v[4:7]
	ds_read_b128 v[8:11], v105 offset:64
	s_nop 5
	ds_read_b128 v[4:7], v105
	s_waitcnt lgkmcnt(0)
	v_mfma_f32_16x16x32_bf16 v[4:7], v[4:7], v[70:73], 0
	v_mfma_f32_16x16x32_bf16 v[14:17], v[8:11], v[0:3], v[4:7]
	ds_read_b128 v[8:11], v102 offset:27712
	s_nop 5
	ds_read_b128 v[4:7], v102 offset:27648
	s_waitcnt lgkmcnt(0)
	v_mfma_f32_16x16x32_bf16 v[4:7], v[4:7], v[70:73], 0
	v_mfma_f32_16x16x32_bf16 v[18:21], v[8:11], v[0:3], v[4:7]
	ds_read_b128 v[8:11], v102 offset:30016
	s_nop 5
	ds_read_b128 v[4:7], v102 offset:29952
	s_waitcnt lgkmcnt(0)
	v_mfma_f32_16x16x32_bf16 v[4:7], v[4:7], v[70:73], 0
	v_mfma_f32_16x16x32_bf16 v[8:11], v[8:11], v[0:3], v[4:7]
	s_nop 6
	ds_read_b128 v[4:7], v102 offset:32256
	s_waitcnt lgkmcnt(0)
	v_mfma_f32_16x16x32_bf16 v[4:7], v[4:7], v[70:73], 0
	v_mfma_f32_16x16x32_bf16 v[4:7], v[108:111], v[0:3], v[4:7]
	ds_read_b128 v[108:111], v106
	s_waitcnt lgkmcnt(0)
	v_mfma_f32_16x16x32_bf16 v[70:73], v[108:111], v[70:73], 0
	ds_read_b128 v[108:111], v106 offset:64
	s_waitcnt lgkmcnt(0)
; DI void mem_attn_item(ldsp lds, const bf16_t* proj, int ldp, int qmcol, int gatecol, const bf16_t* kv, bf16_t* branch, int b0, int item, int tid, int wid, int lane, const bool stage = true) {
;     ...
;     float mx = -INFINITY;
; #pragma unroll
;     for (int t = 0; t < 16; ++t)
; #pragma unroll
;         for (int j = 0; j < 4; ++j) { const float v = sacc[t][j] * 0.125f; sacc[t][j] = v; mx = fmaxf(mx, v); }
;     mx = fmaxf(mx, __shfl_xor(mx, 16)); mx = fmaxf(mx, __shfl_xor(mx, 32));
;     float den = 0.f;
; #pragma unroll
;     for (int t = 0; t < 16; ++t)
; #pragma unroll
;         for (int j = 0; j < 4; ++j) { const float pv = exp2f((sacc[t][j] - mx) * 1.4426950408889634f); sacc[t][j] = pv; den += pv; }
	v_mfma_f32_16x16x32_bf16 v[0:3], v[108:111], v[0:3], v[70:73]
	s_nop 4
	v_mul_f32_e32 v70, 0x3e000000, v66
	v_mul_f32_e32 v71, 0x3e000000, v67
	v_max3_f32 v70, v70, s15, v71
	v_mul_f32_e32 v71, 0x3e000000, v68
	v_mul_f32_e32 v72, 0x3e000000, v69
	v_max3_f32 v70, v70, v71, v72
	v_mul_f32_e32 v71, 0x3e000000, v62
	v_mul_f32_e32 v72, 0x3e000000, v63
	v_max3_f32 v70, v70, v71, v72
	v_mul_f32_e32 v71, 0x3e000000, v64
	v_mul_f32_e32 v72, 0x3e000000, v65
	v_max3_f32 v70, v70, v71, v72
	v_mul_f32_e32 v71, 0x3e000000, v58
	v_mul_f32_e32 v72, 0x3e000000, v59
	v_max3_f32 v70, v70, v71, v72
	v_mul_f32_e32 v71, 0x3e000000, v60
	v_mul_f32_e32 v72, 0x3e000000, v61
	v_max3_f32 v70, v70, v71, v72
	v_mul_f32_e32 v71, 0x3e000000, v54
	v_mul_f32_e32 v72, 0x3e000000, v55
	v_max3_f32 v70, v70, v71, v72
	v_mul_f32_e32 v71, 0x3e000000, v56
	v_mul_f32_e32 v72, 0x3e000000, v57
	v_max3_f32 v70, v70, v71, v72
	v_mul_f32_e32 v71, 0x3e000000, v50
	v_mul_f32_e32 v72, 0x3e000000, v51
	v_max3_f32 v70, v70, v71, v72
	v_mul_f32_e32 v71, 0x3e000000, v52
	v_mul_f32_e32 v72, 0x3e000000, v53
	v_max3_f32 v70, v70, v71, v72
	v_mul_f32_e32 v71, 0x3e000000, v46
	v_mul_f32_e32 v72, 0x3e000000, v47
	v_max3_f32 v70, v70, v71, v72
	v_mul_f32_e32 v71, 0x3e000000, v48
	v_mul_f32_e32 v72, 0x3e000000, v49
	v_max3_f32 v70, v70, v71, v72
	v_mul_f32_e32 v71, 0x3e000000, v42
	v_mul_f32_e32 v72, 0x3e000000, v43
	v_max3_f32 v70, v70, v71, v72
	v_mul_f32_e32 v71, 0x3e000000, v44
	v_mul_f32_e32 v72, 0x3e000000, v45
	v_max3_f32 v70, v70, v71, v72
	v_mul_f32_e32 v71, 0x3e000000, v38
	v_mul_f32_e32 v72, 0x3e000000, v39
	v_max3_f32 v70, v70, v71, v72
	v_mul_f32_e32 v71, 0x3e000000, v40
	v_mul_f32_e32 v72, 0x3e000000, v41
	v_max3_f32 v70, v70, v71, v72
	v_mul_f32_e32 v71, 0x3e000000, v34
	v_mul_f32_e32 v72, 0x3e000000, v35
	v_max3_f32 v70, v70, v71, v72
	v_mul_f32_e32 v71, 0x3e000000, v36
	v_mul_f32_e32 v72, 0x3e000000, v37
	v_max3_f32 v70, v70, v71, v72
	v_mul_f32_e32 v71, 0x3e000000, v26
	v_mul_f32_e32 v72, 0x3e000000, v27
	v_max3_f32 v70, v70, v71, v72
	v_mul_f32_e32 v71, 0x3e000000, v28
	v_mul_f32_e32 v72, 0x3e000000, v29
	v_max3_f32 v70, v70, v71, v72
	v_mul_f32_e32 v71, 0x3e000000, v22
	v_mul_f32_e32 v72, 0x3e000000, v23
	v_max3_f32 v70, v70, v71, v72
	v_mul_f32_e32 v71, 0x3e000000, v24
	v_mul_f32_e32 v72, 0x3e000000, v25
	v_max3_f32 v70, v70, v71, v72
	v_mul_f32_e32 v71, 0x3e000000, v14
	v_mul_f32_e32 v72, 0x3e000000, v15
	v_max3_f32 v70, v70, v71, v72
	v_mul_f32_e32 v71, 0x3e000000, v16
	v_mul_f32_e32 v72, 0x3e000000, v17
	v_max3_f32 v70, v70, v71, v72
	v_mul_f32_e32 v71, 0x3e000000, v18
	v_mul_f32_e32 v72, 0x3e000000, v19
	v_max3_f32 v70, v70, v71, v72
	v_mul_f32_e32 v71, 0x3e000000, v20
	v_mul_f32_e32 v72, 0x3e000000, v21
	v_max3_f32 v70, v70, v71, v72
	v_mul_f32_e32 v71, 0x3e000000, v8
	v_mul_f32_e32 v72, 0x3e000000, v9
	v_max3_f32 v70, v70, v71, v72
	v_mul_f32_e32 v71, 0x3e000000, v10
	v_mul_f32_e32 v72, 0x3e000000, v11
	v_max3_f32 v70, v70, v71, v72
	v_mul_f32_e32 v71, 0x3e000000, v4
	v_mul_f32_e32 v72, 0x3e000000, v5
	v_max3_f32 v70, v70, v71, v72
	v_mul_f32_e32 v71, 0x3e000000, v6
	v_mul_f32_e32 v72, 0x3e000000, v7
	v_max3_f32 v70, v70, v71, v72
	v_mul_f32_e32 v71, 0x3e000000, v0
	v_mul_f32_e32 v72, 0x3e000000, v1
	v_max3_f32 v70, v70, v71, v72
	v_mul_f32_e32 v71, 0x3e000000, v2
	v_mul_f32_e32 v72, 0x3e000000, v3
	v_max3_f32 v70, v70, v71, v72
	ds_bpermute_b32 v71, v33, v70
	v_min3_f32 v224, v66, v67, v68
	v_min3_f32 v224, v224, v69, v62
	v_min3_f32 v224, v224, v63, v64
	v_min3_f32 v224, v224, v65, v58
	v_min3_f32 v224, v224, v59, v60
	v_min3_f32 v224, v224, v61, v54
	v_min3_f32 v224, v224, v55, v56
	v_min3_f32 v224, v224, v57, v50
	v_min3_f32 v224, v224, v51, v52
	v_min3_f32 v224, v224, v53, v46
	v_min3_f32 v224, v224, v47, v48
	v_min3_f32 v224, v224, v49, v42
	v_min3_f32 v224, v224, v43, v44
	v_min3_f32 v224, v224, v45, v38
	v_min3_f32 v224, v224, v39, v40
	v_min3_f32 v224, v224, v41, v34
	s_waitcnt lgkmcnt(0)
	v_max_f32_e32 v71, v71, v71
	v_max_f32_e32 v70, v70, v71
	ds_bpermute_b32 v71, v96, v70
	v_min3_f32 v224, v224, v35, v36
	v_min3_f32 v224, v224, v37, v26
	v_min3_f32 v224, v224, v27, v28
	v_min3_f32 v224, v224, v29, v22
	v_min3_f32 v224, v224, v23, v24
	v_min3_f32 v224, v224, v25, v14
	v_min3_f32 v224, v224, v15, v16
	v_min3_f32 v224, v224, v17, v18
	v_min3_f32 v224, v224, v19, v20
	v_min3_f32 v224, v224, v21, v8
	v_min3_f32 v224, v224, v9, v10
	v_min3_f32 v224, v224, v11, v4
	v_min3_f32 v224, v224, v5, v6
	v_min3_f32 v224, v224, v7, v0
	v_min3_f32 v224, v224, v1, v2
	v_min_f32_e32 v224, v224, v3
	s_waitcnt lgkmcnt(0)
	v_max_f32_e32 v71, v71, v71
	v_max_f32_e32 v85, v70, v71
	v_fma_f32 v225, v224, s85, -v85
	v_mul_f32_e32 v225, 0x3fb8aa3b, v225
	v_cmp_gt_f32_e32 vcc, s86, v225
	s_cbranch_vccnz .Lma_slow_dil
; DI unsigned cvt_pk_bf16(float lo, float hi) { const f32x2_t v = {lo, hi}; const bf16v2_t b = __builtin_convertvector(v, bf16v2_t); return __builtin_bit_cast(unsigned, b); }
; DI f32x4 mfma16(bf16x8 a, bf16x8 b, f32x4 c) { return __builtin_amdgcn_mfma_f32_16x16x32_bf16(a, b, c, 0, 0, 0); }
; DI void mem_attn_item(ldsp lds, const bf16_t* proj, int ldp, int qmcol, int gatecol, const bf16_t* kv, bf16_t* branch, int b0, int item, int tid, int wid, int lane, const bool stage = true) {
;     ...
;     float den = 0.f;
; #pragma unroll
;     for (int t = 0; t < 16; ++t)
; #pragma unroll
;         for (int j = 0; j < 4; ++j) { const float pv = exp2f((sacc[t][j] - mx) * 1.4426950408889634f); sacc[t][j] = pv; den += pv; }
;     den += __shfl_xor(den, 16); den += __shfl_xor(den, 32);
;     f32x4 oacc[4];
; #pragma unroll
;     for (int dt = 0; dt < 4; ++dt) oacc[dt] = (f32x4){0.f, 0.f, 0.f, 0.f};
; #pragma unroll
;     for (int kt = 0; kt < 8; ++kt) {
;         u32x4 pw; pw.x = cvt_pk_bf16(sacc[2 * kt][0], sacc[2 * kt][1]); pw.y = cvt_pk_bf16(sacc[2 * kt][2], sacc[2 * kt][3]);
;         pw.z = cvt_pk_bf16(sacc[2 * kt + 1][0], sacc[2 * kt + 1][1]); pw.w = cvt_pk_bf16(sacc[2 * kt + 1][2], sacc[2 * kt + 1][3]);
;         const bf16x8 pf = __builtin_bit_cast(bf16x8, pw);
;         const ldsp va = Vb + (32 * kt + quad * 4 + (li >> 2)) * KS + (li & 3) * 8;
; #pragma unroll
;         for (int dt = 0; dt < 4; ++dt) oacc[dt] = mfma16(lds_tr8(va + dt * 32, va + 16 * KS + dt * 32), pf, oacc[dt]);
;     }
	v_fma_f32 v66, v66, s85, -v85
	v_mul_f32_e32 v70, 0x3fb8aa3b, v66
	v_fma_f32 v67, v67, s85, -v85
	v_fma_f32 v68, v68, s85, -v85
	v_exp_f32_e32 v66, v70
	v_mul_f32_e32 v71, 0x3fb8aa3b, v68
	v_fma_f32 v69, v69, s85, -v85
	v_mul_f32_e32 v70, 0x3fb8aa3b, v67
	v_fma_f32 v62, v62, s85, -v85
	v_fma_f32 v63, v63, s85, -v85
	v_exp_f32_e32 v67, v70
	v_fma_f32 v58, v58, s85, -v85
	v_exp_f32_e32 v68, v71
	v_add_f32_e32 v70, v66, v67
	v_fma_f32 v59, v59, s85, -v85
	v_mul_f32_e32 v71, 0x3fb8aa3b, v69
	v_add_f32_e32 v70, v68, v70
	v_fma_f32 v60, v60, s85, -v85
	v_exp_f32_e32 v69, v71
	v_fma_f32 v61, v61, s85, -v85
	v_fma_f32 v54, v54, s85, -v85
	v_add_f32_e32 v71, v69, v70
	v_mul_f32_e32 v70, 0x3fb8aa3b, v62
	v_fma_f32 v55, v55, s85, -v85
	v_fma_f32 v56, v56, s85, -v85
	v_exp_f32_e32 v62, v70
	v_fma_f32 v57, v57, s85, -v85
	v_fma_f32 v50, v50, s85, -v85
	v_mov_b32_e32 v70, v62
	v_add_f32_e32 v62, v70, v71
	v_mul_f32_e32 v71, 0x3fb8aa3b, v63
	v_fma_f32 v51, v51, s85, -v85
	v_fma_f32 v52, v52, s85, -v85
	v_exp_f32_e32 v63, v71
	v_fma_f32 v53, v53, s85, -v85
	v_fma_f32 v46, v46, s85, -v85
	v_mov_b32_e32 v71, v63
	v_fma_f32 v63, v64, s85, -v85
	v_mul_f32_e32 v64, 0x3fb8aa3b, v63
	v_fma_f32 v47, v47, s85, -v85
	v_fma_f32 v48, v48, s85, -v85
	v_exp_f32_e32 v63, v64
	v_fma_f32 v49, v49, s85, -v85
	v_fma_f32 v42, v42, s85, -v85
	v_mov_b32_e32 v72, v63
	v_fma_f32 v63, v65, s85, -v85
	v_mul_f32_e32 v64, 0x3fb8aa3b, v63
	v_fma_f32 v43, v43, s85, -v85
	v_fma_f32 v44, v44, s85, -v85
	v_exp_f32_e32 v63, v64
	v_fma_f32 v45, v45, s85, -v85
	v_fma_f32 v38, v38, s85, -v85
	v_mov_b32_e32 v73, v63
	v_mul_f32_e32 v63, 0x3fb8aa3b, v58
	v_fma_f32 v39, v39, s85, -v85
	v_fma_f32 v40, v40, s85, -v85
	v_exp_f32_e32 v58, v63
	v_fma_f32 v41, v41, s85, -v85
	v_fma_f32 v34, v34, s85, -v85
	v_mul_f32_e32 v63, 0x3fb8aa3b, v59
	v_fma_f32 v35, v35, s85, -v85
	v_fma_f32 v36, v36, s85, -v85
	v_exp_f32_e32 v59, v63
	v_add_f32_e32 v62, v71, v62
	v_add_f32_e32 v62, v72, v62
	v_mul_f32_e32 v63, 0x3fb8aa3b, v60
	v_add_f32_e32 v62, v73, v62
	v_add_f32_e32 v62, v58, v62
	v_exp_f32_e32 v60, v63
	v_add_f32_e32 v62, v59, v62
	v_fma_f32 v37, v37, s85, -v85
	v_mul_f32_e32 v63, 0x3fb8aa3b, v61
	v_add_f32_e32 v62, v60, v62
	v_fma_f32 v26, v26, s85, -v85
	v_exp_f32_e32 v61, v63
	v_fma_f32 v27, v27, s85, -v85
	v_fma_f32 v28, v28, s85, -v85
	v_mul_f32_e32 v63, 0x3fb8aa3b, v54
	v_add_f32_e32 v62, v61, v62
	v_fma_f32 v29, v29, s85, -v85
	v_exp_f32_e32 v54, v63
	v_fma_f32 v22, v22, s85, -v85
	v_fma_f32 v23, v23, s85, -v85
	v_mul_f32_e32 v63, 0x3fb8aa3b, v55
	v_add_f32_e32 v62, v54, v62
	v_fma_f32 v24, v24, s85, -v85
	v_exp_f32_e32 v55, v63
	v_fma_f32 v25, v25, s85, -v85
	v_fma_f32 v14, v14, s85, -v85
	v_mul_f32_e32 v63, 0x3fb8aa3b, v56
	v_add_f32_e32 v62, v55, v62
	v_fma_f32 v15, v15, s85, -v85
	v_exp_f32_e32 v56, v63
	v_fma_f32 v8, v8, s85, -v85
	v_fma_f32 v9, v9, s85, -v85
	v_mul_f32_e32 v63, 0x3fb8aa3b, v57
	v_add_f32_e32 v62, v56, v62
	v_cvt_pk_bf16_f32 v66, v66, v67
	v_exp_f32_e32 v57, v63
	v_cvt_pk_bf16_f32 v67, v68, v69
	v_cvt_pk_bf16_f32 v68, v70, v71
	v_mul_f32_e32 v63, 0x3fb8aa3b, v50
	v_add_f32_e32 v62, v57, v62
	v_cvt_pk_bf16_f32 v69, v72, v73
	v_exp_f32_e32 v50, v63
	ds_read_b64_tr_b16 v[72:73], v97 offset:39168
	ds_read_b64_tr_b16 v[70:71], v97 offset:36864
	ds_read_b64_tr_b16 v[108:109], v97 offset:36896
	ds_read_b64_tr_b16 v[110:111], v97 offset:39200
	v_mul_f32_e32 v63, 0x3fb8aa3b, v51
	v_add_f32_e32 v62, v50, v62
	ds_read_b64_tr_b16 v[112:113], v97 offset:36928
	ds_read_b64_tr_b16 v[114:115], v97 offset:39232
	v_exp_f32_e32 v51, v63
	ds_read_b64_tr_b16 v[116:117], v97 offset:36960
	ds_read_b64_tr_b16 v[118:119], v97 offset:39264
	v_cvt_pk_bf16_f32 v58, v58, v59
	v_mul_f32_e32 v63, 0x3fb8aa3b, v52
	v_add_f32_e32 v62, v51, v62
	v_cvt_pk_bf16_f32 v59, v60, v61
	v_exp_f32_e32 v52, v63
	v_cvt_pk_bf16_f32 v60, v54, v55
	v_cvt_pk_bf16_f32 v61, v56, v57
	v_mul_f32_e32 v63, 0x3fb8aa3b, v53
	v_add_f32_e32 v62, v52, v62
	ds_read_b64_tr_b16 v[54:55], v97 offset:41472
	ds_read_b64_tr_b16 v[56:57], v97 offset:43776
	v_exp_f32_e32 v53, v63
	v_fma_f32 v10, v10, s85, -v85
	s_waitcnt lgkmcnt(8)
	v_mfma_f32_16x16x32_bf16 v[70:73], v[70:73], v[66:69], 0
	v_mul_f32_e32 v63, 0x3fb8aa3b, v46
	v_add_f32_e32 v62, v53, v62
	s_waitcnt lgkmcnt(0)
	v_mfma_f32_16x16x32_bf16 v[54:57], v[54:57], v[58:61], v[70:73]
	v_exp_f32_e32 v46, v63
	s_nop 2
	ds_read_b64_tr_b16 v[70:71], v97 offset:41504
	ds_read_b64_tr_b16 v[72:73], v97 offset:43808
	v_mfma_f32_16x16x32_bf16 v[108:111], v[108:111], v[66:69], 0
	v_mul_f32_e32 v63, 0x3fb8aa3b, v47
	v_add_f32_e32 v62, v46, v62
	v_fma_f32 v11, v11, s85, -v85
	v_exp_f32_e32 v47, v63
	s_waitcnt lgkmcnt(0)
	v_mfma_f32_16x16x32_bf16 v[70:73], v[70:73], v[58:61], v[108:111]
	s_nop 2
	ds_read_b64_tr_b16 v[108:109], v97 offset:41536
	ds_read_b64_tr_b16 v[110:111], v97 offset:43840
	v_mul_f32_e32 v63, 0x3fb8aa3b, v48
	v_add_f32_e32 v62, v47, v62
	v_mfma_f32_16x16x32_bf16 v[112:115], v[112:115], v[66:69], 0
	v_exp_f32_e32 v48, v63
	s_waitcnt lgkmcnt(0)
	v_mfma_f32_16x16x32_bf16 v[108:111], v[108:111], v[58:61], v[112:115]
	s_nop 2
	s_nop 1
	ds_read_b64_tr_b16 v[112:113], v97 offset:41568
	ds_read_b64_tr_b16 v[114:115], v97 offset:43872
	v_mul_f32_e32 v63, 0x3fb8aa3b, v49
	v_add_f32_e32 v62, v48, v62
	v_cvt_pk_bf16_f32 v50, v50, v51
	v_exp_f32_e32 v49, v63
	v_cvt_pk_bf16_f32 v51, v52, v53
	v_cvt_pk_bf16_f32 v52, v46, v47
	v_mul_f32_e32 v63, 0x3fb8aa3b, v42
	v_add_f32_e32 v62, v49, v62
	v_cvt_pk_bf16_f32 v53, v48, v49
	v_exp_f32_e32 v42, v63
	ds_read_b64_tr_b16 v[46:47], v97 offset:46080
	ds_read_b64_tr_b16 v[48:49], v97 offset:48384
	v_fma_f32 v4, v4, s85, -v85
	v_mul_f32_e32 v63, 0x3fb8aa3b, v43
	v_add_f32_e32 v62, v42, v62
	s_waitcnt lgkmcnt(0)
; DI unsigned cvt_pk_bf16(float lo, float hi) { const f32x2_t v = {lo, hi}; const bf16v2_t b = __builtin_convertvector(v, bf16v2_t); return __builtin_bit_cast(unsigned, b); }
; DI f32x4 mfma16(bf16x8 a, bf16x8 b, f32x4 c) { return __builtin_amdgcn_mfma_f32_16x16x32_bf16(a, b, c, 0, 0, 0); }
; DI void mem_attn_item(ldsp lds, const bf16_t* proj, int ldp, int qmcol, int gatecol, const bf16_t* kv, bf16_t* branch, int b0, int item, int tid, int wid, int lane, const bool stage = true) {
;     ...
;     float den = 0.f;
; #pragma unroll
;     for (int t = 0; t < 16; ++t)
; #pragma unroll
;         for (int j = 0; j < 4; ++j) { const float pv = exp2f((sacc[t][j] - mx) * 1.4426950408889634f); sacc[t][j] = pv; den += pv; }
;     den += __shfl_xor(den, 16); den += __shfl_xor(den, 32);
;     f32x4 oacc[4];
; #pragma unroll
;     for (int dt = 0; dt < 4; ++dt) oacc[dt] = (f32x4){0.f, 0.f, 0.f, 0.f};
; #pragma unroll
;     for (int kt = 0; kt < 8; ++kt) {
;         u32x4 pw; pw.x = cvt_pk_bf16(sacc[2 * kt][0], sacc[2 * kt][1]); pw.y = cvt_pk_bf16(sacc[2 * kt][2], sacc[2 * kt][3]);
;         pw.z = cvt_pk_bf16(sacc[2 * kt + 1][0], sacc[2 * kt + 1][1]); pw.w = cvt_pk_bf16(sacc[2 * kt + 1][2], sacc[2 * kt + 1][3]);
;         const bf16x8 pf = __builtin_bit_cast(bf16x8, pw);
;         const ldsp va = Vb + (32 * kt + quad * 4 + (li >> 2)) * KS + (li & 3) * 8;
; #pragma unroll
;         for (int dt = 0; dt < 4; ++dt) oacc[dt] = mfma16(lds_tr8(va + dt * 32, va + 16 * KS + dt * 32), pf, oacc[dt]);
;     }
	v_mfma_f32_16x16x32_bf16 v[46:49], v[46:49], v[50:53], v[54:57]
	v_exp_f32_e32 v43, v63
	s_nop 1
	ds_read_b64_tr_b16 v[54:55], v97 offset:46112
	ds_read_b64_tr_b16 v[56:57], v97 offset:48416
	v_mfma_f32_16x16x32_bf16 v[66:69], v[116:119], v[66:69], 0
	v_mul_f32_e32 v63, 0x3fb8aa3b, v44
	v_add_f32_e32 v62, v43, v62
	v_fma_f32 v5, v5, s85, -v85
	v_exp_f32_e32 v44, v63
	v_mfma_f32_16x16x32_bf16 v[58:61], v[112:115], v[58:61], v[66:69]
	s_nop 2
	ds_read_b64_tr_b16 v[66:67], v97 offset:46144
	ds_read_b64_tr_b16 v[68:69], v97 offset:48448
	v_mul_f32_e32 v63, 0x3fb8aa3b, v45
	v_add_f32_e32 v62, v44, v62
	s_waitcnt lgkmcnt(2)
	v_mfma_f32_16x16x32_bf16 v[54:57], v[54:57], v[50:53], v[70:73]
	v_exp_f32_e32 v45, v63
	s_nop 1
	ds_read_b64_tr_b16 v[70:71], v97 offset:46176
	ds_read_b64_tr_b16 v[72:73], v97 offset:48480
	v_cvt_pk_bf16_f32 v42, v42, v43
	v_mul_f32_e32 v63, 0x3fb8aa3b, v38
	v_add_f32_e32 v62, v45, v62
	v_cvt_pk_bf16_f32 v43, v44, v45
	v_exp_f32_e32 v38, v63
	v_fma_f32 v6, v6, s85, -v85
	s_waitcnt lgkmcnt(2)
	v_mfma_f32_16x16x32_bf16 v[66:69], v[66:69], v[50:53], v[108:111]
	v_mul_f32_e32 v63, 0x3fb8aa3b, v39
	v_add_f32_e32 v62, v38, v62
	s_waitcnt lgkmcnt(0)
	v_mfma_f32_16x16x32_bf16 v[50:53], v[70:73], v[50:53], v[58:61]
	v_exp_f32_e32 v39, v63
	v_fma_f32 v7, v7, s85, -v85
	v_fma_f32 v0, v0, s85, -v85
	v_mul_f32_e32 v63, 0x3fb8aa3b, v40
	v_add_f32_e32 v62, v39, v62
	v_cvt_pk_bf16_f32 v44, v38, v39
	v_exp_f32_e32 v40, v63
	v_fma_f32 v1, v1, s85, -v85
	v_fma_f32 v2, v2, s85, -v85
	v_mul_f32_e32 v63, 0x3fb8aa3b, v41
	v_add_f32_e32 v62, v40, v62
	v_fma_f32 v3, v3, s85, -v85
	v_exp_f32_e32 v41, v63
	v_mul_f32_e32 v63, 0x3fb8aa3b, v34
	v_add_f32_e32 v62, v41, v62
	v_cvt_pk_bf16_f32 v45, v40, v41
	v_exp_f32_e32 v34, v63
	ds_read_b64_tr_b16 v[38:39], v97 offset:50688
	ds_read_b64_tr_b16 v[40:41], v97 offset:52992
	s_waitcnt lgkmcnt(0)
	v_mfma_f32_16x16x32_bf16 v[38:41], v[38:41], v[42:45], v[46:49]
	v_mul_f32_e32 v63, 0x3fb8aa3b, v35
	v_add_f32_e32 v62, v34, v62
	s_nop 0
	ds_read_b64_tr_b16 v[46:47], v97 offset:50720
	ds_read_b64_tr_b16 v[48:49], v97 offset:53024
	v_exp_f32_e32 v35, v63
	s_waitcnt lgkmcnt(0)
	v_mfma_f32_16x16x32_bf16 v[46:49], v[46:49], v[42:45], v[54:57]
	s_nop 2
	ds_read_b64_tr_b16 v[54:55], v97 offset:50752
	ds_read_b64_tr_b16 v[56:57], v97 offset:53056
	v_mul_f32_e32 v63, 0x3fb8aa3b, v36
	v_add_f32_e32 v62, v35, v62
	ds_read_b64_tr_b16 v[58:59], v97 offset:50784
	ds_read_b64_tr_b16 v[60:61], v97 offset:53088
	v_exp_f32_e32 v36, v63
	s_waitcnt lgkmcnt(2)
	v_mfma_f32_16x16x32_bf16 v[54:57], v[54:57], v[42:45], v[66:69]
	v_cvt_pk_bf16_f32 v34, v34, v35
	v_mul_f32_e32 v63, 0x3fb8aa3b, v37
	v_add_f32_e32 v62, v36, v62
	s_waitcnt lgkmcnt(0)
	v_mfma_f32_16x16x32_bf16 v[42:45], v[58:61], v[42:45], v[50:53]
	v_exp_f32_e32 v37, v63
	s_nop 1
	ds_read_b64_tr_b16 v[50:51], v97 offset:55296
	ds_read_b64_tr_b16 v[52:53], v97 offset:57600
	v_mul_f32_e32 v63, 0x3fb8aa3b, v26
	v_add_f32_e32 v62, v37, v62
	v_cvt_pk_bf16_f32 v35, v36, v37
	v_exp_f32_e32 v26, v63
	v_mul_f32_e32 v63, 0x3fb8aa3b, v27
	v_add_f32_e32 v62, v26, v62
	s_nop 0
	v_exp_f32_e32 v27, v63
	s_nop 0
	v_add_f32_e32 v63, v27, v62
	v_mul_f32_e32 v62, 0x3fb8aa3b, v28
	v_cvt_pk_bf16_f32 v36, v26, v27
	s_nop 0
	v_exp_f32_e32 v28, v62
	s_nop 0
	v_mov_b32_e32 v62, v28
	v_add_f32_e32 v28, v62, v63
	v_mul_f32_e32 v63, 0x3fb8aa3b, v29
	s_nop 1
	v_exp_f32_e32 v29, v63
	s_nop 0
	v_mov_b32_e32 v63, v29
	v_mul_f32_e32 v29, 0x3fb8aa3b, v22
	v_add_f32_e32 v28, v63, v28
	v_cvt_pk_bf16_f32 v37, v62, v63
	v_exp_f32_e32 v22, v29
	s_waitcnt lgkmcnt(0)
	v_mfma_f32_16x16x32_bf16 v[38:41], v[50:53], v[34:37], v[38:41]
	ds_read_b64_tr_b16 v[50:51], v97 offset:55328
	ds_read_b64_tr_b16 v[52:53], v97 offset:57632
	v_mul_f32_e32 v29, 0x3fb8aa3b, v23
	v_add_f32_e32 v28, v22, v28
	s_waitcnt lgkmcnt(0)
	v_mfma_f32_16x16x32_bf16 v[46:49], v[50:53], v[34:37], v[46:49]
	v_exp_f32_e32 v23, v29
	ds_read_b64_tr_b16 v[50:51], v97 offset:55360
	ds_read_b64_tr_b16 v[52:53], v97 offset:57664
	s_waitcnt lgkmcnt(0)
	v_mfma_f32_16x16x32_bf16 v[50:53], v[50:53], v[34:37], v[54:57]
	v_mul_f32_e32 v29, 0x3fb8aa3b, v24
	v_add_f32_e32 v28, v23, v28
	s_nop 0
	ds_read_b64_tr_b16 v[54:55], v97 offset:55392
	ds_read_b64_tr_b16 v[56:57], v97 offset:57696
	v_exp_f32_e32 v24, v29
	s_waitcnt lgkmcnt(0)
	v_mfma_f32_16x16x32_bf16 v[34:37], v[54:57], v[34:37], v[42:45]
	v_mul_f32_e32 v29, 0x3fb8aa3b, v25
	v_add_f32_e32 v28, v24, v28
	s_nop 0
	v_exp_f32_e32 v25, v29
	s_nop 0
	v_add_f32_e32 v29, v25, v28
	v_mul_f32_e32 v28, 0x3fb8aa3b, v14
	s_nop 1
	v_exp_f32_e32 v14, v28
	s_nop 0
	v_mov_b32_e32 v28, v14
	v_add_f32_e32 v14, v28, v29
	v_mul_f32_e32 v29, 0x3fb8aa3b, v15
	s_nop 1
	v_exp_f32_e32 v15, v29
	s_nop 0
	v_mov_b32_e32 v29, v15
	v_fma_f32 v15, v16, s85, -v85
	v_mul_f32_e32 v16, 0x3fb8aa3b, v15
	v_add_f32_e32 v14, v29, v14
	s_nop 0
	v_exp_f32_e32 v15, v16
	s_nop 0
	v_mov_b32_e32 v64, v15
	v_fma_f32 v15, v17, s85, -v85
	v_mul_f32_e32 v16, 0x3fb8aa3b, v15
	v_add_f32_e32 v14, v64, v14
	s_nop 0
	v_exp_f32_e32 v15, v16
	s_nop 0
	v_mov_b32_e32 v65, v15
	v_add_f32_e32 v15, v65, v14
	v_fma_f32 v14, v18, s85, -v85
	v_mul_f32_e32 v16, 0x3fb8aa3b, v14
	s_nop 1
	v_exp_f32_e32 v14, v16
	s_nop 0
	v_add_f32_e32 v16, v14, v15
	v_fma_f32 v15, v19, s85, -v85
	v_mul_f32_e32 v17, 0x3fb8aa3b, v15
	s_nop 1
	v_exp_f32_e32 v15, v17
	s_nop 0
	v_add_f32_e32 v17, v15, v16
	v_fma_f32 v16, v20, s85, -v85
	v_mul_f32_e32 v18, 0x3fb8aa3b, v16
	v_cvt_pk_bf16_f32 v20, v22, v23
	v_cvt_pk_bf16_f32 v22, v28, v29
	v_exp_f32_e32 v16, v18
	v_cvt_pk_bf16_f32 v23, v64, v65
	v_cvt_pk_bf16_f32 v14, v14, v15
	v_add_f32_e32 v18, v16, v17
	v_fma_f32 v17, v21, s85, -v85
	v_mul_f32_e32 v19, 0x3fb8aa3b, v17
	v_cvt_pk_bf16_f32 v21, v24, v25
	ds_read_b64_tr_b16 v[24:25], v97 offset:59904
	ds_read_b64_tr_b16 v[26:27], v97 offset:62208
	v_exp_f32_e32 v17, v19
	s_waitcnt lgkmcnt(0)
; DI unsigned cvt_pk_bf16(float lo, float hi) { const f32x2_t v = {lo, hi}; const bf16v2_t b = __builtin_convertvector(v, bf16v2_t); return __builtin_bit_cast(unsigned, b); }
; DI f32x4 mfma16(bf16x8 a, bf16x8 b, f32x4 c) { return __builtin_amdgcn_mfma_f32_16x16x32_bf16(a, b, c, 0, 0, 0); }
; DI void mem_attn_item(ldsp lds, const bf16_t* proj, int ldp, int qmcol, int gatecol, const bf16_t* kv, bf16_t* branch, int b0, int item, int tid, int wid, int lane, const bool stage = true) {
;     ...
;     float den = 0.f;
; #pragma unroll
;     for (int t = 0; t < 16; ++t)
; #pragma unroll
;         for (int j = 0; j < 4; ++j) { const float pv = exp2f((sacc[t][j] - mx) * 1.4426950408889634f); sacc[t][j] = pv; den += pv; }
;     den += __shfl_xor(den, 16); den += __shfl_xor(den, 32);
;     f32x4 oacc[4];
; #pragma unroll
;     for (int dt = 0; dt < 4; ++dt) oacc[dt] = (f32x4){0.f, 0.f, 0.f, 0.f};
; #pragma unroll
;     for (int kt = 0; kt < 8; ++kt) {
;         u32x4 pw; pw.x = cvt_pk_bf16(sacc[2 * kt][0], sacc[2 * kt][1]); pw.y = cvt_pk_bf16(sacc[2 * kt][2], sacc[2 * kt][3]);
;         pw.z = cvt_pk_bf16(sacc[2 * kt + 1][0], sacc[2 * kt + 1][1]); pw.w = cvt_pk_bf16(sacc[2 * kt + 1][2], sacc[2 * kt + 1][3]);
;         const bf16x8 pf = __builtin_bit_cast(bf16x8, pw);
;         const ldsp va = Vb + (32 * kt + quad * 4 + (li >> 2)) * KS + (li & 3) * 8;
; #pragma unroll
;         for (int dt = 0; dt < 4; ++dt) oacc[dt] = mfma16(lds_tr8(va + dt * 32, va + 16 * KS + dt * 32), pf, oacc[dt]);
;     }
	v_mfma_f32_16x16x32_bf16 v[24:27], v[24:27], v[20:23], v[38:41]
	s_nop 2
	ds_read_b64_tr_b16 v[38:39], v97 offset:59936
	ds_read_b64_tr_b16 v[40:41], v97 offset:62240
	v_mul_f32_e32 v19, 0x3fb8aa3b, v8
	v_add_f32_e32 v18, v17, v18
	s_waitcnt lgkmcnt(0)
	v_mfma_f32_16x16x32_bf16 v[38:41], v[38:41], v[20:23], v[46:49]
	v_exp_f32_e32 v8, v19
	ds_read_b64_tr_b16 v[42:43], v97 offset:59968
	ds_read_b64_tr_b16 v[44:45], v97 offset:62272
	ds_read_b64_tr_b16 v[46:47], v97 offset:60000
	ds_read_b64_tr_b16 v[48:49], v97 offset:62304
	v_mul_f32_e32 v19, 0x3fb8aa3b, v9
	v_add_f32_e32 v18, v8, v18
	v_cvt_pk_bf16_f32 v15, v16, v17
	v_exp_f32_e32 v9, v19
	s_waitcnt lgkmcnt(2)
	v_mfma_f32_16x16x32_bf16 v[42:45], v[42:45], v[20:23], v[50:53]
	v_mul_f32_e32 v19, 0x3fb8aa3b, v10
	v_add_f32_e32 v18, v9, v18
	v_cvt_pk_bf16_f32 v16, v8, v9
	v_exp_f32_e32 v10, v19
	s_waitcnt lgkmcnt(0)
	v_mfma_f32_16x16x32_bf16 v[20:23], v[46:49], v[20:23], v[34:37]
	v_mul_f32_e32 v19, 0x3fb8aa3b, v11
	v_add_f32_e32 v18, v10, v18
	s_nop 0
	v_exp_f32_e32 v11, v19
	v_mul_f32_e32 v19, 0x3fb8aa3b, v4
	v_add_f32_e32 v18, v11, v18
	v_cvt_pk_bf16_f32 v17, v10, v11
	v_exp_f32_e32 v4, v19
	ds_read_b64_tr_b16 v[8:9], v97 offset:64512
	ds_read_b64_tr_b16 v[10:11], v98 offset:29952
	ds_read_b64_tr_b16 v[28:29], v98 offset:29984
	s_waitcnt lgkmcnt(1)
	v_mfma_f32_16x16x32_bf16 v[8:11], v[8:11], v[14:17], v[24:27]
	v_mul_f32_e32 v19, 0x3fb8aa3b, v5
	s_nop 1
	ds_read_b64_tr_b16 v[26:27], v97 offset:64544
	v_add_f32_e32 v18, v4, v18
	v_exp_f32_e32 v5, v19
	s_waitcnt lgkmcnt(0)
	v_mfma_f32_16x16x32_bf16 v[24:27], v[26:29], v[14:17], v[38:41]
	v_mul_f32_e32 v19, 0x3fb8aa3b, v6
	v_add_f32_e32 v18, v5, v18
	ds_read_b64_tr_b16 v[34:35], v97 offset:64576
	ds_read_b64_tr_b16 v[36:37], v98 offset:30016
	v_exp_f32_e32 v6, v19
	ds_read_b64_tr_b16 v[38:39], v97 offset:64608
	ds_read_b64_tr_b16 v[40:41], v98 offset:30048
	s_waitcnt lgkmcnt(0)
	v_mfma_f32_16x16x32_bf16 v[20:23], v[38:41], v[14:17], v[20:23]
	v_mul_f32_e32 v19, 0x3fb8aa3b, v7
	v_add_f32_e32 v18, v6, v18
	v_cvt_pk_bf16_f32 v38, v4, v5
	v_exp_f32_e32 v7, v19
	v_mfma_f32_16x16x32_bf16 v[34:37], v[34:37], v[14:17], v[42:45]
	v_mul_f32_e32 v19, 0x3fb8aa3b, v0
	v_add_f32_e32 v18, v7, v18
	v_cvt_pk_bf16_f32 v39, v6, v7
	v_exp_f32_e32 v0, v19
	v_mul_f32_e32 v19, 0x3fb8aa3b, v1
	v_add_f32_e32 v18, v0, v18
	s_nop 0
	v_exp_f32_e32 v1, v19
	v_mul_f32_e32 v19, 0x3fb8aa3b, v2
	v_add_f32_e32 v18, v1, v18
	v_cvt_pk_bf16_f32 v40, v0, v1
	v_exp_f32_e32 v2, v19
	v_mul_f32_e32 v19, 0x3fb8aa3b, v3
	v_add_f32_e32 v18, v2, v18
	s_nop 0
	v_exp_f32_e32 v3, v19
	s_branch .Lma_join_dil
.Lma_slow_dil:
	v_fma_f32 v66, v66, s85, -v85
	v_mul_f32_e32 v70, 0x3fb8aa3b, v66
	v_cmp_gt_f32_e32 vcc, s86, v70
	v_fma_f32 v67, v67, s85, -v85
	v_fma_f32 v68, v68, s85, -v85
	v_cndmask_b32_e32 v70, 0, v235, vcc
	v_fmac_f32_e32 v70, 0x3fb8aa3b, v66
	v_exp_f32_e32 v66, v70
	v_cndmask_b32_e32 v70, 0, v236, vcc
	v_mul_f32_e32 v71, 0x3fb8aa3b, v68
	v_fma_f32 v69, v69, s85, -v85
	v_ldexp_f32 v66, v66, v70
	v_mul_f32_e32 v70, 0x3fb8aa3b, v67
	v_cmp_gt_f32_e32 vcc, s86, v70
	v_fma_f32 v62, v62, s85, -v85
	v_fma_f32 v63, v63, s85, -v85
	v_cndmask_b32_e32 v70, 0, v235, vcc
	v_fmac_f32_e32 v70, 0x3fb8aa3b, v67
	v_exp_f32_e32 v67, v70
	v_cndmask_b32_e32 v70, 0, v236, vcc
	v_cmp_gt_f32_e32 vcc, s86, v71
	v_fma_f32 v58, v58, s85, -v85
	v_ldexp_f32 v67, v67, v70
	v_cndmask_b32_e32 v71, 0, v235, vcc
	v_fmac_f32_e32 v71, 0x3fb8aa3b, v68
	v_exp_f32_e32 v68, v71
	v_cndmask_b32_e32 v71, 0, v236, vcc
	v_add_f32_e32 v70, v66, v67
	v_fma_f32 v59, v59, s85, -v85
	v_ldexp_f32 v68, v68, v71
	v_mul_f32_e32 v71, 0x3fb8aa3b, v69
	v_cmp_gt_f32_e32 vcc, s86, v71
	v_add_f32_e32 v70, v68, v70
	v_fma_f32 v60, v60, s85, -v85
	v_cndmask_b32_e32 v71, 0, v235, vcc
	v_fmac_f32_e32 v71, 0x3fb8aa3b, v69
	v_exp_f32_e32 v69, v71
	v_cndmask_b32_e32 v71, 0, v236, vcc
	v_fma_f32 v61, v61, s85, -v85
	v_fma_f32 v54, v54, s85, -v85
	v_ldexp_f32 v69, v69, v71
	v_add_f32_e32 v71, v69, v70
	v_mul_f32_e32 v70, 0x3fb8aa3b, v62
	v_cmp_gt_f32_e32 vcc, s86, v70
	v_fma_f32 v55, v55, s85, -v85
	v_fma_f32 v56, v56, s85, -v85
	v_cndmask_b32_e32 v70, 0, v235, vcc
	v_fmac_f32_e32 v70, 0x3fb8aa3b, v62
	v_exp_f32_e32 v62, v70
	v_cndmask_b32_e32 v70, 0, v236, vcc
	v_fma_f32 v57, v57, s85, -v85
	v_fma_f32 v50, v50, s85, -v85
	v_ldexp_f32 v70, v62, v70
	v_add_f32_e32 v62, v70, v71
	v_mul_f32_e32 v71, 0x3fb8aa3b, v63
	v_cmp_gt_f32_e32 vcc, s86, v71
	v_fma_f32 v51, v51, s85, -v85
	v_fma_f32 v52, v52, s85, -v85
	v_cndmask_b32_e32 v71, 0, v235, vcc
	v_fmac_f32_e32 v71, 0x3fb8aa3b, v63
	v_exp_f32_e32 v63, v71
	v_cndmask_b32_e32 v71, 0, v236, vcc
	v_fma_f32 v53, v53, s85, -v85
	v_fma_f32 v46, v46, s85, -v85
	v_ldexp_f32 v71, v63, v71
	v_fma_f32 v63, v64, s85, -v85
	v_mul_f32_e32 v64, 0x3fb8aa3b, v63
	v_cmp_gt_f32_e32 vcc, s86, v64
	v_fma_f32 v47, v47, s85, -v85
	v_fma_f32 v48, v48, s85, -v85
	v_cndmask_b32_e32 v64, 0, v235, vcc
	v_fmac_f32_e32 v64, 0x3fb8aa3b, v63
	v_exp_f32_e32 v63, v64
	v_cndmask_b32_e32 v64, 0, v236, vcc
	v_fma_f32 v49, v49, s85, -v85
	v_fma_f32 v42, v42, s85, -v85
	v_ldexp_f32 v72, v63, v64
	v_fma_f32 v63, v65, s85, -v85
	v_mul_f32_e32 v64, 0x3fb8aa3b, v63
	v_cmp_gt_f32_e32 vcc, s86, v64
	v_fma_f32 v43, v43, s85, -v85
	v_fma_f32 v44, v44, s85, -v85
	v_cndmask_b32_e32 v64, 0, v235, vcc
	v_fmac_f32_e32 v64, 0x3fb8aa3b, v63
	v_exp_f32_e32 v63, v64
	v_cndmask_b32_e32 v64, 0, v236, vcc
	v_fma_f32 v45, v45, s85, -v85
	v_fma_f32 v38, v38, s85, -v85
	v_ldexp_f32 v73, v63, v64
	v_mul_f32_e32 v63, 0x3fb8aa3b, v58
	v_cmp_gt_f32_e32 vcc, s86, v63
	v_fma_f32 v39, v39, s85, -v85
	v_fma_f32 v40, v40, s85, -v85
	v_cndmask_b32_e32 v63, 0, v235, vcc
; DI unsigned cvt_pk_bf16(float lo, float hi) { const f32x2_t v = {lo, hi}; const bf16v2_t b = __builtin_convertvector(v, bf16v2_t); return __builtin_bit_cast(unsigned, b); }
; DI f32x4 mfma16(bf16x8 a, bf16x8 b, f32x4 c) { return __builtin_amdgcn_mfma_f32_16x16x32_bf16(a, b, c, 0, 0, 0); }
; DI void mem_attn_item(ldsp lds, const bf16_t* proj, int ldp, int qmcol, int gatecol, const bf16_t* kv, bf16_t* branch, int b0, int item, int tid, int wid, int lane, const bool stage = true) {
;     ...
;     float den = 0.f;
; #pragma unroll
;     for (int t = 0; t < 16; ++t)
; #pragma unroll
;         for (int j = 0; j < 4; ++j) { const float pv = exp2f((sacc[t][j] - mx) * 1.4426950408889634f); sacc[t][j] = pv; den += pv; }
;     den += __shfl_xor(den, 16); den += __shfl_xor(den, 32);
;     f32x4 oacc[4];
; #pragma unroll
;     for (int dt = 0; dt < 4; ++dt) oacc[dt] = (f32x4){0.f, 0.f, 0.f, 0.f};
; #pragma unroll
;     for (int kt = 0; kt < 8; ++kt) {
;         u32x4 pw; pw.x = cvt_pk_bf16(sacc[2 * kt][0], sacc[2 * kt][1]); pw.y = cvt_pk_bf16(sacc[2 * kt][2], sacc[2 * kt][3]);
;         pw.z = cvt_pk_bf16(sacc[2 * kt + 1][0], sacc[2 * kt + 1][1]); pw.w = cvt_pk_bf16(sacc[2 * kt + 1][2], sacc[2 * kt + 1][3]);
;         const bf16x8 pf = __builtin_bit_cast(bf16x8, pw);
;         const ldsp va = Vb + (32 * kt + quad * 4 + (li >> 2)) * KS + (li & 3) * 8;
; #pragma unroll
;         for (int dt = 0; dt < 4; ++dt) oacc[dt] = mfma16(lds_tr8(va + dt * 32, va + 16 * KS + dt * 32), pf, oacc[dt]);
;     }
	v_fmac_f32_e32 v63, 0x3fb8aa3b, v58
	v_exp_f32_e32 v58, v63
	v_cndmask_b32_e32 v63, 0, v236, vcc
	v_fma_f32 v41, v41, s85, -v85
	v_fma_f32 v34, v34, s85, -v85
	v_ldexp_f32 v58, v58, v63
	v_mul_f32_e32 v63, 0x3fb8aa3b, v59
	v_cmp_gt_f32_e32 vcc, s86, v63
	v_fma_f32 v35, v35, s85, -v85
	v_fma_f32 v36, v36, s85, -v85
	v_cndmask_b32_e32 v63, 0, v235, vcc
	v_fmac_f32_e32 v63, 0x3fb8aa3b, v59
	v_exp_f32_e32 v59, v63
	v_cndmask_b32_e32 v63, 0, v236, vcc
	v_add_f32_e32 v62, v71, v62
	v_add_f32_e32 v62, v72, v62
	v_ldexp_f32 v59, v59, v63
	v_mul_f32_e32 v63, 0x3fb8aa3b, v60
	v_cmp_gt_f32_e32 vcc, s86, v63
	v_add_f32_e32 v62, v73, v62
	v_add_f32_e32 v62, v58, v62
	v_cndmask_b32_e32 v63, 0, v235, vcc
	v_fmac_f32_e32 v63, 0x3fb8aa3b, v60
	v_exp_f32_e32 v60, v63
	v_cndmask_b32_e32 v63, 0, v236, vcc
	v_add_f32_e32 v62, v59, v62
	v_fma_f32 v37, v37, s85, -v85
	v_ldexp_f32 v60, v60, v63
	v_mul_f32_e32 v63, 0x3fb8aa3b, v61
	v_cmp_gt_f32_e32 vcc, s86, v63
	v_add_f32_e32 v62, v60, v62
	v_fma_f32 v26, v26, s85, -v85
	v_cndmask_b32_e32 v63, 0, v235, vcc
	v_fmac_f32_e32 v63, 0x3fb8aa3b, v61
	v_exp_f32_e32 v61, v63
	v_cndmask_b32_e32 v63, 0, v236, vcc
	v_fma_f32 v27, v27, s85, -v85
	v_fma_f32 v28, v28, s85, -v85
	v_ldexp_f32 v61, v61, v63
	v_mul_f32_e32 v63, 0x3fb8aa3b, v54
	v_cmp_gt_f32_e32 vcc, s86, v63
	v_add_f32_e32 v62, v61, v62
	v_fma_f32 v29, v29, s85, -v85
	v_cndmask_b32_e32 v63, 0, v235, vcc
	v_fmac_f32_e32 v63, 0x3fb8aa3b, v54
	v_exp_f32_e32 v54, v63
	v_cndmask_b32_e32 v63, 0, v236, vcc
	v_fma_f32 v22, v22, s85, -v85
	v_fma_f32 v23, v23, s85, -v85
	v_ldexp_f32 v54, v54, v63
	v_mul_f32_e32 v63, 0x3fb8aa3b, v55
	v_cmp_gt_f32_e32 vcc, s86, v63
	v_add_f32_e32 v62, v54, v62
	v_fma_f32 v24, v24, s85, -v85
	v_cndmask_b32_e32 v63, 0, v235, vcc
	v_fmac_f32_e32 v63, 0x3fb8aa3b, v55
	v_exp_f32_e32 v55, v63
	v_cndmask_b32_e32 v63, 0, v236, vcc
	v_fma_f32 v25, v25, s85, -v85
	v_fma_f32 v14, v14, s85, -v85
	v_ldexp_f32 v55, v55, v63
	v_mul_f32_e32 v63, 0x3fb8aa3b, v56
	v_cmp_gt_f32_e32 vcc, s86, v63
	v_add_f32_e32 v62, v55, v62
	v_fma_f32 v15, v15, s85, -v85
	v_cndmask_b32_e32 v63, 0, v235, vcc
	v_fmac_f32_e32 v63, 0x3fb8aa3b, v56
	v_exp_f32_e32 v56, v63
	v_cndmask_b32_e32 v63, 0, v236, vcc
	v_fma_f32 v8, v8, s85, -v85
	v_fma_f32 v9, v9, s85, -v85
	v_ldexp_f32 v56, v56, v63
	v_mul_f32_e32 v63, 0x3fb8aa3b, v57
	v_cmp_gt_f32_e32 vcc, s86, v63
	v_add_f32_e32 v62, v56, v62
	v_cvt_pk_bf16_f32 v66, v66, v67
	v_cndmask_b32_e32 v63, 0, v235, vcc
	v_fmac_f32_e32 v63, 0x3fb8aa3b, v57
	v_exp_f32_e32 v57, v63
	v_cndmask_b32_e32 v63, 0, v236, vcc
	v_cvt_pk_bf16_f32 v67, v68, v69
	v_cvt_pk_bf16_f32 v68, v70, v71
	v_ldexp_f32 v57, v57, v63
	v_mul_f32_e32 v63, 0x3fb8aa3b, v50
	v_cmp_gt_f32_e32 vcc, s86, v63
	v_add_f32_e32 v62, v57, v62
	v_cvt_pk_bf16_f32 v69, v72, v73
	v_cndmask_b32_e32 v63, 0, v235, vcc
	v_fmac_f32_e32 v63, 0x3fb8aa3b, v50
	v_exp_f32_e32 v50, v63
	v_cndmask_b32_e32 v63, 0, v236, vcc
	ds_read_b64_tr_b16 v[72:73], v97 offset:39168
	ds_read_b64_tr_b16 v[70:71], v97 offset:36864
	ds_read_b64_tr_b16 v[108:109], v97 offset:36896
	ds_read_b64_tr_b16 v[110:111], v97 offset:39200
	v_ldexp_f32 v50, v50, v63
	v_mul_f32_e32 v63, 0x3fb8aa3b, v51
	v_cmp_gt_f32_e32 vcc, s86, v63
	v_add_f32_e32 v62, v50, v62
	ds_read_b64_tr_b16 v[112:113], v97 offset:36928
	ds_read_b64_tr_b16 v[114:115], v97 offset:39232
	v_cndmask_b32_e32 v63, 0, v235, vcc
	v_fmac_f32_e32 v63, 0x3fb8aa3b, v51
	v_exp_f32_e32 v51, v63
	v_cndmask_b32_e32 v63, 0, v236, vcc
	ds_read_b64_tr_b16 v[116:117], v97 offset:36960
	ds_read_b64_tr_b16 v[118:119], v97 offset:39264
	v_cvt_pk_bf16_f32 v58, v58, v59
	v_ldexp_f32 v51, v51, v63
	v_mul_f32_e32 v63, 0x3fb8aa3b, v52
	v_cmp_gt_f32_e32 vcc, s86, v63
	v_add_f32_e32 v62, v51, v62
	v_cvt_pk_bf16_f32 v59, v60, v61
	v_cndmask_b32_e32 v63, 0, v235, vcc
	v_fmac_f32_e32 v63, 0x3fb8aa3b, v52
	v_exp_f32_e32 v52, v63
	v_cndmask_b32_e32 v63, 0, v236, vcc
	v_cvt_pk_bf16_f32 v60, v54, v55
	v_cvt_pk_bf16_f32 v61, v56, v57
	v_ldexp_f32 v52, v52, v63
	v_mul_f32_e32 v63, 0x3fb8aa3b, v53
	v_cmp_gt_f32_e32 vcc, s86, v63
	v_add_f32_e32 v62, v52, v62
	ds_read_b64_tr_b16 v[54:55], v97 offset:41472
	ds_read_b64_tr_b16 v[56:57], v97 offset:43776
	v_cndmask_b32_e32 v63, 0, v235, vcc
	v_fmac_f32_e32 v63, 0x3fb8aa3b, v53
	v_exp_f32_e32 v53, v63
	v_cndmask_b32_e32 v63, 0, v236, vcc
	v_fma_f32 v10, v10, s85, -v85
	s_waitcnt lgkmcnt(8)
	v_mfma_f32_16x16x32_bf16 v[70:73], v[70:73], v[66:69], 0
	v_ldexp_f32 v53, v53, v63
	v_mul_f32_e32 v63, 0x3fb8aa3b, v46
	v_cmp_gt_f32_e32 vcc, s86, v63
	v_add_f32_e32 v62, v53, v62
	s_waitcnt lgkmcnt(0)
	v_mfma_f32_16x16x32_bf16 v[54:57], v[54:57], v[58:61], v[70:73]
	v_cndmask_b32_e32 v63, 0, v235, vcc
	v_fmac_f32_e32 v63, 0x3fb8aa3b, v46
	v_exp_f32_e32 v46, v63
	v_cndmask_b32_e32 v63, 0, v236, vcc
	ds_read_b64_tr_b16 v[70:71], v97 offset:41504
	ds_read_b64_tr_b16 v[72:73], v97 offset:43808
	v_mfma_f32_16x16x32_bf16 v[108:111], v[108:111], v[66:69], 0
	v_ldexp_f32 v46, v46, v63
	v_mul_f32_e32 v63, 0x3fb8aa3b, v47
	v_cmp_gt_f32_e32 vcc, s86, v63
	v_add_f32_e32 v62, v46, v62
	v_fma_f32 v11, v11, s85, -v85
	v_cndmask_b32_e32 v63, 0, v235, vcc
	v_fmac_f32_e32 v63, 0x3fb8aa3b, v47
	v_exp_f32_e32 v47, v63
	v_cndmask_b32_e32 v63, 0, v236, vcc
	s_waitcnt lgkmcnt(0)
	v_mfma_f32_16x16x32_bf16 v[70:73], v[70:73], v[58:61], v[108:111]
	s_nop 2
	ds_read_b64_tr_b16 v[108:109], v97 offset:41536
	ds_read_b64_tr_b16 v[110:111], v97 offset:43840
	v_ldexp_f32 v47, v47, v63
	v_mul_f32_e32 v63, 0x3fb8aa3b, v48
	v_cmp_gt_f32_e32 vcc, s86, v63
	v_add_f32_e32 v62, v47, v62
	v_mfma_f32_16x16x32_bf16 v[112:115], v[112:115], v[66:69], 0
	v_cndmask_b32_e32 v63, 0, v235, vcc
	v_fmac_f32_e32 v63, 0x3fb8aa3b, v48
	v_exp_f32_e32 v48, v63
	v_cndmask_b32_e32 v63, 0, v236, vcc
	s_waitcnt lgkmcnt(0)
; DI unsigned cvt_pk_bf16(float lo, float hi) { const f32x2_t v = {lo, hi}; const bf16v2_t b = __builtin_convertvector(v, bf16v2_t); return __builtin_bit_cast(unsigned, b); }
; DI f32x4 mfma16(bf16x8 a, bf16x8 b, f32x4 c) { return __builtin_amdgcn_mfma_f32_16x16x32_bf16(a, b, c, 0, 0, 0); }
; DI void mem_attn_item(ldsp lds, const bf16_t* proj, int ldp, int qmcol, int gatecol, const bf16_t* kv, bf16_t* branch, int b0, int item, int tid, int wid, int lane, const bool stage = true) {
;     ...
;     float den = 0.f;
; #pragma unroll
;     for (int t = 0; t < 16; ++t)
; #pragma unroll
;         for (int j = 0; j < 4; ++j) { const float pv = exp2f((sacc[t][j] - mx) * 1.4426950408889634f); sacc[t][j] = pv; den += pv; }
;     den += __shfl_xor(den, 16); den += __shfl_xor(den, 32);
;     f32x4 oacc[4];
; #pragma unroll
;     for (int dt = 0; dt < 4; ++dt) oacc[dt] = (f32x4){0.f, 0.f, 0.f, 0.f};
; #pragma unroll
;     for (int kt = 0; kt < 8; ++kt) {
;         u32x4 pw; pw.x = cvt_pk_bf16(sacc[2 * kt][0], sacc[2 * kt][1]); pw.y = cvt_pk_bf16(sacc[2 * kt][2], sacc[2 * kt][3]);
;         pw.z = cvt_pk_bf16(sacc[2 * kt + 1][0], sacc[2 * kt + 1][1]); pw.w = cvt_pk_bf16(sacc[2 * kt + 1][2], sacc[2 * kt + 1][3]);
;         const bf16x8 pf = __builtin_bit_cast(bf16x8, pw);
;         const ldsp va = Vb + (32 * kt + quad * 4 + (li >> 2)) * KS + (li & 3) * 8;
; #pragma unroll
;         for (int dt = 0; dt < 4; ++dt) oacc[dt] = mfma16(lds_tr8(va + dt * 32, va + 16 * KS + dt * 32), pf, oacc[dt]);
;     }
	v_mfma_f32_16x16x32_bf16 v[108:111], v[108:111], v[58:61], v[112:115]
	s_nop 2
	ds_read_b64_tr_b16 v[112:113], v97 offset:41568
	ds_read_b64_tr_b16 v[114:115], v97 offset:43872
	v_ldexp_f32 v48, v48, v63
	v_mul_f32_e32 v63, 0x3fb8aa3b, v49
	v_cmp_gt_f32_e32 vcc, s86, v63
	v_add_f32_e32 v62, v48, v62
	v_cvt_pk_bf16_f32 v50, v50, v51
	v_cndmask_b32_e32 v63, 0, v235, vcc
	v_fmac_f32_e32 v63, 0x3fb8aa3b, v49
	v_exp_f32_e32 v49, v63
	v_cndmask_b32_e32 v63, 0, v236, vcc
	v_cvt_pk_bf16_f32 v51, v52, v53
	v_cvt_pk_bf16_f32 v52, v46, v47
	v_ldexp_f32 v49, v49, v63
	v_mul_f32_e32 v63, 0x3fb8aa3b, v42
	v_cmp_gt_f32_e32 vcc, s86, v63
	v_add_f32_e32 v62, v49, v62
	v_cvt_pk_bf16_f32 v53, v48, v49
	v_cndmask_b32_e32 v63, 0, v235, vcc
	v_fmac_f32_e32 v63, 0x3fb8aa3b, v42
	v_exp_f32_e32 v42, v63
	v_cndmask_b32_e32 v63, 0, v236, vcc
	ds_read_b64_tr_b16 v[46:47], v97 offset:46080
	ds_read_b64_tr_b16 v[48:49], v97 offset:48384
	v_fma_f32 v4, v4, s85, -v85
	v_ldexp_f32 v42, v42, v63
	v_mul_f32_e32 v63, 0x3fb8aa3b, v43
	v_cmp_gt_f32_e32 vcc, s86, v63
	v_add_f32_e32 v62, v42, v62
	s_waitcnt lgkmcnt(0)
	v_mfma_f32_16x16x32_bf16 v[46:49], v[46:49], v[50:53], v[54:57]
	v_cndmask_b32_e32 v63, 0, v235, vcc
	v_fmac_f32_e32 v63, 0x3fb8aa3b, v43
	v_exp_f32_e32 v43, v63
	v_cndmask_b32_e32 v63, 0, v236, vcc
	ds_read_b64_tr_b16 v[54:55], v97 offset:46112
	ds_read_b64_tr_b16 v[56:57], v97 offset:48416
	v_mfma_f32_16x16x32_bf16 v[66:69], v[116:119], v[66:69], 0
	v_ldexp_f32 v43, v43, v63
	v_mul_f32_e32 v63, 0x3fb8aa3b, v44
	v_cmp_gt_f32_e32 vcc, s86, v63
	v_add_f32_e32 v62, v43, v62
	v_fma_f32 v5, v5, s85, -v85
	v_cndmask_b32_e32 v63, 0, v235, vcc
	v_fmac_f32_e32 v63, 0x3fb8aa3b, v44
	v_exp_f32_e32 v44, v63
	v_cndmask_b32_e32 v63, 0, v236, vcc
	v_mfma_f32_16x16x32_bf16 v[58:61], v[112:115], v[58:61], v[66:69]
	s_nop 2
	ds_read_b64_tr_b16 v[66:67], v97 offset:46144
	ds_read_b64_tr_b16 v[68:69], v97 offset:48448
	v_ldexp_f32 v44, v44, v63
	v_mul_f32_e32 v63, 0x3fb8aa3b, v45
	v_cmp_gt_f32_e32 vcc, s86, v63
	v_add_f32_e32 v62, v44, v62
	s_waitcnt lgkmcnt(2)
	v_mfma_f32_16x16x32_bf16 v[54:57], v[54:57], v[50:53], v[70:73]
	v_cndmask_b32_e32 v63, 0, v235, vcc
	v_fmac_f32_e32 v63, 0x3fb8aa3b, v45
	v_exp_f32_e32 v45, v63
	v_cndmask_b32_e32 v63, 0, v236, vcc
	ds_read_b64_tr_b16 v[70:71], v97 offset:46176
	ds_read_b64_tr_b16 v[72:73], v97 offset:48480
	v_cvt_pk_bf16_f32 v42, v42, v43
	v_ldexp_f32 v45, v45, v63
	v_mul_f32_e32 v63, 0x3fb8aa3b, v38
	v_cmp_gt_f32_e32 vcc, s86, v63
	v_add_f32_e32 v62, v45, v62
	v_cvt_pk_bf16_f32 v43, v44, v45
	v_cndmask_b32_e32 v63, 0, v235, vcc
	v_fmac_f32_e32 v63, 0x3fb8aa3b, v38
	v_exp_f32_e32 v38, v63
	v_cndmask_b32_e32 v63, 0, v236, vcc
	v_fma_f32 v6, v6, s85, -v85
	s_waitcnt lgkmcnt(2)
	v_mfma_f32_16x16x32_bf16 v[66:69], v[66:69], v[50:53], v[108:111]
	v_ldexp_f32 v38, v38, v63
	v_mul_f32_e32 v63, 0x3fb8aa3b, v39
	v_cmp_gt_f32_e32 vcc, s86, v63
	v_add_f32_e32 v62, v38, v62
	s_waitcnt lgkmcnt(0)
	v_mfma_f32_16x16x32_bf16 v[50:53], v[70:73], v[50:53], v[58:61]
	v_cndmask_b32_e32 v63, 0, v235, vcc
	v_fmac_f32_e32 v63, 0x3fb8aa3b, v39
	v_exp_f32_e32 v39, v63
	v_cndmask_b32_e32 v63, 0, v236, vcc
	v_fma_f32 v7, v7, s85, -v85
	v_fma_f32 v0, v0, s85, -v85
	v_ldexp_f32 v39, v39, v63
	v_mul_f32_e32 v63, 0x3fb8aa3b, v40
	v_cmp_gt_f32_e32 vcc, s86, v63
	v_add_f32_e32 v62, v39, v62
	v_cvt_pk_bf16_f32 v44, v38, v39
	v_cndmask_b32_e32 v63, 0, v235, vcc
	v_fmac_f32_e32 v63, 0x3fb8aa3b, v40
	v_exp_f32_e32 v40, v63
	v_cndmask_b32_e32 v63, 0, v236, vcc
	v_fma_f32 v1, v1, s85, -v85
	v_fma_f32 v2, v2, s85, -v85
	v_ldexp_f32 v40, v40, v63
	v_mul_f32_e32 v63, 0x3fb8aa3b, v41
	v_cmp_gt_f32_e32 vcc, s86, v63
	v_add_f32_e32 v62, v40, v62
	v_fma_f32 v3, v3, s85, -v85
	v_cndmask_b32_e32 v63, 0, v235, vcc
	v_fmac_f32_e32 v63, 0x3fb8aa3b, v41
	v_exp_f32_e32 v41, v63
	v_cndmask_b32_e32 v63, 0, v236, vcc
	v_ldexp_f32 v41, v41, v63
	v_mul_f32_e32 v63, 0x3fb8aa3b, v34
	v_cmp_gt_f32_e32 vcc, s86, v63
	v_add_f32_e32 v62, v41, v62
	v_cvt_pk_bf16_f32 v45, v40, v41
	v_cndmask_b32_e32 v63, 0, v235, vcc
	v_fmac_f32_e32 v63, 0x3fb8aa3b, v34
	v_exp_f32_e32 v34, v63
	v_cndmask_b32_e32 v63, 0, v236, vcc
	ds_read_b64_tr_b16 v[38:39], v97 offset:50688
	ds_read_b64_tr_b16 v[40:41], v97 offset:52992
	s_waitcnt lgkmcnt(0)
	v_mfma_f32_16x16x32_bf16 v[38:41], v[38:41], v[42:45], v[46:49]
	v_ldexp_f32 v34, v34, v63
	v_mul_f32_e32 v63, 0x3fb8aa3b, v35
	v_cmp_gt_f32_e32 vcc, s86, v63
	v_add_f32_e32 v62, v34, v62
	ds_read_b64_tr_b16 v[46:47], v97 offset:50720
	ds_read_b64_tr_b16 v[48:49], v97 offset:53024
	v_cndmask_b32_e32 v63, 0, v235, vcc
	v_fmac_f32_e32 v63, 0x3fb8aa3b, v35
	v_exp_f32_e32 v35, v63
	v_cndmask_b32_e32 v63, 0, v236, vcc
	s_waitcnt lgkmcnt(0)
	v_mfma_f32_16x16x32_bf16 v[46:49], v[46:49], v[42:45], v[54:57]
	s_nop 2
	ds_read_b64_tr_b16 v[54:55], v97 offset:50752
	ds_read_b64_tr_b16 v[56:57], v97 offset:53056
	v_ldexp_f32 v35, v35, v63
	v_mul_f32_e32 v63, 0x3fb8aa3b, v36
	v_cmp_gt_f32_e32 vcc, s86, v63
	v_add_f32_e32 v62, v35, v62
	ds_read_b64_tr_b16 v[58:59], v97 offset:50784
	ds_read_b64_tr_b16 v[60:61], v97 offset:53088
	v_cndmask_b32_e32 v63, 0, v235, vcc
	v_fmac_f32_e32 v63, 0x3fb8aa3b, v36
	v_exp_f32_e32 v36, v63
	v_cndmask_b32_e32 v63, 0, v236, vcc
	s_waitcnt lgkmcnt(2)
	v_mfma_f32_16x16x32_bf16 v[54:57], v[54:57], v[42:45], v[66:69]
	v_cvt_pk_bf16_f32 v34, v34, v35
	v_ldexp_f32 v36, v36, v63
	v_mul_f32_e32 v63, 0x3fb8aa3b, v37
	v_cmp_gt_f32_e32 vcc, s86, v63
	v_add_f32_e32 v62, v36, v62
	s_waitcnt lgkmcnt(0)
; DI unsigned cvt_pk_bf16(float lo, float hi) { const f32x2_t v = {lo, hi}; const bf16v2_t b = __builtin_convertvector(v, bf16v2_t); return __builtin_bit_cast(unsigned, b); }
; DI f32x4 mfma16(bf16x8 a, bf16x8 b, f32x4 c) { return __builtin_amdgcn_mfma_f32_16x16x32_bf16(a, b, c, 0, 0, 0); }
; DI void mem_attn_item(ldsp lds, const bf16_t* proj, int ldp, int qmcol, int gatecol, const bf16_t* kv, bf16_t* branch, int b0, int item, int tid, int wid, int lane, const bool stage = true) {
;     ...
;     float den = 0.f;
; #pragma unroll
;     for (int t = 0; t < 16; ++t)
; #pragma unroll
;         for (int j = 0; j < 4; ++j) { const float pv = exp2f((sacc[t][j] - mx) * 1.4426950408889634f); sacc[t][j] = pv; den += pv; }
;     den += __shfl_xor(den, 16); den += __shfl_xor(den, 32);
;     f32x4 oacc[4];
; #pragma unroll
;     for (int dt = 0; dt < 4; ++dt) oacc[dt] = (f32x4){0.f, 0.f, 0.f, 0.f};
; #pragma unroll
;     for (int kt = 0; kt < 8; ++kt) {
;         u32x4 pw; pw.x = cvt_pk_bf16(sacc[2 * kt][0], sacc[2 * kt][1]); pw.y = cvt_pk_bf16(sacc[2 * kt][2], sacc[2 * kt][3]);
;         pw.z = cvt_pk_bf16(sacc[2 * kt + 1][0], sacc[2 * kt + 1][1]); pw.w = cvt_pk_bf16(sacc[2 * kt + 1][2], sacc[2 * kt + 1][3]);
;         const bf16x8 pf = __builtin_bit_cast(bf16x8, pw);
;         const ldsp va = Vb + (32 * kt + quad * 4 + (li >> 2)) * KS + (li & 3) * 8;
; #pragma unroll
;         for (int dt = 0; dt < 4; ++dt) oacc[dt] = mfma16(lds_tr8(va + dt * 32, va + 16 * KS + dt * 32), pf, oacc[dt]);
;     }
	v_mfma_f32_16x16x32_bf16 v[42:45], v[58:61], v[42:45], v[50:53]
	v_cndmask_b32_e32 v63, 0, v235, vcc
	v_fmac_f32_e32 v63, 0x3fb8aa3b, v37
	v_exp_f32_e32 v37, v63
	v_cndmask_b32_e32 v63, 0, v236, vcc
	ds_read_b64_tr_b16 v[50:51], v97 offset:55296
	ds_read_b64_tr_b16 v[52:53], v97 offset:57600
	v_ldexp_f32 v37, v37, v63
	v_mul_f32_e32 v63, 0x3fb8aa3b, v26
	v_cmp_gt_f32_e32 vcc, s86, v63
	v_add_f32_e32 v62, v37, v62
	v_cvt_pk_bf16_f32 v35, v36, v37
	v_cndmask_b32_e32 v63, 0, v235, vcc
	v_fmac_f32_e32 v63, 0x3fb8aa3b, v26
	v_exp_f32_e32 v26, v63
	v_cndmask_b32_e32 v63, 0, v236, vcc
	v_ldexp_f32 v26, v26, v63
	v_mul_f32_e32 v63, 0x3fb8aa3b, v27
	v_cmp_gt_f32_e32 vcc, s86, v63
	v_add_f32_e32 v62, v26, v62
	s_nop 0
	v_cndmask_b32_e32 v63, 0, v235, vcc
	v_fmac_f32_e32 v63, 0x3fb8aa3b, v27
	v_exp_f32_e32 v27, v63
	v_cndmask_b32_e32 v63, 0, v236, vcc
	v_ldexp_f32 v27, v27, v63
	v_add_f32_e32 v63, v27, v62
	v_mul_f32_e32 v62, 0x3fb8aa3b, v28
	v_cmp_gt_f32_e32 vcc, s86, v62
	v_cvt_pk_bf16_f32 v36, v26, v27
	s_nop 0
	v_cndmask_b32_e32 v62, 0, v235, vcc
	v_fmac_f32_e32 v62, 0x3fb8aa3b, v28
	v_exp_f32_e32 v28, v62
	v_cndmask_b32_e32 v62, 0, v236, vcc
	v_ldexp_f32 v62, v28, v62
	v_add_f32_e32 v28, v62, v63
	v_mul_f32_e32 v63, 0x3fb8aa3b, v29
	v_cmp_gt_f32_e32 vcc, s86, v63
	s_nop 1
	v_cndmask_b32_e32 v63, 0, v235, vcc
	v_fmac_f32_e32 v63, 0x3fb8aa3b, v29
	v_exp_f32_e32 v29, v63
	v_cndmask_b32_e32 v63, 0, v236, vcc
	v_ldexp_f32 v63, v29, v63
	v_mul_f32_e32 v29, 0x3fb8aa3b, v22
	v_cmp_gt_f32_e32 vcc, s86, v29
	v_add_f32_e32 v28, v63, v28
	v_cvt_pk_bf16_f32 v37, v62, v63
	v_cndmask_b32_e32 v29, 0, v235, vcc
	v_fmac_f32_e32 v29, 0x3fb8aa3b, v22
	v_exp_f32_e32 v22, v29
	v_cndmask_b32_e32 v29, 0, v236, vcc
	s_waitcnt lgkmcnt(0)
	v_mfma_f32_16x16x32_bf16 v[38:41], v[50:53], v[34:37], v[38:41]
	ds_read_b64_tr_b16 v[50:51], v97 offset:55328
	ds_read_b64_tr_b16 v[52:53], v97 offset:57632
	v_ldexp_f32 v22, v22, v29
	v_mul_f32_e32 v29, 0x3fb8aa3b, v23
	v_cmp_gt_f32_e32 vcc, s86, v29
	v_add_f32_e32 v28, v22, v28
	s_waitcnt lgkmcnt(0)
	v_mfma_f32_16x16x32_bf16 v[46:49], v[50:53], v[34:37], v[46:49]
	v_cndmask_b32_e32 v29, 0, v235, vcc
	v_fmac_f32_e32 v29, 0x3fb8aa3b, v23
	v_exp_f32_e32 v23, v29
	v_cndmask_b32_e32 v29, 0, v236, vcc
	ds_read_b64_tr_b16 v[50:51], v97 offset:55360
	ds_read_b64_tr_b16 v[52:53], v97 offset:57664
	s_waitcnt lgkmcnt(0)
	v_mfma_f32_16x16x32_bf16 v[50:53], v[50:53], v[34:37], v[54:57]
	v_ldexp_f32 v23, v23, v29
	v_mul_f32_e32 v29, 0x3fb8aa3b, v24
	v_cmp_gt_f32_e32 vcc, s86, v29
	v_add_f32_e32 v28, v23, v28
	ds_read_b64_tr_b16 v[54:55], v97 offset:55392
	ds_read_b64_tr_b16 v[56:57], v97 offset:57696
	v_cndmask_b32_e32 v29, 0, v235, vcc
	v_fmac_f32_e32 v29, 0x3fb8aa3b, v24
	v_exp_f32_e32 v24, v29
	v_cndmask_b32_e32 v29, 0, v236, vcc
	s_waitcnt lgkmcnt(0)
	v_mfma_f32_16x16x32_bf16 v[34:37], v[54:57], v[34:37], v[42:45]
	v_ldexp_f32 v24, v24, v29
	v_mul_f32_e32 v29, 0x3fb8aa3b, v25
	v_cmp_gt_f32_e32 vcc, s86, v29
	v_add_f32_e32 v28, v24, v28
	s_nop 0
	v_cndmask_b32_e32 v29, 0, v235, vcc
	v_fmac_f32_e32 v29, 0x3fb8aa3b, v25
	v_exp_f32_e32 v25, v29
	v_cndmask_b32_e32 v29, 0, v236, vcc
	v_ldexp_f32 v25, v25, v29
	v_add_f32_e32 v29, v25, v28
	v_mul_f32_e32 v28, 0x3fb8aa3b, v14
	v_cmp_gt_f32_e32 vcc, s86, v28
	s_nop 1
	v_cndmask_b32_e32 v28, 0, v235, vcc
	v_fmac_f32_e32 v28, 0x3fb8aa3b, v14
	v_exp_f32_e32 v14, v28
	v_cndmask_b32_e32 v28, 0, v236, vcc
	v_ldexp_f32 v28, v14, v28
	v_add_f32_e32 v14, v28, v29
	v_mul_f32_e32 v29, 0x3fb8aa3b, v15
	v_cmp_gt_f32_e32 vcc, s86, v29
	s_nop 1
	v_cndmask_b32_e32 v29, 0, v235, vcc
	v_fmac_f32_e32 v29, 0x3fb8aa3b, v15
	v_exp_f32_e32 v15, v29
	v_cndmask_b32_e32 v29, 0, v236, vcc
	v_ldexp_f32 v29, v15, v29
	v_fma_f32 v15, v16, s85, -v85
	v_mul_f32_e32 v16, 0x3fb8aa3b, v15
	v_cmp_gt_f32_e32 vcc, s86, v16
	v_add_f32_e32 v14, v29, v14
	s_nop 0
	v_cndmask_b32_e32 v16, 0, v235, vcc
	v_fmac_f32_e32 v16, 0x3fb8aa3b, v15
	v_exp_f32_e32 v15, v16
	v_cndmask_b32_e32 v16, 0, v236, vcc
	v_ldexp_f32 v64, v15, v16
	v_fma_f32 v15, v17, s85, -v85
	v_mul_f32_e32 v16, 0x3fb8aa3b, v15
	v_cmp_gt_f32_e32 vcc, s86, v16
	v_add_f32_e32 v14, v64, v14
	s_nop 0
	v_cndmask_b32_e32 v16, 0, v235, vcc
	v_fmac_f32_e32 v16, 0x3fb8aa3b, v15
	v_exp_f32_e32 v15, v16
	v_cndmask_b32_e32 v16, 0, v236, vcc
	v_ldexp_f32 v65, v15, v16
	v_add_f32_e32 v15, v65, v14
	v_fma_f32 v14, v18, s85, -v85
	v_mul_f32_e32 v16, 0x3fb8aa3b, v14
	v_cmp_gt_f32_e32 vcc, s86, v16
	s_nop 1
	v_cndmask_b32_e32 v16, 0, v235, vcc
	v_fmac_f32_e32 v16, 0x3fb8aa3b, v14
	v_exp_f32_e32 v14, v16
	v_cndmask_b32_e32 v16, 0, v236, vcc
	v_ldexp_f32 v14, v14, v16
	v_add_f32_e32 v16, v14, v15
	v_fma_f32 v15, v19, s85, -v85
	v_mul_f32_e32 v17, 0x3fb8aa3b, v15
	v_cmp_gt_f32_e32 vcc, s86, v17
	s_nop 1
	v_cndmask_b32_e32 v17, 0, v235, vcc
	v_fmac_f32_e32 v17, 0x3fb8aa3b, v15
	v_exp_f32_e32 v15, v17
	v_cndmask_b32_e32 v17, 0, v236, vcc
	v_ldexp_f32 v15, v15, v17
	v_add_f32_e32 v17, v15, v16
	v_fma_f32 v16, v20, s85, -v85
	v_mul_f32_e32 v18, 0x3fb8aa3b, v16
	v_cmp_gt_f32_e32 vcc, s86, v18
	v_cvt_pk_bf16_f32 v20, v22, v23
	v_cvt_pk_bf16_f32 v22, v28, v29
	v_cndmask_b32_e32 v18, 0, v235, vcc
	v_fmac_f32_e32 v18, 0x3fb8aa3b, v16
	v_exp_f32_e32 v16, v18
	v_cndmask_b32_e32 v18, 0, v236, vcc
	v_cvt_pk_bf16_f32 v23, v64, v65
	v_cvt_pk_bf16_f32 v14, v14, v15
	v_ldexp_f32 v16, v16, v18
	v_add_f32_e32 v18, v16, v17
	v_fma_f32 v17, v21, s85, -v85
	v_mul_f32_e32 v19, 0x3fb8aa3b, v17
	v_cmp_gt_f32_e32 vcc, s86, v19
	v_cvt_pk_bf16_f32 v21, v24, v25
	ds_read_b64_tr_b16 v[24:25], v97 offset:59904
	ds_read_b64_tr_b16 v[26:27], v97 offset:62208
	v_cndmask_b32_e32 v19, 0, v235, vcc
	v_fmac_f32_e32 v19, 0x3fb8aa3b, v17
	v_exp_f32_e32 v17, v19
	v_cndmask_b32_e32 v19, 0, v236, vcc
	s_waitcnt lgkmcnt(0)
; DI unsigned cvt_pk_bf16(float lo, float hi) { const f32x2_t v = {lo, hi}; const bf16v2_t b = __builtin_convertvector(v, bf16v2_t); return __builtin_bit_cast(unsigned, b); }
; DI f32x4 mfma16(bf16x8 a, bf16x8 b, f32x4 c) { return __builtin_amdgcn_mfma_f32_16x16x32_bf16(a, b, c, 0, 0, 0); }
; DI void mem_attn_item(ldsp lds, const bf16_t* proj, int ldp, int qmcol, int gatecol, const bf16_t* kv, bf16_t* branch, int b0, int item, int tid, int wid, int lane, const bool stage = true) {
;     ...
;     float den = 0.f;
; #pragma unroll
;     for (int t = 0; t < 16; ++t)
; #pragma unroll
;         for (int j = 0; j < 4; ++j) { const float pv = exp2f((sacc[t][j] - mx) * 1.4426950408889634f); sacc[t][j] = pv; den += pv; }
;     den += __shfl_xor(den, 16); den += __shfl_xor(den, 32);
;     f32x4 oacc[4];
; #pragma unroll
;     for (int dt = 0; dt < 4; ++dt) oacc[dt] = (f32x4){0.f, 0.f, 0.f, 0.f};
; #pragma unroll
;     for (int kt = 0; kt < 8; ++kt) {
;         u32x4 pw; pw.x = cvt_pk_bf16(sacc[2 * kt][0], sacc[2 * kt][1]); pw.y = cvt_pk_bf16(sacc[2 * kt][2], sacc[2 * kt][3]);
;         pw.z = cvt_pk_bf16(sacc[2 * kt + 1][0], sacc[2 * kt + 1][1]); pw.w = cvt_pk_bf16(sacc[2 * kt + 1][2], sacc[2 * kt + 1][3]);
;         const bf16x8 pf = __builtin_bit_cast(bf16x8, pw);
;         const ldsp va = Vb + (32 * kt + quad * 4 + (li >> 2)) * KS + (li & 3) * 8;
; #pragma unroll
;         for (int dt = 0; dt < 4; ++dt) oacc[dt] = mfma16(lds_tr8(va + dt * 32, va + 16 * KS + dt * 32), pf, oacc[dt]);
;     }
	v_mfma_f32_16x16x32_bf16 v[24:27], v[24:27], v[20:23], v[38:41]
	s_nop 2
	ds_read_b64_tr_b16 v[38:39], v97 offset:59936
	ds_read_b64_tr_b16 v[40:41], v97 offset:62240
	v_ldexp_f32 v17, v17, v19
	v_mul_f32_e32 v19, 0x3fb8aa3b, v8
	v_cmp_gt_f32_e32 vcc, s86, v19
	v_add_f32_e32 v18, v17, v18
	s_waitcnt lgkmcnt(0)
	v_mfma_f32_16x16x32_bf16 v[38:41], v[38:41], v[20:23], v[46:49]
	v_cndmask_b32_e32 v19, 0, v235, vcc
	v_fmac_f32_e32 v19, 0x3fb8aa3b, v8
	v_exp_f32_e32 v8, v19
	v_cndmask_b32_e32 v19, 0, v236, vcc
	ds_read_b64_tr_b16 v[42:43], v97 offset:59968
	ds_read_b64_tr_b16 v[44:45], v97 offset:62272
	ds_read_b64_tr_b16 v[46:47], v97 offset:60000
	ds_read_b64_tr_b16 v[48:49], v97 offset:62304
	v_ldexp_f32 v8, v8, v19
	v_mul_f32_e32 v19, 0x3fb8aa3b, v9
	v_cmp_gt_f32_e32 vcc, s86, v19
	v_add_f32_e32 v18, v8, v18
	v_cvt_pk_bf16_f32 v15, v16, v17
	v_cndmask_b32_e32 v19, 0, v235, vcc
	v_fmac_f32_e32 v19, 0x3fb8aa3b, v9
	v_exp_f32_e32 v9, v19
	v_cndmask_b32_e32 v19, 0, v236, vcc
	s_waitcnt lgkmcnt(2)
	v_mfma_f32_16x16x32_bf16 v[42:45], v[42:45], v[20:23], v[50:53]
	v_ldexp_f32 v9, v9, v19
	v_mul_f32_e32 v19, 0x3fb8aa3b, v10
	v_cmp_gt_f32_e32 vcc, s86, v19
	v_add_f32_e32 v18, v9, v18
	v_cvt_pk_bf16_f32 v16, v8, v9
	v_cndmask_b32_e32 v19, 0, v235, vcc
	v_fmac_f32_e32 v19, 0x3fb8aa3b, v10
	v_exp_f32_e32 v10, v19
	v_cndmask_b32_e32 v19, 0, v236, vcc
	s_waitcnt lgkmcnt(0)
	v_mfma_f32_16x16x32_bf16 v[20:23], v[46:49], v[20:23], v[34:37]
	v_ldexp_f32 v10, v10, v19
	v_mul_f32_e32 v19, 0x3fb8aa3b, v11
	v_cmp_gt_f32_e32 vcc, s86, v19
	v_add_f32_e32 v18, v10, v18
	s_nop 0
	v_cndmask_b32_e32 v19, 0, v235, vcc
	v_fmac_f32_e32 v19, 0x3fb8aa3b, v11
	v_exp_f32_e32 v11, v19
	v_cndmask_b32_e32 v19, 0, v236, vcc
	v_ldexp_f32 v11, v11, v19
	v_mul_f32_e32 v19, 0x3fb8aa3b, v4
	v_cmp_gt_f32_e32 vcc, s86, v19
	v_add_f32_e32 v18, v11, v18
	v_cvt_pk_bf16_f32 v17, v10, v11
	v_cndmask_b32_e32 v19, 0, v235, vcc
	v_fmac_f32_e32 v19, 0x3fb8aa3b, v4
	v_exp_f32_e32 v4, v19
	v_cndmask_b32_e32 v19, 0, v236, vcc
	ds_read_b64_tr_b16 v[8:9], v97 offset:64512
	ds_read_b64_tr_b16 v[10:11], v98 offset:29952
	ds_read_b64_tr_b16 v[28:29], v98 offset:29984
	s_waitcnt lgkmcnt(1)
	v_mfma_f32_16x16x32_bf16 v[8:11], v[8:11], v[14:17], v[24:27]
	v_ldexp_f32 v4, v4, v19
	v_mul_f32_e32 v19, 0x3fb8aa3b, v5
	v_cmp_gt_f32_e32 vcc, s86, v19
	ds_read_b64_tr_b16 v[26:27], v97 offset:64544
	v_add_f32_e32 v18, v4, v18
	v_cndmask_b32_e32 v19, 0, v235, vcc
	v_fmac_f32_e32 v19, 0x3fb8aa3b, v5
	v_exp_f32_e32 v5, v19
	v_cndmask_b32_e32 v19, 0, v236, vcc
	s_waitcnt lgkmcnt(0)
	v_mfma_f32_16x16x32_bf16 v[24:27], v[26:29], v[14:17], v[38:41]
	v_ldexp_f32 v5, v5, v19
	v_mul_f32_e32 v19, 0x3fb8aa3b, v6
	v_cmp_gt_f32_e32 vcc, s86, v19
	v_add_f32_e32 v18, v5, v18
	ds_read_b64_tr_b16 v[34:35], v97 offset:64576
	ds_read_b64_tr_b16 v[36:37], v98 offset:30016
	v_cndmask_b32_e32 v19, 0, v235, vcc
	v_fmac_f32_e32 v19, 0x3fb8aa3b, v6
	v_exp_f32_e32 v6, v19
	v_cndmask_b32_e32 v19, 0, v236, vcc
	ds_read_b64_tr_b16 v[38:39], v97 offset:64608
	ds_read_b64_tr_b16 v[40:41], v98 offset:30048
	s_waitcnt lgkmcnt(0)
	v_mfma_f32_16x16x32_bf16 v[20:23], v[38:41], v[14:17], v[20:23]
	v_ldexp_f32 v6, v6, v19
	v_mul_f32_e32 v19, 0x3fb8aa3b, v7
	v_cmp_gt_f32_e32 vcc, s86, v19
	v_add_f32_e32 v18, v6, v18
	v_cvt_pk_bf16_f32 v38, v4, v5
	v_cndmask_b32_e32 v19, 0, v235, vcc
	v_fmac_f32_e32 v19, 0x3fb8aa3b, v7
	v_exp_f32_e32 v7, v19
	v_cndmask_b32_e32 v19, 0, v236, vcc
	v_mfma_f32_16x16x32_bf16 v[34:37], v[34:37], v[14:17], v[42:45]
	v_ldexp_f32 v7, v7, v19
	v_mul_f32_e32 v19, 0x3fb8aa3b, v0
	v_cmp_gt_f32_e32 vcc, s86, v19
	v_add_f32_e32 v18, v7, v18
	v_cvt_pk_bf16_f32 v39, v6, v7
	v_cndmask_b32_e32 v19, 0, v235, vcc
	v_fmac_f32_e32 v19, 0x3fb8aa3b, v0
	v_exp_f32_e32 v0, v19
	v_cndmask_b32_e32 v19, 0, v236, vcc
	v_ldexp_f32 v0, v0, v19
	v_mul_f32_e32 v19, 0x3fb8aa3b, v1
	v_cmp_gt_f32_e32 vcc, s86, v19
	v_add_f32_e32 v18, v0, v18
	s_nop 0
	v_cndmask_b32_e32 v19, 0, v235, vcc
	v_fmac_f32_e32 v19, 0x3fb8aa3b, v1
	v_exp_f32_e32 v1, v19
	v_cndmask_b32_e32 v19, 0, v236, vcc
	v_ldexp_f32 v1, v1, v19
	v_mul_f32_e32 v19, 0x3fb8aa3b, v2
	v_cmp_gt_f32_e32 vcc, s86, v19
	v_add_f32_e32 v18, v1, v18
	v_cvt_pk_bf16_f32 v40, v0, v1
	v_cndmask_b32_e32 v19, 0, v235, vcc
	v_fmac_f32_e32 v19, 0x3fb8aa3b, v2
	v_exp_f32_e32 v2, v19
	v_cndmask_b32_e32 v19, 0, v236, vcc
	v_ldexp_f32 v2, v2, v19
	v_mul_f32_e32 v19, 0x3fb8aa3b, v3
	v_cmp_gt_f32_e32 vcc, s86, v19
	v_add_f32_e32 v18, v2, v18
	s_nop 0
	v_cndmask_b32_e32 v19, 0, v235, vcc
	v_fmac_f32_e32 v19, 0x3fb8aa3b, v3
	v_exp_f32_e32 v3, v19
	v_cndmask_b32_e32 v19, 0, v236, vcc
	v_ldexp_f32 v3, v3, v19
; DI unsigned cvt_pk_bf16(float lo, float hi) { const f32x2_t v = {lo, hi}; const bf16v2_t b = __builtin_convertvector(v, bf16v2_t); return __builtin_bit_cast(unsigned, b); }
; DI float bf_lo(unsigned u) { return __uint_as_float(u << 16); }
; DI float bf_hi(unsigned u) { return __uint_as_float(u & 0xffff0000u); }
; DI f32x4 mfma16(bf16x8 a, bf16x8 b, f32x4 c) { return __builtin_amdgcn_mfma_f32_16x16x32_bf16(a, b, c, 0, 0, 0); }
; DI float silu_f(float x) { return x / (1.0f + __expf(-x)); }
; DI void mem_attn_item(ldsp lds, const bf16_t* proj, int ldp, int qmcol, int gatecol, const bf16_t* kv, bf16_t* branch, int b0, int item, int tid, int wid, int lane, const bool stage = true) {
;     ...
;     den += __shfl_xor(den, 16); den += __shfl_xor(den, 32);
;     f32x4 oacc[4];
; #pragma unroll
;     for (int dt = 0; dt < 4; ++dt) oacc[dt] = (f32x4){0.f, 0.f, 0.f, 0.f};
; #pragma unroll
;     for (int kt = 0; kt < 8; ++kt) {
;         u32x4 pw; pw.x = cvt_pk_bf16(sacc[2 * kt][0], sacc[2 * kt][1]); pw.y = cvt_pk_bf16(sacc[2 * kt][2], sacc[2 * kt][3]);
;         pw.z = cvt_pk_bf16(sacc[2 * kt + 1][0], sacc[2 * kt + 1][1]); pw.w = cvt_pk_bf16(sacc[2 * kt + 1][2], sacc[2 * kt + 1][3]);
;         const bf16x8 pf = __builtin_bit_cast(bf16x8, pw);
;         const ldsp va = Vb + (32 * kt + quad * 4 + (li >> 2)) * KS + (li & 3) * 8;
; #pragma unroll
;         for (int dt = 0; dt < 4; ++dt) oacc[dt] = mfma16(lds_tr8(va + dt * 32, va + 16 * KS + dt * 32), pf, oacc[dt]);
;     }
;     const float inv = 1.0f / den;
;     bf16_t* dst = branch + ((size_t)(b0 + bl) * 2048 + tq) * 1024 + 768 + hm * 64 + quad * 4;
; #pragma unroll
;     for (int dt = 0; dt < 4; ++dt) {
;         const u32x2 gt = gtv[dt];
;         u32x2 o;
;         o.x = cvt_pk_bf16(oacc[dt][0] * inv * silu_f(bf_lo(gt.x)), oacc[dt][1] * inv * silu_f(bf_hi(gt.x)));
;         o.y = cvt_pk_bf16(oacc[dt][2] * inv * silu_f(bf_lo(gt.y)), oacc[dt][3] * inv * silu_f(bf_hi(gt.y)));
;         *(u32x2*)(dst + dt * 16) = o;
;     }
.Lma_join_dil:
	v_add_f32_e32 v18, v3, v18
	v_cvt_pk_bf16_f32 v41, v2, v3
	ds_read_b64_tr_b16 v[0:1], v98 offset:32256
	ds_read_b64_tr_b16 v[2:3], v98 offset:34560
	s_waitcnt lgkmcnt(0)
	v_mfma_f32_16x16x32_bf16 v[14:17], v[0:3], v[38:41], v[8:11]
	ds_read_b64_tr_b16 v[0:1], v98 offset:32288
	ds_read_b64_tr_b16 v[2:3], v98 offset:34592
	ds_bpermute_b32 v19, v33, v18
	s_waitcnt lgkmcnt(0)
	v_add_f32_e32 v18, v18, v19
	v_mfma_f32_16x16x32_bf16 v[8:11], v[0:3], v[38:41], v[24:27]
	ds_read_b64_tr_b16 v[0:1], v98 offset:32320
	ds_read_b64_tr_b16 v[2:3], v98 offset:34624
	ds_bpermute_b32 v19, v96, v18
	s_waitcnt vmcnt(3)
	v_and_b32_e32 v24, 0xffff0000, v92
	s_waitcnt lgkmcnt(1)
	v_mfma_f32_16x16x32_bf16 v[4:7], v[0:3], v[38:41], v[34:37]
	ds_read_b64_tr_b16 v[0:1], v98 offset:32352
	ds_read_b64_tr_b16 v[2:3], v98 offset:34656
	s_waitcnt lgkmcnt(2)
	v_add_f32_e32 v18, v18, v19
	v_div_scale_f32 v19, s[22:23], v18, v18, 1.0
	s_waitcnt lgkmcnt(0)
	v_mfma_f32_16x16x32_bf16 v[0:3], v[0:3], v[38:41], v[20:23]
	s_nop 2
	v_rcp_f32_e32 v20, v19
	s_nop 0
	v_fma_f32 v21, -v19, v20, 1.0
	v_fmac_f32_e32 v20, v21, v20
	v_div_scale_f32 v21, vcc, 1.0, v18, 1.0
	v_mul_f32_e32 v22, v21, v20
	v_fma_f32 v23, -v19, v22, v21
	v_fmac_f32_e32 v22, v23, v20
	v_fma_f32 v19, -v19, v22, v21
	v_lshlrev_b32_e32 v21, 16, v92
	v_div_fmas_f32 v19, v19, v20, v22
	v_mul_f32_e32 v22, 0xbfb8aa3b, v21
	v_mul_f32_e32 v23, 0xbfb8aa3b, v24
	v_exp_f32_e32 v22, v22
	v_exp_f32_e32 v23, v23
	v_div_fixup_f32 v20, v19, v18, 1.0
	v_pk_mul_f32 v[14:15], v[20:21], v[14:15] op_sel_hi:[0,1]
	v_lshlrev_b64 v[18:19], 11, v[94:95]
	v_pk_add_f32 v[22:23], v[22:23], 1.0 op_sel_hi:[1,0]
	v_lshl_add_u64 v[18:19], v[82:83], 0, v[18:19]
	v_div_scale_f32 v25, s[22:23], v23, v23, v24
	v_rcp_f32_e32 v26, v25
	s_nop 0
	v_fma_f32 v27, -v25, v26, 1.0
	v_fmac_f32_e32 v26, v27, v26
	v_div_scale_f32 v27, vcc, v24, v23, v24
	v_mul_f32_e32 v28, v27, v26
	v_fma_f32 v29, -v25, v28, v27
	v_fmac_f32_e32 v28, v29, v26
	v_fma_f32 v25, -v25, v28, v27
	v_div_fmas_f32 v25, v25, v26, v28
	v_div_fixup_f32 v23, v25, v23, v24
	v_div_scale_f32 v24, s[22:23], v22, v22, v21
	v_rcp_f32_e32 v25, v24
	s_nop 0
	v_fma_f32 v26, -v24, v25, 1.0
	v_fmac_f32_e32 v25, v26, v25
	v_div_scale_f32 v26, vcc, v21, v22, v21
	v_mul_f32_e32 v27, v26, v25
	v_fma_f32 v28, -v24, v27, v26
	v_fmac_f32_e32 v27, v28, v25
	v_fma_f32 v24, -v24, v27, v26
	v_div_fmas_f32 v24, v24, v25, v27
	v_div_fixup_f32 v22, v24, v22, v21
	v_pk_mul_f32 v[14:15], v[22:23], v[14:15]
	v_and_b32_e32 v21, 0xffff0000, v93
	v_cvt_pk_bf16_f32 v14, v14, v15
	v_lshlrev_b32_e32 v15, 16, v93
	v_mul_f32_e32 v22, 0xbfb8aa3b, v15
	v_mul_f32_e32 v23, 0xbfb8aa3b, v21
	v_exp_f32_e32 v22, v22
	v_exp_f32_e32 v23, v23
	v_pk_mul_f32 v[16:17], v[20:21], v[16:17] op_sel_hi:[0,1]
	v_pk_add_f32 v[22:23], v[22:23], 1.0 op_sel_hi:[1,0]
	s_nop 0
	v_div_scale_f32 v24, s[22:23], v23, v23, v21
	v_rcp_f32_e32 v25, v24
	s_nop 0
	v_fma_f32 v26, -v24, v25, 1.0
	v_fmac_f32_e32 v25, v26, v25
	v_div_scale_f32 v26, vcc, v21, v23, v21
	v_mul_f32_e32 v27, v26, v25
	v_fma_f32 v28, -v24, v27, v26
	v_fmac_f32_e32 v27, v28, v25
	v_fma_f32 v24, -v24, v27, v26
	v_div_fmas_f32 v24, v24, v25, v27
	v_div_fixup_f32 v23, v24, v23, v21
	v_div_scale_f32 v21, s[22:23], v22, v22, v15
	v_rcp_f32_e32 v24, v21
	s_nop 0
	v_fma_f32 v25, -v21, v24, 1.0
	v_fmac_f32_e32 v24, v25, v24
	v_div_scale_f32 v25, vcc, v15, v22, v15
	v_mul_f32_e32 v26, v25, v24
	v_fma_f32 v27, -v21, v26, v25
	v_fmac_f32_e32 v26, v27, v24
	v_fma_f32 v21, -v21, v26, v25
	v_div_fmas_f32 v21, v21, v24, v26
	v_div_fixup_f32 v22, v21, v22, v15
	v_pk_mul_f32 v[16:17], v[22:23], v[16:17]
	v_pk_mul_f32 v[8:9], v[20:21], v[8:9] op_sel_hi:[0,1]
	v_cvt_pk_bf16_f32 v15, v16, v17
	s_waitcnt vmcnt(2)
	v_lshlrev_b32_e32 v16, 16, v90
	v_and_b32_e32 v17, 0xffff0000, v90
	global_store_dwordx2 v[18:19], v[14:15], off offset:1536
	v_mul_f32_e32 v14, 0xbfb8aa3b, v16
	v_mul_f32_e32 v15, 0xbfb8aa3b, v17
	v_exp_f32_e32 v14, v14
	v_exp_f32_e32 v15, v15
	s_nop 0
	v_pk_add_f32 v[14:15], v[14:15], 1.0 op_sel_hi:[1,0]
	s_nop 0
	v_div_scale_f32 v21, s[22:23], v15, v15, v17
	v_rcp_f32_e32 v22, v21
	s_nop 0
	v_fma_f32 v23, -v21, v22, 1.0
	v_fmac_f32_e32 v22, v23, v22
	v_div_scale_f32 v23, vcc, v17, v15, v17
	v_mul_f32_e32 v24, v23, v22
	v_fma_f32 v25, -v21, v24, v23
	v_fmac_f32_e32 v24, v25, v22
	v_fma_f32 v21, -v21, v24, v23
	v_div_fmas_f32 v21, v21, v22, v24
	v_div_fixup_f32 v15, v21, v15, v17
	v_div_scale_f32 v17, s[22:23], v14, v14, v16
	v_rcp_f32_e32 v21, v17
	s_nop 0
	v_fma_f32 v22, -v17, v21, 1.0
	v_fmac_f32_e32 v21, v22, v21
	v_div_scale_f32 v22, vcc, v16, v14, v16
	v_mul_f32_e32 v23, v22, v21
	v_fma_f32 v24, -v17, v23, v22
	v_fmac_f32_e32 v23, v24, v21
	v_fma_f32 v17, -v17, v23, v22
	v_div_fmas_f32 v17, v17, v21, v23
	v_div_fixup_f32 v14, v17, v14, v16
	v_pk_mul_f32 v[8:9], v[14:15], v[8:9]
	v_and_b32_e32 v16, 0xffff0000, v91
	v_cvt_pk_bf16_f32 v8, v8, v9
	v_lshlrev_b32_e32 v9, 16, v91
	v_mul_f32_e32 v14, 0xbfb8aa3b, v9
	v_mul_f32_e32 v15, 0xbfb8aa3b, v16
	v_exp_f32_e32 v14, v14
	v_exp_f32_e32 v15, v15
	v_pk_mul_f32 v[10:11], v[20:21], v[10:11] op_sel_hi:[0,1]
	v_pk_add_f32 v[14:15], v[14:15], 1.0 op_sel_hi:[1,0]
	s_nop 0
	v_div_scale_f32 v17, s[22:23], v15, v15, v16
	v_rcp_f32_e32 v21, v17
	s_nop 0
	v_fma_f32 v22, -v17, v21, 1.0
	v_fmac_f32_e32 v21, v22, v21
	v_div_scale_f32 v22, vcc, v16, v15, v16
	v_mul_f32_e32 v23, v22, v21
	v_fma_f32 v24, -v17, v23, v22
	v_fmac_f32_e32 v23, v24, v21
	v_fma_f32 v17, -v17, v23, v22
	v_div_fmas_f32 v17, v17, v21, v23
	v_div_fixup_f32 v15, v17, v15, v16
	v_div_scale_f32 v16, s[22:23], v14, v14, v9
	v_rcp_f32_e32 v17, v16
	s_nop 0
	v_fma_f32 v21, -v16, v17, 1.0
	v_fmac_f32_e32 v17, v21, v17
	v_div_scale_f32 v21, vcc, v9, v14, v9
	v_mul_f32_e32 v22, v21, v17
	v_fma_f32 v23, -v16, v22, v21
	v_fmac_f32_e32 v22, v23, v17
	v_fma_f32 v16, -v16, v22, v21
	v_div_fmas_f32 v16, v16, v17, v22
	v_div_fixup_f32 v14, v16, v14, v9
	v_pk_mul_f32 v[10:11], v[14:15], v[10:11]
	v_pk_mul_f32 v[4:5], v[20:21], v[4:5] op_sel_hi:[0,1]
	v_cvt_pk_bf16_f32 v9, v10, v11
	s_waitcnt vmcnt(2)
; DI unsigned cvt_pk_bf16(float lo, float hi) { const f32x2_t v = {lo, hi}; const bf16v2_t b = __builtin_convertvector(v, bf16v2_t); return __builtin_bit_cast(unsigned, b); }
; DI float bf_lo(unsigned u) { return __uint_as_float(u << 16); }
; DI float bf_hi(unsigned u) { return __uint_as_float(u & 0xffff0000u); }
; DI float silu_f(float x) { return x / (1.0f + __expf(-x)); }
; DI void mem_attn_item(ldsp lds, const bf16_t* proj, int ldp, int qmcol, int gatecol, const bf16_t* kv, bf16_t* branch, int b0, int item, int tid, int wid, int lane, const bool stage = true) {
;     ...
;     const float inv = 1.0f / den;
;     bf16_t* dst = branch + ((size_t)(b0 + bl) * 2048 + tq) * 1024 + 768 + hm * 64 + quad * 4;
; #pragma unroll
;     for (int dt = 0; dt < 4; ++dt) {
;         const u32x2 gt = gtv[dt];
;         u32x2 o;
;         o.x = cvt_pk_bf16(oacc[dt][0] * inv * silu_f(bf_lo(gt.x)), oacc[dt][1] * inv * silu_f(bf_hi(gt.x)));
;         o.y = cvt_pk_bf16(oacc[dt][2] * inv * silu_f(bf_lo(gt.y)), oacc[dt][3] * inv * silu_f(bf_hi(gt.y)));
;         *(u32x2*)(dst + dt * 16) = o;
;     }
;     __syncthreads();
	v_lshlrev_b32_e32 v10, 16, v88
	v_and_b32_e32 v11, 0xffff0000, v88
	global_store_dwordx2 v[18:19], v[8:9], off offset:1568
	v_mul_f32_e32 v8, 0xbfb8aa3b, v10
	v_mul_f32_e32 v9, 0xbfb8aa3b, v11
	v_exp_f32_e32 v8, v8
	v_exp_f32_e32 v9, v9
	s_nop 0
	v_pk_add_f32 v[8:9], v[8:9], 1.0 op_sel_hi:[1,0]
	s_nop 0
	v_div_scale_f32 v14, s[22:23], v9, v9, v11
	v_rcp_f32_e32 v15, v14
	s_nop 0
	v_fma_f32 v16, -v14, v15, 1.0
	v_fmac_f32_e32 v15, v16, v15
	v_div_scale_f32 v16, vcc, v11, v9, v11
	v_mul_f32_e32 v17, v16, v15
	v_fma_f32 v21, -v14, v17, v16
	v_fmac_f32_e32 v17, v21, v15
	v_fma_f32 v14, -v14, v17, v16
	v_div_fmas_f32 v14, v14, v15, v17
	v_div_fixup_f32 v9, v14, v9, v11
	v_div_scale_f32 v11, s[22:23], v8, v8, v10
	v_rcp_f32_e32 v14, v11
	v_pk_mul_f32 v[6:7], v[20:21], v[6:7] op_sel_hi:[0,1]
	v_pk_mul_f32 v[0:1], v[20:21], v[0:1] op_sel_hi:[0,1]
	v_pk_mul_f32 v[2:3], v[20:21], v[2:3] op_sel_hi:[0,1]
	v_fma_f32 v15, -v11, v14, 1.0
	v_fmac_f32_e32 v14, v15, v14
	v_div_scale_f32 v15, vcc, v10, v8, v10
	v_mul_f32_e32 v16, v15, v14
	v_fma_f32 v17, -v11, v16, v15
	v_fmac_f32_e32 v16, v17, v14
	v_fma_f32 v11, -v11, v16, v15
	v_div_fmas_f32 v11, v11, v14, v16
	v_div_fixup_f32 v8, v11, v8, v10
	v_pk_mul_f32 v[4:5], v[8:9], v[4:5]
	v_and_b32_e32 v10, 0xffff0000, v89
	v_cvt_pk_bf16_f32 v4, v4, v5
	v_lshlrev_b32_e32 v5, 16, v89
	v_mul_f32_e32 v8, 0xbfb8aa3b, v5
	v_mul_f32_e32 v9, 0xbfb8aa3b, v10
	v_exp_f32_e32 v8, v8
	v_exp_f32_e32 v9, v9
	s_nop 0
	v_pk_add_f32 v[8:9], v[8:9], 1.0 op_sel_hi:[1,0]
	s_nop 0
	v_div_scale_f32 v11, s[22:23], v9, v9, v10
	v_rcp_f32_e32 v14, v11
	s_nop 0
	v_fma_f32 v15, -v11, v14, 1.0
	v_fmac_f32_e32 v14, v15, v14
	v_div_scale_f32 v15, vcc, v10, v9, v10
	v_mul_f32_e32 v16, v15, v14
	v_fma_f32 v17, -v11, v16, v15
	v_fmac_f32_e32 v16, v17, v14
	v_fma_f32 v11, -v11, v16, v15
	v_div_fmas_f32 v11, v11, v14, v16
	v_div_fixup_f32 v9, v11, v9, v10
	v_div_scale_f32 v10, s[22:23], v8, v8, v5
	v_rcp_f32_e32 v11, v10
	s_nop 0
	v_fma_f32 v14, -v10, v11, 1.0
	v_fmac_f32_e32 v11, v14, v11
	v_div_scale_f32 v14, vcc, v5, v8, v5
	v_mul_f32_e32 v15, v14, v11
	v_fma_f32 v16, -v10, v15, v14
	v_fmac_f32_e32 v15, v16, v11
	v_fma_f32 v10, -v10, v15, v14
	v_div_fmas_f32 v10, v10, v11, v15
	v_div_fixup_f32 v8, v10, v8, v5
	v_pk_mul_f32 v[6:7], v[8:9], v[6:7]
	s_nop 0
	v_cvt_pk_bf16_f32 v5, v6, v7
	s_waitcnt vmcnt(2)
	v_lshlrev_b32_e32 v6, 16, v86
	v_and_b32_e32 v7, 0xffff0000, v86
	global_store_dwordx2 v[18:19], v[4:5], off offset:1600
	v_mul_f32_e32 v4, 0xbfb8aa3b, v6
	v_mul_f32_e32 v5, 0xbfb8aa3b, v7
	v_exp_f32_e32 v4, v4
	v_exp_f32_e32 v5, v5
	s_nop 0
	v_pk_add_f32 v[4:5], v[4:5], 1.0 op_sel_hi:[1,0]
	s_nop 0
	v_div_scale_f32 v8, s[22:23], v5, v5, v7
	v_rcp_f32_e32 v9, v8
	s_nop 0
	v_fma_f32 v10, -v8, v9, 1.0
	v_fmac_f32_e32 v9, v10, v9
	v_div_scale_f32 v10, vcc, v7, v5, v7
	v_mul_f32_e32 v11, v10, v9
	v_fma_f32 v14, -v8, v11, v10
	v_fmac_f32_e32 v11, v14, v9
	v_fma_f32 v8, -v8, v11, v10
	v_div_fmas_f32 v8, v8, v9, v11
	v_div_fixup_f32 v5, v8, v5, v7
	v_div_scale_f32 v7, s[22:23], v4, v4, v6
	v_rcp_f32_e32 v8, v7
	s_nop 0
	v_fma_f32 v9, -v7, v8, 1.0
	v_fmac_f32_e32 v8, v9, v8
	v_div_scale_f32 v9, vcc, v6, v4, v6
	v_mul_f32_e32 v10, v9, v8
	v_fma_f32 v11, -v7, v10, v9
	v_fmac_f32_e32 v10, v11, v8
	v_fma_f32 v7, -v7, v10, v9
	v_div_fmas_f32 v7, v7, v8, v10
	v_div_fixup_f32 v4, v7, v4, v6
	v_pk_mul_f32 v[0:1], v[4:5], v[0:1]
	v_and_b32_e32 v6, 0xffff0000, v87
	v_cvt_pk_bf16_f32 v0, v0, v1
	v_lshlrev_b32_e32 v1, 16, v87
	v_mul_f32_e32 v4, 0xbfb8aa3b, v1
	v_mul_f32_e32 v5, 0xbfb8aa3b, v6
	v_exp_f32_e32 v4, v4
	v_exp_f32_e32 v5, v5
	s_nop 0
	v_pk_add_f32 v[4:5], v[4:5], 1.0 op_sel_hi:[1,0]
	s_nop 0
	v_div_scale_f32 v7, s[22:23], v5, v5, v6
	v_rcp_f32_e32 v8, v7
	s_nop 0
	v_fma_f32 v9, -v7, v8, 1.0
	v_fmac_f32_e32 v8, v9, v8
	v_div_scale_f32 v9, vcc, v6, v5, v6
	v_mul_f32_e32 v10, v9, v8
	v_fma_f32 v11, -v7, v10, v9
	v_fmac_f32_e32 v10, v11, v8
	v_fma_f32 v7, -v7, v10, v9
	v_div_fmas_f32 v7, v7, v8, v10
	v_div_fixup_f32 v5, v7, v5, v6
	v_div_scale_f32 v6, s[22:23], v4, v4, v1
	v_rcp_f32_e32 v7, v6
	s_mov_b64 s[22:23], 0
	v_fma_f32 v8, -v6, v7, 1.0
	v_fmac_f32_e32 v7, v8, v7
	v_div_scale_f32 v8, vcc, v1, v4, v1
	v_mul_f32_e32 v9, v8, v7
	v_fma_f32 v10, -v6, v9, v8
	v_fmac_f32_e32 v9, v10, v7
	v_fma_f32 v6, -v6, v9, v8
	v_div_fmas_f32 v6, v6, v7, v9
	v_div_fixup_f32 v4, v6, v4, v1
	v_pk_mul_f32 v[2:3], v[4:5], v[2:3]
	s_and_b64 vcc, exec, s[40:41]
	v_cvt_pk_bf16_f32 v1, v2, v3
	global_store_dwordx2 v[18:19], v[0:1], off offset:1632
	s_barrier
	s_cbranch_vccnz .LBB0_447

; DI f32x4 mfma16(bf16x8 a, bf16x8 b, f32x4 c) { return __builtin_amdgcn_mfma_f32_16x16x32_bf16(a, b, c, 0, 0, 0); }
; DI void mem_attn_item(ldsp lds, const bf16_t* proj, int ldp, int qmcol, int gatecol, const bf16_t* kv, bf16_t* branch, int b0, int item, int tid, int wid, int lane, const bool stage = true) {
;     ...
;     const int li = lane & 15, quad = lane >> 4;
;     const int tq = 128 * qt + 16 * wid + li;
;     const size_t prow = (size_t)bl * 2048 + tq;
;     bf16x8 qf[2];
; #pragma unroll
;     for (int ks = 0; ks < 2; ++ks) qf[ks] = *(const bf16x8*)(proj + prow * ldp + qmcol + hm * 64 + ks * 32 + quad * 8);
;     u32x2 gtv[4];
; #pragma unroll
;     for (int dt = 0; dt < 4; ++dt) gtv[dt] = *(const u32x2*)(proj + prow * ldp + gatecol + 768 + hm * 64 + quad * 4 + dt * 16);
;     __syncthreads();
;     f32x4 sacc[16];
; #pragma unroll
;     for (int t = 0; t < 16; ++t) {
;         sacc[t] = (f32x4){0.f, 0.f, 0.f, 0.f};
;         const ldsp ka = Kb + (16 * t + li) * KS + quad * 16;
; #pragma unroll
;         for (int ks = 0; ks < 2; ++ks) sacc[t] = mfma16(lds_rd8(ka + ks * 64), qf[ks], sacc[t]);
;     }
.LBB0_511:
	s_add_i32 s15, s93, s14
	s_and_b32 s15, s15, 0x780
	v_add_u32_e32 v94, s15, v13
	v_readlane_b32 s22, v252, 10
	v_ashrrev_i32_e32 v95, 31, v94
	v_readlane_b32 s23, v252, 11
	v_mov_b32_e32 v83, v12
	v_mov_b32_e32 v85, v12
	v_lshl_add_u64 v[0:1], s[22:23], 0, v[94:95]
	v_readlane_b32 s22, v251, 15
	v_readlane_b32 s23, v251, 16
	s_movk_i32 s15, 0x1000
	s_addk_i32 s14, 0x80
	v_mov_b64_e32 v[2:3], s[22:23]
	v_mad_u64_u32 v[2:3], s[22:23], v0, s94, v[2:3]
	v_mad_i32_i24 v3, v1, s94, v3
	v_lshl_add_u64 v[4:5], v[2:3], 0, s[0:1]
	v_lshl_add_u64 v[0:1], v[4:5], 0, v[82:83]
	global_load_dwordx4 v[70:73], v[0:1], off offset:3104
	s_nop 0
	global_load_dwordx4 v[0:3], v[0:1], off offset:3168
	v_lshl_add_u64 v[4:5], v[4:5], 0, v[84:85]
	v_lshl_add_u64 v[6:7], v[4:5], 0, s[26:27]
	v_add_co_u32_e32 v4, vcc, s15, v4
	s_mov_b32 s15, 0xff800000
	s_nop 0
	v_addc_co_u32_e32 v5, vcc, 0, v5, vcc
	global_load_dwordx2 v[92:93], v[4:5], off offset:1056
	global_load_dwordx2 v[90:91], v[6:7], off offset:32
	global_load_dwordx2 v[88:89], v[6:7], off offset:64
	global_load_dwordx2 v[86:87], v[6:7], off offset:96
	s_waitcnt lgkmcnt(0)
	s_barrier
	ds_read_b128 v[4:7], v103
	ds_read_b128 v[8:11], v103 offset:64
	s_cmpk_eq_i32 s14, 0x400
	s_waitcnt vmcnt(5) lgkmcnt(1)
	v_mfma_f32_16x16x32_bf16 v[4:7], v[4:7], v[70:73], 0
	ds_read_b128 v[108:111], v103 offset:32320
	s_waitcnt vmcnt(4) lgkmcnt(1)
	v_mfma_f32_16x16x32_bf16 v[66:69], v[8:11], v[0:3], v[4:7]
	ds_read_b128 v[8:11], v103 offset:2368
	s_nop 3
	ds_read_b128 v[4:7], v103 offset:2304
	s_waitcnt lgkmcnt(0)
	v_mfma_f32_16x16x32_bf16 v[4:7], v[4:7], v[70:73], 0
	v_mfma_f32_16x16x32_bf16 v[62:65], v[8:11], v[0:3], v[4:7]
	ds_read_b128 v[8:11], v103 offset:4672
	s_nop 5
	ds_read_b128 v[4:7], v103 offset:4608
	s_waitcnt lgkmcnt(0)
	v_mfma_f32_16x16x32_bf16 v[4:7], v[4:7], v[70:73], 0
	v_mfma_f32_16x16x32_bf16 v[58:61], v[8:11], v[0:3], v[4:7]
	ds_read_b128 v[8:11], v104 offset:64
	s_nop 5
	ds_read_b128 v[4:7], v104
	s_waitcnt lgkmcnt(0)
	v_mfma_f32_16x16x32_bf16 v[4:7], v[4:7], v[70:73], 0
	v_mfma_f32_16x16x32_bf16 v[54:57], v[8:11], v[0:3], v[4:7]
	ds_read_b128 v[8:11], v103 offset:9280
	s_nop 5
	ds_read_b128 v[4:7], v103 offset:9216
	s_waitcnt lgkmcnt(0)
	v_mfma_f32_16x16x32_bf16 v[4:7], v[4:7], v[70:73], 0
	v_mfma_f32_16x16x32_bf16 v[50:53], v[8:11], v[0:3], v[4:7]
	ds_read_b128 v[8:11], v103 offset:11584
	s_nop 5
	ds_read_b128 v[4:7], v103 offset:11520
	s_waitcnt lgkmcnt(0)
	v_mfma_f32_16x16x32_bf16 v[4:7], v[4:7], v[70:73], 0
	v_mfma_f32_16x16x32_bf16 v[46:49], v[8:11], v[0:3], v[4:7]
	ds_read_b128 v[8:11], v103 offset:13888
	s_nop 5
	ds_read_b128 v[4:7], v103 offset:13824
	s_waitcnt lgkmcnt(0)
	v_mfma_f32_16x16x32_bf16 v[4:7], v[4:7], v[70:73], 0
	v_mfma_f32_16x16x32_bf16 v[42:45], v[8:11], v[0:3], v[4:7]
	ds_read_b128 v[8:11], v105 offset:64
	s_nop 5
	ds_read_b128 v[4:7], v105
	s_waitcnt lgkmcnt(0)
	v_mfma_f32_16x16x32_bf16 v[4:7], v[4:7], v[70:73], 0
	v_mfma_f32_16x16x32_bf16 v[38:41], v[8:11], v[0:3], v[4:7]
	ds_read_b128 v[8:11], v103 offset:18496
	s_nop 5
	ds_read_b128 v[4:7], v103 offset:18432
	s_waitcnt lgkmcnt(0)
	v_mfma_f32_16x16x32_bf16 v[4:7], v[4:7], v[70:73], 0
	v_mfma_f32_16x16x32_bf16 v[34:37], v[8:11], v[0:3], v[4:7]
	ds_read_b128 v[8:11], v103 offset:20800
	s_nop 5
	ds_read_b128 v[4:7], v103 offset:20736
	s_waitcnt lgkmcnt(0)
	v_mfma_f32_16x16x32_bf16 v[4:7], v[4:7], v[70:73], 0
	v_mfma_f32_16x16x32_bf16 v[26:29], v[8:11], v[0:3], v[4:7]
	ds_read_b128 v[8:11], v103 offset:23104
	s_nop 5
	ds_read_b128 v[4:7], v103 offset:23040
	s_waitcnt lgkmcnt(0)
	v_mfma_f32_16x16x32_bf16 v[4:7], v[4:7], v[70:73], 0
	v_mfma_f32_16x16x32_bf16 v[22:25], v[8:11], v[0:3], v[4:7]
	ds_read_b128 v[8:11], v106 offset:64
	s_nop 5
	ds_read_b128 v[4:7], v106
	s_waitcnt lgkmcnt(0)
	v_mfma_f32_16x16x32_bf16 v[4:7], v[4:7], v[70:73], 0
	v_mfma_f32_16x16x32_bf16 v[18:21], v[8:11], v[0:3], v[4:7]
	ds_read_b128 v[8:11], v103 offset:27712
	s_nop 5
	ds_read_b128 v[4:7], v103 offset:27648
	s_waitcnt lgkmcnt(0)
	v_mfma_f32_16x16x32_bf16 v[4:7], v[4:7], v[70:73], 0
	v_mfma_f32_16x16x32_bf16 v[14:17], v[8:11], v[0:3], v[4:7]
	ds_read_b128 v[8:11], v103 offset:30016
	s_nop 5
	ds_read_b128 v[4:7], v103 offset:29952
	s_waitcnt lgkmcnt(0)
	v_mfma_f32_16x16x32_bf16 v[4:7], v[4:7], v[70:73], 0
	v_mfma_f32_16x16x32_bf16 v[8:11], v[8:11], v[0:3], v[4:7]
	s_nop 6
	ds_read_b128 v[4:7], v103 offset:32256
	s_waitcnt lgkmcnt(0)
	v_mfma_f32_16x16x32_bf16 v[4:7], v[4:7], v[70:73], 0
	v_mfma_f32_16x16x32_bf16 v[4:7], v[108:111], v[0:3], v[4:7]
	ds_read_b128 v[108:111], v107
	s_waitcnt lgkmcnt(0)
	v_mfma_f32_16x16x32_bf16 v[70:73], v[108:111], v[70:73], 0
	ds_read_b128 v[108:111], v107 offset:64
	s_waitcnt lgkmcnt(0)
; DI void mem_attn_item(ldsp lds, const bf16_t* proj, int ldp, int qmcol, int gatecol, const bf16_t* kv, bf16_t* branch, int b0, int item, int tid, int wid, int lane, const bool stage = true) {
;     ...
;     float mx = -INFINITY;
; #pragma unroll
;     for (int t = 0; t < 16; ++t)
; #pragma unroll
;         for (int j = 0; j < 4; ++j) { const float v = sacc[t][j] * 0.125f; sacc[t][j] = v; mx = fmaxf(mx, v); }
;     mx = fmaxf(mx, __shfl_xor(mx, 16)); mx = fmaxf(mx, __shfl_xor(mx, 32));
;     float den = 0.f;
; #pragma unroll
;     for (int t = 0; t < 16; ++t)
; #pragma unroll
;         for (int j = 0; j < 4; ++j) { const float pv = exp2f((sacc[t][j] - mx) * 1.4426950408889634f); sacc[t][j] = pv; den += pv; }
	v_mfma_f32_16x16x32_bf16 v[0:3], v[108:111], v[0:3], v[70:73]
	s_nop 4
	v_mul_f32_e32 v70, 0x3e000000, v66
	v_mul_f32_e32 v71, 0x3e000000, v67
	v_max3_f32 v70, v70, s15, v71
	v_mul_f32_e32 v71, 0x3e000000, v68
	v_mul_f32_e32 v72, 0x3e000000, v69
	v_max3_f32 v70, v70, v71, v72
	v_mul_f32_e32 v71, 0x3e000000, v62
	v_mul_f32_e32 v72, 0x3e000000, v63
	v_max3_f32 v70, v70, v71, v72
	v_mul_f32_e32 v71, 0x3e000000, v64
	v_mul_f32_e32 v72, 0x3e000000, v65
	v_max3_f32 v70, v70, v71, v72
	v_mul_f32_e32 v71, 0x3e000000, v58
	v_mul_f32_e32 v72, 0x3e000000, v59
	v_max3_f32 v70, v70, v71, v72
	v_mul_f32_e32 v71, 0x3e000000, v60
	v_mul_f32_e32 v72, 0x3e000000, v61
	v_max3_f32 v70, v70, v71, v72
	v_mul_f32_e32 v71, 0x3e000000, v54
	v_mul_f32_e32 v72, 0x3e000000, v55
	v_max3_f32 v70, v70, v71, v72
	v_mul_f32_e32 v71, 0x3e000000, v56
	v_mul_f32_e32 v72, 0x3e000000, v57
	v_max3_f32 v70, v70, v71, v72
	v_mul_f32_e32 v71, 0x3e000000, v50
	v_mul_f32_e32 v72, 0x3e000000, v51
	v_max3_f32 v70, v70, v71, v72
	v_mul_f32_e32 v71, 0x3e000000, v52
	v_mul_f32_e32 v72, 0x3e000000, v53
	v_max3_f32 v70, v70, v71, v72
	v_mul_f32_e32 v71, 0x3e000000, v46
	v_mul_f32_e32 v72, 0x3e000000, v47
	v_max3_f32 v70, v70, v71, v72
	v_mul_f32_e32 v71, 0x3e000000, v48
	v_mul_f32_e32 v72, 0x3e000000, v49
	v_max3_f32 v70, v70, v71, v72
	v_mul_f32_e32 v71, 0x3e000000, v42
	v_mul_f32_e32 v72, 0x3e000000, v43
	v_max3_f32 v70, v70, v71, v72
	v_mul_f32_e32 v71, 0x3e000000, v44
	v_mul_f32_e32 v72, 0x3e000000, v45
	v_max3_f32 v70, v70, v71, v72
	v_mul_f32_e32 v71, 0x3e000000, v38
	v_mul_f32_e32 v72, 0x3e000000, v39
	v_max3_f32 v70, v70, v71, v72
	v_mul_f32_e32 v71, 0x3e000000, v40
	v_mul_f32_e32 v72, 0x3e000000, v41
	v_max3_f32 v70, v70, v71, v72
	v_mul_f32_e32 v71, 0x3e000000, v34
	v_mul_f32_e32 v72, 0x3e000000, v35
	v_max3_f32 v70, v70, v71, v72
	v_mul_f32_e32 v71, 0x3e000000, v36
	v_mul_f32_e32 v72, 0x3e000000, v37
	v_max3_f32 v70, v70, v71, v72
	v_mul_f32_e32 v71, 0x3e000000, v26
	v_mul_f32_e32 v72, 0x3e000000, v27
	v_max3_f32 v70, v70, v71, v72
	v_mul_f32_e32 v71, 0x3e000000, v28
	v_mul_f32_e32 v72, 0x3e000000, v29
	v_max3_f32 v70, v70, v71, v72
	v_mul_f32_e32 v71, 0x3e000000, v22
	v_mul_f32_e32 v72, 0x3e000000, v23
	v_max3_f32 v70, v70, v71, v72
	v_mul_f32_e32 v71, 0x3e000000, v24
	v_mul_f32_e32 v72, 0x3e000000, v25
	v_max3_f32 v70, v70, v71, v72
	v_mul_f32_e32 v71, 0x3e000000, v18
	v_mul_f32_e32 v72, 0x3e000000, v19
	v_max3_f32 v70, v70, v71, v72
	v_mul_f32_e32 v71, 0x3e000000, v20
	v_mul_f32_e32 v72, 0x3e000000, v21
	v_max3_f32 v70, v70, v71, v72
	v_mul_f32_e32 v71, 0x3e000000, v14
	v_mul_f32_e32 v72, 0x3e000000, v15
	v_max3_f32 v70, v70, v71, v72
	v_mul_f32_e32 v71, 0x3e000000, v16
	v_mul_f32_e32 v72, 0x3e000000, v17
	v_max3_f32 v70, v70, v71, v72
	v_mul_f32_e32 v71, 0x3e000000, v8
	v_mul_f32_e32 v72, 0x3e000000, v9
	v_max3_f32 v70, v70, v71, v72
	v_mul_f32_e32 v71, 0x3e000000, v10
	v_mul_f32_e32 v72, 0x3e000000, v11
	v_max3_f32 v70, v70, v71, v72
	v_mul_f32_e32 v71, 0x3e000000, v4
	v_mul_f32_e32 v72, 0x3e000000, v5
	v_max3_f32 v70, v70, v71, v72
	v_mul_f32_e32 v71, 0x3e000000, v6
	v_mul_f32_e32 v72, 0x3e000000, v7
	v_max3_f32 v70, v70, v71, v72
	v_mul_f32_e32 v71, 0x3e000000, v0
	v_mul_f32_e32 v72, 0x3e000000, v1
	v_max3_f32 v70, v70, v71, v72
	v_mul_f32_e32 v71, 0x3e000000, v2
	v_mul_f32_e32 v72, 0x3e000000, v3
	v_max3_f32 v70, v70, v71, v72
	ds_bpermute_b32 v71, v33, v70
	v_min3_f32 v224, v66, v67, v68
	v_min3_f32 v224, v224, v69, v62
	v_min3_f32 v224, v224, v63, v64
	v_min3_f32 v224, v224, v65, v58
	v_min3_f32 v224, v224, v59, v60
	v_min3_f32 v224, v224, v61, v54
	v_min3_f32 v224, v224, v55, v56
	v_min3_f32 v224, v224, v57, v50
	v_min3_f32 v224, v224, v51, v52
	v_min3_f32 v224, v224, v53, v46
	v_min3_f32 v224, v224, v47, v48
	v_min3_f32 v224, v224, v49, v42
	v_min3_f32 v224, v224, v43, v44
	v_min3_f32 v224, v224, v45, v38
	v_min3_f32 v224, v224, v39, v40
	v_min3_f32 v224, v224, v41, v34
	s_waitcnt lgkmcnt(0)
	v_max_f32_e32 v71, v71, v71
	v_max_f32_e32 v70, v70, v71
	ds_bpermute_b32 v71, v96, v70
	v_min3_f32 v224, v224, v35, v36
	v_min3_f32 v224, v224, v37, v26
	v_min3_f32 v224, v224, v27, v28
	v_min3_f32 v224, v224, v29, v22
	v_min3_f32 v224, v224, v23, v24
	v_min3_f32 v224, v224, v25, v18
	v_min3_f32 v224, v224, v19, v20
	v_min3_f32 v224, v224, v21, v14
	v_min3_f32 v224, v224, v15, v16
	v_min3_f32 v224, v224, v17, v8
	v_min3_f32 v224, v224, v9, v10
	v_min3_f32 v224, v224, v11, v4
	v_min3_f32 v224, v224, v5, v6
	v_min3_f32 v224, v224, v7, v0
	v_min3_f32 v224, v224, v1, v2
	v_min_f32_e32 v224, v224, v3
	s_waitcnt lgkmcnt(0)
	v_max_f32_e32 v71, v71, v71
	v_max_f32_e32 v72, v70, v71
	v_fma_f32 v225, v224, s85, -v72
	v_mul_f32_e32 v225, 0x3fb8aa3b, v225
	v_cmp_gt_f32_e32 vcc, s86, v225
	s_cbranch_vccnz .Lma_slow_gla
; DI unsigned cvt_pk_bf16(float lo, float hi) { const f32x2_t v = {lo, hi}; const bf16v2_t b = __builtin_convertvector(v, bf16v2_t); return __builtin_bit_cast(unsigned, b); }
; DI f32x4 mfma16(bf16x8 a, bf16x8 b, f32x4 c) { return __builtin_amdgcn_mfma_f32_16x16x32_bf16(a, b, c, 0, 0, 0); }
; DI void mem_attn_item(ldsp lds, const bf16_t* proj, int ldp, int qmcol, int gatecol, const bf16_t* kv, bf16_t* branch, int b0, int item, int tid, int wid, int lane, const bool stage = true) {
;     ...
;     float den = 0.f;
; #pragma unroll
;     for (int t = 0; t < 16; ++t)
; #pragma unroll
;         for (int j = 0; j < 4; ++j) { const float pv = exp2f((sacc[t][j] - mx) * 1.4426950408889634f); sacc[t][j] = pv; den += pv; }
;     den += __shfl_xor(den, 16); den += __shfl_xor(den, 32);
;     f32x4 oacc[4];
; #pragma unroll
;     for (int dt = 0; dt < 4; ++dt) oacc[dt] = (f32x4){0.f, 0.f, 0.f, 0.f};
; #pragma unroll
;     for (int kt = 0; kt < 8; ++kt) {
;         u32x4 pw; pw.x = cvt_pk_bf16(sacc[2 * kt][0], sacc[2 * kt][1]); pw.y = cvt_pk_bf16(sacc[2 * kt][2], sacc[2 * kt][3]);
;         pw.z = cvt_pk_bf16(sacc[2 * kt + 1][0], sacc[2 * kt + 1][1]); pw.w = cvt_pk_bf16(sacc[2 * kt + 1][2], sacc[2 * kt + 1][3]);
;         const bf16x8 pf = __builtin_bit_cast(bf16x8, pw);
;         const ldsp va = Vb + (32 * kt + quad * 4 + (li >> 2)) * KS + (li & 3) * 8;
; #pragma unroll
;         for (int dt = 0; dt < 4; ++dt) oacc[dt] = mfma16(lds_tr8(va + dt * 32, va + 16 * KS + dt * 32), pf, oacc[dt]);
;     }
	v_fma_f32 v66, v66, s85, -v72
	v_mul_f32_e32 v70, 0x3fb8aa3b, v66
	v_fma_f32 v67, v67, s85, -v72
	v_fma_f32 v68, v68, s85, -v72
	v_exp_f32_e32 v66, v70
	v_mul_f32_e32 v71, 0x3fb8aa3b, v68
	v_fma_f32 v69, v69, s85, -v72
	v_mul_f32_e32 v70, 0x3fb8aa3b, v67
	v_fma_f32 v62, v62, s85, -v72
	v_fma_f32 v63, v63, s85, -v72
	v_exp_f32_e32 v67, v70
	v_fma_f32 v58, v58, s85, -v72
	v_exp_f32_e32 v68, v71
	v_add_f32_e32 v70, v66, v67
	v_fma_f32 v59, v59, s85, -v72
	v_mul_f32_e32 v71, 0x3fb8aa3b, v69
	v_add_f32_e32 v70, v68, v70
	v_fma_f32 v60, v60, s85, -v72
	v_exp_f32_e32 v69, v71
	v_fma_f32 v61, v61, s85, -v72
	v_fma_f32 v54, v54, s85, -v72
	v_add_f32_e32 v71, v69, v70
	v_mul_f32_e32 v70, 0x3fb8aa3b, v62
	v_fma_f32 v55, v55, s85, -v72
	v_fma_f32 v56, v56, s85, -v72
	v_exp_f32_e32 v62, v70
	v_fma_f32 v57, v57, s85, -v72
	v_fma_f32 v50, v50, s85, -v72
	v_mov_b32_e32 v70, v62
	v_add_f32_e32 v62, v70, v71
	v_mul_f32_e32 v71, 0x3fb8aa3b, v63
	v_fma_f32 v51, v51, s85, -v72
	v_fma_f32 v52, v52, s85, -v72
	v_exp_f32_e32 v63, v71
	v_fma_f32 v53, v53, s85, -v72
	v_fma_f32 v46, v46, s85, -v72
	v_mov_b32_e32 v71, v63
	v_fma_f32 v63, v64, s85, -v72
	v_mul_f32_e32 v64, 0x3fb8aa3b, v63
	v_fma_f32 v47, v47, s85, -v72
	v_fma_f32 v48, v48, s85, -v72
	v_exp_f32_e32 v63, v64
	v_fma_f32 v49, v49, s85, -v72
	v_fma_f32 v42, v42, s85, -v72
	v_mov_b32_e32 v64, v63
	v_fma_f32 v63, v65, s85, -v72
	v_mul_f32_e32 v65, 0x3fb8aa3b, v63
	v_fma_f32 v43, v43, s85, -v72
	v_fma_f32 v44, v44, s85, -v72
	v_exp_f32_e32 v63, v65
	v_fma_f32 v45, v45, s85, -v72
	v_fma_f32 v38, v38, s85, -v72
	v_mov_b32_e32 v65, v63
	v_mul_f32_e32 v63, 0x3fb8aa3b, v58
	v_fma_f32 v39, v39, s85, -v72
	v_fma_f32 v40, v40, s85, -v72
	v_exp_f32_e32 v58, v63
	v_fma_f32 v41, v41, s85, -v72
	v_fma_f32 v34, v34, s85, -v72
	v_mul_f32_e32 v63, 0x3fb8aa3b, v59
	v_fma_f32 v35, v35, s85, -v72
	v_fma_f32 v36, v36, s85, -v72
	v_exp_f32_e32 v59, v63
	v_add_f32_e32 v62, v71, v62
	v_add_f32_e32 v62, v64, v62
	v_mul_f32_e32 v63, 0x3fb8aa3b, v60
	v_add_f32_e32 v62, v65, v62
	v_add_f32_e32 v62, v58, v62
	v_exp_f32_e32 v60, v63
	v_add_f32_e32 v62, v59, v62
	v_fma_f32 v37, v37, s85, -v72
	v_mul_f32_e32 v63, 0x3fb8aa3b, v61
	v_add_f32_e32 v62, v60, v62
	v_fma_f32 v26, v26, s85, -v72
	v_exp_f32_e32 v61, v63
	v_fma_f32 v27, v27, s85, -v72
	v_fma_f32 v28, v28, s85, -v72
	v_mul_f32_e32 v63, 0x3fb8aa3b, v54
	v_add_f32_e32 v62, v61, v62
	v_fma_f32 v29, v29, s85, -v72
	v_exp_f32_e32 v54, v63
	v_fma_f32 v22, v22, s85, -v72
	v_fma_f32 v23, v23, s85, -v72
	v_mul_f32_e32 v63, 0x3fb8aa3b, v55
	v_add_f32_e32 v62, v54, v62
	v_fma_f32 v24, v24, s85, -v72
	v_exp_f32_e32 v55, v63
	v_fma_f32 v25, v25, s85, -v72
	v_fma_f32 v18, v18, s85, -v72
	v_mul_f32_e32 v63, 0x3fb8aa3b, v56
	v_add_f32_e32 v62, v55, v62
	v_fma_f32 v19, v19, s85, -v72
	v_exp_f32_e32 v56, v63
	v_fma_f32 v14, v14, s85, -v72
	v_fma_f32 v15, v15, s85, -v72
	v_mul_f32_e32 v63, 0x3fb8aa3b, v57
	v_add_f32_e32 v62, v56, v62
	v_fma_f32 v16, v16, s85, -v72
	v_exp_f32_e32 v57, v63
	v_fma_f32 v17, v17, s85, -v72
	v_fma_f32 v8, v8, s85, -v72
	v_mul_f32_e32 v63, 0x3fb8aa3b, v50
	v_add_f32_e32 v62, v57, v62
	v_fma_f32 v9, v9, s85, -v72
	v_exp_f32_e32 v50, v63
	v_fma_f32 v10, v10, s85, -v72
	v_fma_f32 v11, v11, s85, -v72
	v_mul_f32_e32 v63, 0x3fb8aa3b, v51
	v_add_f32_e32 v62, v50, v62
	v_fma_f32 v4, v4, s85, -v72
	v_exp_f32_e32 v51, v63
	v_fma_f32 v5, v5, s85, -v72
	v_fma_f32 v6, v6, s85, -v72
	v_mul_f32_e32 v63, 0x3fb8aa3b, v52
	v_add_f32_e32 v62, v51, v62
	v_fma_f32 v7, v7, s85, -v72
	v_exp_f32_e32 v52, v63
	v_fma_f32 v0, v0, s85, -v72
	v_fma_f32 v1, v1, s85, -v72
	v_mul_f32_e32 v63, 0x3fb8aa3b, v53
	v_add_f32_e32 v62, v52, v62
	v_fma_f32 v2, v2, s85, -v72
	v_exp_f32_e32 v53, v63
	v_fma_f32 v3, v3, s85, -v72
	v_cvt_pk_bf16_f32 v66, v66, v67
	v_mul_f32_e32 v63, 0x3fb8aa3b, v46
	v_add_f32_e32 v62, v53, v62
	v_cvt_pk_bf16_f32 v67, v68, v69
	v_exp_f32_e32 v46, v63
	v_cvt_pk_bf16_f32 v68, v70, v71
	v_cvt_pk_bf16_f32 v69, v64, v65
	v_mul_f32_e32 v63, 0x3fb8aa3b, v47
	v_add_f32_e32 v62, v46, v62
	v_cvt_pk_bf16_f32 v58, v58, v59
	v_exp_f32_e32 v47, v63
	v_cvt_pk_bf16_f32 v59, v60, v61
	v_cvt_pk_bf16_f32 v60, v54, v55
	v_mul_f32_e32 v63, 0x3fb8aa3b, v48
	v_add_f32_e32 v62, v47, v62
	v_cvt_pk_bf16_f32 v61, v56, v57
	v_exp_f32_e32 v48, v63
	v_cvt_pk_bf16_f32 v50, v50, v51
	v_cvt_pk_bf16_f32 v51, v52, v53
	v_mul_f32_e32 v63, 0x3fb8aa3b, v49
	v_add_f32_e32 v62, v48, v62
	v_cvt_pk_bf16_f32 v52, v46, v47
	v_exp_f32_e32 v49, v63
	v_mul_f32_e32 v63, 0x3fb8aa3b, v42
	v_add_f32_e32 v62, v49, v62
	v_cvt_pk_bf16_f32 v53, v48, v49
	v_exp_f32_e32 v42, v63
	v_mul_f32_e32 v63, 0x3fb8aa3b, v43
	v_add_f32_e32 v62, v42, v62
	s_nop 0
	v_exp_f32_e32 v43, v63
	v_mul_f32_e32 v63, 0x3fb8aa3b, v44
	v_add_f32_e32 v62, v43, v62
	v_cvt_pk_bf16_f32 v42, v42, v43
	v_exp_f32_e32 v44, v63
	v_mul_f32_e32 v63, 0x3fb8aa3b, v45
	v_add_f32_e32 v62, v44, v62
	s_nop 0
	v_exp_f32_e32 v45, v63
	v_mul_f32_e32 v63, 0x3fb8aa3b, v38
	v_add_f32_e32 v62, v45, v62
	v_cvt_pk_bf16_f32 v43, v44, v45
	v_exp_f32_e32 v38, v63
	v_mul_f32_e32 v63, 0x3fb8aa3b, v39
	v_add_f32_e32 v62, v38, v62
	s_nop 0
	v_exp_f32_e32 v39, v63
	v_mul_f32_e32 v63, 0x3fb8aa3b, v40
	v_add_f32_e32 v62, v39, v62
	v_cvt_pk_bf16_f32 v44, v38, v39
	v_exp_f32_e32 v40, v63
	v_mul_f32_e32 v63, 0x3fb8aa3b, v41
	v_add_f32_e32 v62, v40, v62
	s_nop 0
	v_exp_f32_e32 v41, v63
	v_mul_f32_e32 v63, 0x3fb8aa3b, v34
	v_add_f32_e32 v62, v41, v62
	v_cvt_pk_bf16_f32 v45, v40, v41
	v_exp_f32_e32 v34, v63
	v_mul_f32_e32 v63, 0x3fb8aa3b, v35
	v_add_f32_e32 v62, v34, v62
	s_nop 0
	v_exp_f32_e32 v35, v63
	v_mul_f32_e32 v63, 0x3fb8aa3b, v36
	v_add_f32_e32 v62, v35, v62
	v_cvt_pk_bf16_f32 v34, v34, v35
; DI unsigned cvt_pk_bf16(float lo, float hi) { const f32x2_t v = {lo, hi}; const bf16v2_t b = __builtin_convertvector(v, bf16v2_t); return __builtin_bit_cast(unsigned, b); }
; DI f32x4 mfma16(bf16x8 a, bf16x8 b, f32x4 c) { return __builtin_amdgcn_mfma_f32_16x16x32_bf16(a, b, c, 0, 0, 0); }
; DI void mem_attn_item(ldsp lds, const bf16_t* proj, int ldp, int qmcol, int gatecol, const bf16_t* kv, bf16_t* branch, int b0, int item, int tid, int wid, int lane, const bool stage = true) {
;     ...
;     float den = 0.f;
; #pragma unroll
;     for (int t = 0; t < 16; ++t)
; #pragma unroll
;         for (int j = 0; j < 4; ++j) { const float pv = exp2f((sacc[t][j] - mx) * 1.4426950408889634f); sacc[t][j] = pv; den += pv; }
;     den += __shfl_xor(den, 16); den += __shfl_xor(den, 32);
;     f32x4 oacc[4];
; #pragma unroll
;     for (int dt = 0; dt < 4; ++dt) oacc[dt] = (f32x4){0.f, 0.f, 0.f, 0.f};
; #pragma unroll
;     for (int kt = 0; kt < 8; ++kt) {
;         u32x4 pw; pw.x = cvt_pk_bf16(sacc[2 * kt][0], sacc[2 * kt][1]); pw.y = cvt_pk_bf16(sacc[2 * kt][2], sacc[2 * kt][3]);
;         pw.z = cvt_pk_bf16(sacc[2 * kt + 1][0], sacc[2 * kt + 1][1]); pw.w = cvt_pk_bf16(sacc[2 * kt + 1][2], sacc[2 * kt + 1][3]);
;         const bf16x8 pf = __builtin_bit_cast(bf16x8, pw);
;         const ldsp va = Vb + (32 * kt + quad * 4 + (li >> 2)) * KS + (li & 3) * 8;
; #pragma unroll
;         for (int dt = 0; dt < 4; ++dt) oacc[dt] = mfma16(lds_tr8(va + dt * 32, va + 16 * KS + dt * 32), pf, oacc[dt]);
;     }
	v_exp_f32_e32 v36, v63
	v_mul_f32_e32 v63, 0x3fb8aa3b, v37
	v_add_f32_e32 v62, v36, v62
	s_nop 0
	v_exp_f32_e32 v37, v63
	v_mul_f32_e32 v63, 0x3fb8aa3b, v26
	v_add_f32_e32 v62, v37, v62
	v_cvt_pk_bf16_f32 v35, v36, v37
	v_exp_f32_e32 v26, v63
	v_mul_f32_e32 v63, 0x3fb8aa3b, v27
	v_add_f32_e32 v62, v26, v62
	s_nop 0
	v_exp_f32_e32 v27, v63
	s_nop 0
	v_add_f32_e32 v63, v27, v62
	v_mul_f32_e32 v62, 0x3fb8aa3b, v28
	v_cvt_pk_bf16_f32 v36, v26, v27
	s_nop 0
	v_exp_f32_e32 v28, v62
	s_nop 0
	v_mov_b32_e32 v62, v28
	v_add_f32_e32 v28, v62, v63
	v_mul_f32_e32 v63, 0x3fb8aa3b, v29
	s_nop 1
	v_exp_f32_e32 v29, v63
	s_nop 0
	v_mov_b32_e32 v63, v29
	v_mul_f32_e32 v29, 0x3fb8aa3b, v22
	v_add_f32_e32 v28, v63, v28
	v_cvt_pk_bf16_f32 v37, v62, v63
	v_exp_f32_e32 v22, v29
	v_mul_f32_e32 v29, 0x3fb8aa3b, v23
	v_add_f32_e32 v28, v22, v28
	s_nop 0
	v_exp_f32_e32 v23, v29
	v_mul_f32_e32 v29, 0x3fb8aa3b, v24
	v_add_f32_e32 v28, v23, v28
	v_cvt_pk_bf16_f32 v22, v22, v23
	v_exp_f32_e32 v24, v29
	v_mul_f32_e32 v29, 0x3fb8aa3b, v25
	v_add_f32_e32 v28, v24, v28
	s_nop 0
	v_exp_f32_e32 v25, v29
	s_nop 0
	v_add_f32_e32 v29, v25, v28
	v_mul_f32_e32 v28, 0x3fb8aa3b, v18
	v_cvt_pk_bf16_f32 v23, v24, v25
	s_nop 0
	v_exp_f32_e32 v18, v28
	s_nop 0
	v_mov_b32_e32 v28, v18
	v_add_f32_e32 v18, v28, v29
	v_mul_f32_e32 v29, 0x3fb8aa3b, v19
	s_nop 1
	v_exp_f32_e32 v19, v29
	s_nop 0
	v_mov_b32_e32 v29, v19
	v_fma_f32 v19, v20, s85, -v72
	v_mul_f32_e32 v20, 0x3fb8aa3b, v19
	v_add_f32_e32 v18, v29, v18
	v_cvt_pk_bf16_f32 v24, v28, v29
	v_exp_f32_e32 v19, v20
	s_nop 0
	v_mov_b32_e32 v20, v19
	v_fma_f32 v19, v21, s85, -v72
	v_mul_f32_e32 v21, 0x3fb8aa3b, v19
	ds_read_b64_tr_b16 v[72:73], v97 offset:39168
	ds_read_b64_tr_b16 v[70:71], v97 offset:36864
	ds_read_b64_tr_b16 v[108:109], v97 offset:36896
	v_exp_f32_e32 v19, v21
	ds_read_b64_tr_b16 v[110:111], v97 offset:39200
	ds_read_b64_tr_b16 v[112:113], v97 offset:36928
	ds_read_b64_tr_b16 v[114:115], v97 offset:39232
	v_mov_b32_e32 v21, v19
	v_mul_f32_e32 v19, 0x3fb8aa3b, v14
	ds_read_b64_tr_b16 v[116:117], v97 offset:36960
	ds_read_b64_tr_b16 v[118:119], v97 offset:39264
	v_exp_f32_e32 v14, v19
	ds_read_b64_tr_b16 v[54:55], v97 offset:41472
	ds_read_b64_tr_b16 v[56:57], v97 offset:43776
	s_waitcnt lgkmcnt(8)
	v_mfma_f32_16x16x32_bf16 v[70:73], v[70:73], v[66:69], 0
	v_mul_f32_e32 v19, 0x3fb8aa3b, v15
	s_waitcnt lgkmcnt(6)
	v_mfma_f32_16x16x32_bf16 v[108:111], v[108:111], v[66:69], 0
	v_cvt_pk_bf16_f32 v25, v20, v21
	v_exp_f32_e32 v15, v19
	s_waitcnt lgkmcnt(4)
	v_mfma_f32_16x16x32_bf16 v[112:115], v[112:115], v[66:69], 0
	v_add_f32_e32 v18, v20, v18
	v_mul_f32_e32 v19, 0x3fb8aa3b, v16
	s_waitcnt lgkmcnt(2)
	v_mfma_f32_16x16x32_bf16 v[64:67], v[116:119], v[66:69], 0
	v_add_f32_e32 v18, v21, v18
	v_exp_f32_e32 v16, v19
	s_waitcnt lgkmcnt(0)
	v_mfma_f32_16x16x32_bf16 v[54:57], v[54:57], v[58:61], v[70:73]
	ds_read_b64_tr_b16 v[68:69], v97 offset:41504
	s_nop 1
	ds_read_b64_tr_b16 v[70:71], v97 offset:43808
	v_mul_f32_e32 v19, 0x3fb8aa3b, v17
	s_waitcnt lgkmcnt(0)
	v_mfma_f32_16x16x32_bf16 v[68:71], v[68:71], v[58:61], v[108:111]
	v_exp_f32_e32 v17, v19
	s_nop 1
	ds_read_b64_tr_b16 v[108:109], v97 offset:41536
	ds_read_b64_tr_b16 v[110:111], v97 offset:43840
	s_waitcnt lgkmcnt(0)
	v_mfma_f32_16x16x32_bf16 v[108:111], v[108:111], v[58:61], v[112:115]
	v_mul_f32_e32 v19, 0x3fb8aa3b, v8
	s_nop 1
	ds_read_b64_tr_b16 v[112:113], v97 offset:41568
	ds_read_b64_tr_b16 v[114:115], v97 offset:43872
	v_exp_f32_e32 v8, v19
	ds_read_b64_tr_b16 v[46:47], v97 offset:46080
	ds_read_b64_tr_b16 v[48:49], v97 offset:48384
	s_waitcnt lgkmcnt(0)
	v_mfma_f32_16x16x32_bf16 v[46:49], v[46:49], v[50:53], v[54:57]
	v_mul_f32_e32 v19, 0x3fb8aa3b, v9
	s_nop 1
	ds_read_b64_tr_b16 v[54:55], v97 offset:46112
	ds_read_b64_tr_b16 v[56:57], v97 offset:48416
	v_exp_f32_e32 v9, v19
	v_mfma_f32_16x16x32_bf16 v[58:61], v[112:115], v[58:61], v[64:67]
	s_nop 2
	ds_read_b64_tr_b16 v[64:65], v97 offset:46144
	ds_read_b64_tr_b16 v[66:67], v97 offset:48448
	v_mul_f32_e32 v19, 0x3fb8aa3b, v10
	s_waitcnt lgkmcnt(2)
	v_mfma_f32_16x16x32_bf16 v[54:57], v[54:57], v[50:53], v[68:71]
	s_nop 2
	ds_read_b64_tr_b16 v[68:69], v97 offset:46176
	ds_read_b64_tr_b16 v[70:71], v97 offset:48480
	v_exp_f32_e32 v10, v19
	ds_read_b64_tr_b16 v[38:39], v97 offset:50688
	ds_read_b64_tr_b16 v[40:41], v97 offset:52992
	s_waitcnt lgkmcnt(0)
	v_mfma_f32_16x16x32_bf16 v[38:41], v[38:41], v[42:45], v[46:49]
	v_mul_f32_e32 v19, 0x3fb8aa3b, v11
	s_nop 1
	ds_read_b64_tr_b16 v[46:47], v97 offset:50720
	ds_read_b64_tr_b16 v[48:49], v97 offset:53024
	v_exp_f32_e32 v11, v19
	v_mfma_f32_16x16x32_bf16 v[64:67], v[64:67], v[50:53], v[108:111]
	v_add_f32_e32 v18, v14, v18
	v_mul_f32_e32 v19, 0x3fb8aa3b, v4
	v_mfma_f32_16x16x32_bf16 v[50:53], v[68:71], v[50:53], v[58:61]
	v_add_f32_e32 v18, v15, v18
	v_exp_f32_e32 v4, v19
	s_waitcnt lgkmcnt(0)
	v_mfma_f32_16x16x32_bf16 v[46:49], v[46:49], v[42:45], v[54:57]
	s_nop 2
	ds_read_b64_tr_b16 v[54:55], v97 offset:50752
	ds_read_b64_tr_b16 v[56:57], v97 offset:53056
	v_mul_f32_e32 v19, 0x3fb8aa3b, v5
	ds_read_b64_tr_b16 v[58:59], v97 offset:50784
	ds_read_b64_tr_b16 v[60:61], v97 offset:53088
	v_exp_f32_e32 v5, v19
	s_waitcnt lgkmcnt(2)
	v_mfma_f32_16x16x32_bf16 v[54:57], v[54:57], v[42:45], v[64:67]
	v_add_f32_e32 v18, v16, v18
	v_mul_f32_e32 v19, 0x3fb8aa3b, v6
	s_waitcnt lgkmcnt(0)
	v_mfma_f32_16x16x32_bf16 v[42:45], v[58:61], v[42:45], v[50:53]
	s_nop 2
	ds_read_b64_tr_b16 v[50:51], v97 offset:55296
	ds_read_b64_tr_b16 v[52:53], v97 offset:57600
	v_exp_f32_e32 v6, v19
	s_waitcnt lgkmcnt(0)
; DI unsigned cvt_pk_bf16(float lo, float hi) { const f32x2_t v = {lo, hi}; const bf16v2_t b = __builtin_convertvector(v, bf16v2_t); return __builtin_bit_cast(unsigned, b); }
; DI f32x4 mfma16(bf16x8 a, bf16x8 b, f32x4 c) { return __builtin_amdgcn_mfma_f32_16x16x32_bf16(a, b, c, 0, 0, 0); }
; DI void mem_attn_item(ldsp lds, const bf16_t* proj, int ldp, int qmcol, int gatecol, const bf16_t* kv, bf16_t* branch, int b0, int item, int tid, int wid, int lane, const bool stage = true) {
;     ...
;     float den = 0.f;
; #pragma unroll
;     for (int t = 0; t < 16; ++t)
; #pragma unroll
;         for (int j = 0; j < 4; ++j) { const float pv = exp2f((sacc[t][j] - mx) * 1.4426950408889634f); sacc[t][j] = pv; den += pv; }
;     den += __shfl_xor(den, 16); den += __shfl_xor(den, 32);
;     f32x4 oacc[4];
; #pragma unroll
;     for (int dt = 0; dt < 4; ++dt) oacc[dt] = (f32x4){0.f, 0.f, 0.f, 0.f};
; #pragma unroll
;     for (int kt = 0; kt < 8; ++kt) {
;         u32x4 pw; pw.x = cvt_pk_bf16(sacc[2 * kt][0], sacc[2 * kt][1]); pw.y = cvt_pk_bf16(sacc[2 * kt][2], sacc[2 * kt][3]);
;         pw.z = cvt_pk_bf16(sacc[2 * kt + 1][0], sacc[2 * kt + 1][1]); pw.w = cvt_pk_bf16(sacc[2 * kt + 1][2], sacc[2 * kt + 1][3]);
;         const bf16x8 pf = __builtin_bit_cast(bf16x8, pw);
;         const ldsp va = Vb + (32 * kt + quad * 4 + (li >> 2)) * KS + (li & 3) * 8;
; #pragma unroll
;         for (int dt = 0; dt < 4; ++dt) oacc[dt] = mfma16(lds_tr8(va + dt * 32, va + 16 * KS + dt * 32), pf, oacc[dt]);
;     }
	v_mfma_f32_16x16x32_bf16 v[38:41], v[50:53], v[34:37], v[38:41]
	ds_read_b64_tr_b16 v[50:51], v97 offset:55328
	ds_read_b64_tr_b16 v[52:53], v97 offset:57632
	v_mul_f32_e32 v19, 0x3fb8aa3b, v7
	s_waitcnt lgkmcnt(0)
	v_mfma_f32_16x16x32_bf16 v[46:49], v[50:53], v[34:37], v[46:49]
	v_exp_f32_e32 v7, v19
	ds_read_b64_tr_b16 v[50:51], v97 offset:55360
	ds_read_b64_tr_b16 v[52:53], v97 offset:57664
	s_waitcnt lgkmcnt(0)
	v_mfma_f32_16x16x32_bf16 v[50:53], v[50:53], v[34:37], v[54:57]
	v_mul_f32_e32 v19, 0x3fb8aa3b, v0
	s_nop 1
	ds_read_b64_tr_b16 v[54:55], v97 offset:55392
	ds_read_b64_tr_b16 v[56:57], v97 offset:57696
	v_exp_f32_e32 v0, v19
	ds_read_b64_tr_b16 v[26:27], v97 offset:59904
	ds_read_b64_tr_b16 v[28:29], v97 offset:62208
	s_waitcnt lgkmcnt(0)
	v_mfma_f32_16x16x32_bf16 v[26:29], v[26:29], v[22:25], v[38:41]
	v_mul_f32_e32 v19, 0x3fb8aa3b, v1
	s_nop 1
	ds_read_b64_tr_b16 v[38:39], v97 offset:59936
	ds_read_b64_tr_b16 v[40:41], v97 offset:62240
	v_exp_f32_e32 v1, v19
	v_mfma_f32_16x16x32_bf16 v[34:37], v[54:57], v[34:37], v[42:45]
	s_nop 2
	ds_read_b64_tr_b16 v[42:43], v97 offset:59968
	ds_read_b64_tr_b16 v[44:45], v97 offset:62272
	v_add_f32_e32 v18, v17, v18
	s_waitcnt lgkmcnt(2)
	v_mfma_f32_16x16x32_bf16 v[38:41], v[38:41], v[22:25], v[46:49]
	s_nop 2
	ds_read_b64_tr_b16 v[46:47], v97 offset:60000
	ds_read_b64_tr_b16 v[48:49], v97 offset:62304
	v_add_f32_e32 v18, v8, v18
	v_mul_f32_e32 v19, 0x3fb8aa3b, v2
	v_add_f32_e32 v18, v9, v18
	v_add_f32_e32 v18, v10, v18
	v_add_f32_e32 v18, v11, v18
	s_waitcnt lgkmcnt(2)
	v_mfma_f32_16x16x32_bf16 v[42:45], v[42:45], v[22:25], v[50:53]
	v_cvt_pk_bf16_f32 v14, v14, v15
	v_cvt_pk_bf16_f32 v15, v16, v17
	v_cvt_pk_bf16_f32 v16, v8, v9
	s_waitcnt lgkmcnt(0)
	v_mfma_f32_16x16x32_bf16 v[20:23], v[46:49], v[22:25], v[34:37]
	v_cvt_pk_bf16_f32 v17, v10, v11
	ds_read_b64_tr_b16 v[8:9], v97 offset:64512
	ds_read_b64_tr_b16 v[10:11], v98 offset:29952
	ds_read_b64_tr_b16 v[36:37], v98 offset:29984
	ds_read_b64_tr_b16 v[34:35], v97 offset:64544
	v_exp_f32_e32 v2, v19
	v_add_f32_e32 v18, v4, v18
	v_add_f32_e32 v18, v5, v18
	v_mul_f32_e32 v19, 0x3fb8aa3b, v3
	v_add_f32_e32 v18, v6, v18
	s_waitcnt lgkmcnt(2)
	v_mfma_f32_16x16x32_bf16 v[8:11], v[8:11], v[14:17], v[26:29]
	v_exp_f32_e32 v3, v19
	s_waitcnt lgkmcnt(0)
	v_mfma_f32_16x16x32_bf16 v[24:27], v[34:37], v[14:17], v[38:41]
	ds_read_b64_tr_b16 v[34:35], v97 offset:64576
	ds_read_b64_tr_b16 v[36:37], v98 offset:30016
	s_nop 0
	ds_read_b64_tr_b16 v[38:39], v97 offset:64608
	ds_read_b64_tr_b16 v[40:41], v98 offset:30048
	v_add_f32_e32 v18, v7, v18
	v_add_f32_e32 v18, v0, v18
	v_add_f32_e32 v18, v1, v18
	v_add_f32_e32 v18, v2, v18
	s_branch .Lma_join_gla
.Lma_slow_gla:
	v_fma_f32 v66, v66, s85, -v72
	v_mul_f32_e32 v70, 0x3fb8aa3b, v66
	v_cmp_gt_f32_e32 vcc, s86, v70
	v_fma_f32 v67, v67, s85, -v72
	v_fma_f32 v68, v68, s85, -v72
	v_cndmask_b32_e32 v70, 0, v235, vcc
	v_fmac_f32_e32 v70, 0x3fb8aa3b, v66
	v_exp_f32_e32 v66, v70
	v_cndmask_b32_e32 v70, 0, v236, vcc
	v_mul_f32_e32 v71, 0x3fb8aa3b, v68
	v_fma_f32 v69, v69, s85, -v72
	v_ldexp_f32 v66, v66, v70
	v_mul_f32_e32 v70, 0x3fb8aa3b, v67
	v_cmp_gt_f32_e32 vcc, s86, v70
	v_fma_f32 v62, v62, s85, -v72
	v_fma_f32 v63, v63, s85, -v72
	v_cndmask_b32_e32 v70, 0, v235, vcc
	v_fmac_f32_e32 v70, 0x3fb8aa3b, v67
	v_exp_f32_e32 v67, v70
	v_cndmask_b32_e32 v70, 0, v236, vcc
	v_cmp_gt_f32_e32 vcc, s86, v71
	v_fma_f32 v58, v58, s85, -v72
	v_ldexp_f32 v67, v67, v70
	v_cndmask_b32_e32 v71, 0, v235, vcc
	v_fmac_f32_e32 v71, 0x3fb8aa3b, v68
	v_exp_f32_e32 v68, v71
	v_cndmask_b32_e32 v71, 0, v236, vcc
	v_add_f32_e32 v70, v66, v67
	v_fma_f32 v59, v59, s85, -v72
	v_ldexp_f32 v68, v68, v71
	v_mul_f32_e32 v71, 0x3fb8aa3b, v69
	v_cmp_gt_f32_e32 vcc, s86, v71
	v_add_f32_e32 v70, v68, v70
	v_fma_f32 v60, v60, s85, -v72
	v_cndmask_b32_e32 v71, 0, v235, vcc
	v_fmac_f32_e32 v71, 0x3fb8aa3b, v69
	v_exp_f32_e32 v69, v71
	v_cndmask_b32_e32 v71, 0, v236, vcc
	v_fma_f32 v61, v61, s85, -v72
	v_fma_f32 v54, v54, s85, -v72
	v_ldexp_f32 v69, v69, v71
	v_add_f32_e32 v71, v69, v70
	v_mul_f32_e32 v70, 0x3fb8aa3b, v62
	v_cmp_gt_f32_e32 vcc, s86, v70
	v_fma_f32 v55, v55, s85, -v72
	v_fma_f32 v56, v56, s85, -v72
	v_cndmask_b32_e32 v70, 0, v235, vcc
	v_fmac_f32_e32 v70, 0x3fb8aa3b, v62
	v_exp_f32_e32 v62, v70
	v_cndmask_b32_e32 v70, 0, v236, vcc
	v_fma_f32 v57, v57, s85, -v72
	v_fma_f32 v50, v50, s85, -v72
	v_ldexp_f32 v70, v62, v70
	v_add_f32_e32 v62, v70, v71
	v_mul_f32_e32 v71, 0x3fb8aa3b, v63
	v_cmp_gt_f32_e32 vcc, s86, v71
	v_fma_f32 v51, v51, s85, -v72
	v_fma_f32 v52, v52, s85, -v72
	v_cndmask_b32_e32 v71, 0, v235, vcc
	v_fmac_f32_e32 v71, 0x3fb8aa3b, v63
	v_exp_f32_e32 v63, v71
	v_cndmask_b32_e32 v71, 0, v236, vcc
	v_fma_f32 v53, v53, s85, -v72
	v_fma_f32 v46, v46, s85, -v72
	v_ldexp_f32 v71, v63, v71
	v_fma_f32 v63, v64, s85, -v72
	v_mul_f32_e32 v64, 0x3fb8aa3b, v63
	v_cmp_gt_f32_e32 vcc, s86, v64
	v_fma_f32 v47, v47, s85, -v72
	v_fma_f32 v48, v48, s85, -v72
	v_cndmask_b32_e32 v64, 0, v235, vcc
	v_fmac_f32_e32 v64, 0x3fb8aa3b, v63
	v_exp_f32_e32 v63, v64
	v_cndmask_b32_e32 v64, 0, v236, vcc
	v_fma_f32 v49, v49, s85, -v72
	v_fma_f32 v42, v42, s85, -v72
	v_ldexp_f32 v64, v63, v64
	v_fma_f32 v63, v65, s85, -v72
	v_mul_f32_e32 v65, 0x3fb8aa3b, v63
	v_cmp_gt_f32_e32 vcc, s86, v65
	v_fma_f32 v43, v43, s85, -v72
	v_fma_f32 v44, v44, s85, -v72
	v_cndmask_b32_e32 v65, 0, v235, vcc
	v_fmac_f32_e32 v65, 0x3fb8aa3b, v63
	v_exp_f32_e32 v63, v65
	v_cndmask_b32_e32 v65, 0, v236, vcc
	v_fma_f32 v45, v45, s85, -v72
	v_fma_f32 v38, v38, s85, -v72
	v_ldexp_f32 v65, v63, v65
	v_mul_f32_e32 v63, 0x3fb8aa3b, v58
	v_cmp_gt_f32_e32 vcc, s86, v63
	v_fma_f32 v39, v39, s85, -v72
; DI unsigned cvt_pk_bf16(float lo, float hi) { const f32x2_t v = {lo, hi}; const bf16v2_t b = __builtin_convertvector(v, bf16v2_t); return __builtin_bit_cast(unsigned, b); }
; DI f32x4 mfma16(bf16x8 a, bf16x8 b, f32x4 c) { return __builtin_amdgcn_mfma_f32_16x16x32_bf16(a, b, c, 0, 0, 0); }
; DI void mem_attn_item(ldsp lds, const bf16_t* proj, int ldp, int qmcol, int gatecol, const bf16_t* kv, bf16_t* branch, int b0, int item, int tid, int wid, int lane, const bool stage = true) {
;     ...
;     float den = 0.f;
; #pragma unroll
;     for (int t = 0; t < 16; ++t)
; #pragma unroll
;         for (int j = 0; j < 4; ++j) { const float pv = exp2f((sacc[t][j] - mx) * 1.4426950408889634f); sacc[t][j] = pv; den += pv; }
;     den += __shfl_xor(den, 16); den += __shfl_xor(den, 32);
;     f32x4 oacc[4];
; #pragma unroll
;     for (int dt = 0; dt < 4; ++dt) oacc[dt] = (f32x4){0.f, 0.f, 0.f, 0.f};
; #pragma unroll
;     for (int kt = 0; kt < 8; ++kt) {
;         u32x4 pw; pw.x = cvt_pk_bf16(sacc[2 * kt][0], sacc[2 * kt][1]); pw.y = cvt_pk_bf16(sacc[2 * kt][2], sacc[2 * kt][3]);
;         pw.z = cvt_pk_bf16(sacc[2 * kt + 1][0], sacc[2 * kt + 1][1]); pw.w = cvt_pk_bf16(sacc[2 * kt + 1][2], sacc[2 * kt + 1][3]);
;         const bf16x8 pf = __builtin_bit_cast(bf16x8, pw);
;         const ldsp va = Vb + (32 * kt + quad * 4 + (li >> 2)) * KS + (li & 3) * 8;
; #pragma unroll
;         for (int dt = 0; dt < 4; ++dt) oacc[dt] = mfma16(lds_tr8(va + dt * 32, va + 16 * KS + dt * 32), pf, oacc[dt]);
;     }
	v_fma_f32 v40, v40, s85, -v72
	v_cndmask_b32_e32 v63, 0, v235, vcc
	v_fmac_f32_e32 v63, 0x3fb8aa3b, v58
	v_exp_f32_e32 v58, v63
	v_cndmask_b32_e32 v63, 0, v236, vcc
	v_fma_f32 v41, v41, s85, -v72
	v_fma_f32 v34, v34, s85, -v72
	v_ldexp_f32 v58, v58, v63
	v_mul_f32_e32 v63, 0x3fb8aa3b, v59
	v_cmp_gt_f32_e32 vcc, s86, v63
	v_fma_f32 v35, v35, s85, -v72
	v_fma_f32 v36, v36, s85, -v72
	v_cndmask_b32_e32 v63, 0, v235, vcc
	v_fmac_f32_e32 v63, 0x3fb8aa3b, v59
	v_exp_f32_e32 v59, v63
	v_cndmask_b32_e32 v63, 0, v236, vcc
	v_add_f32_e32 v62, v71, v62
	v_add_f32_e32 v62, v64, v62
	v_ldexp_f32 v59, v59, v63
	v_mul_f32_e32 v63, 0x3fb8aa3b, v60
	v_cmp_gt_f32_e32 vcc, s86, v63
	v_add_f32_e32 v62, v65, v62
	v_add_f32_e32 v62, v58, v62
	v_cndmask_b32_e32 v63, 0, v235, vcc
	v_fmac_f32_e32 v63, 0x3fb8aa3b, v60
	v_exp_f32_e32 v60, v63
	v_cndmask_b32_e32 v63, 0, v236, vcc
	v_add_f32_e32 v62, v59, v62
	v_fma_f32 v37, v37, s85, -v72
	v_ldexp_f32 v60, v60, v63
	v_mul_f32_e32 v63, 0x3fb8aa3b, v61
	v_cmp_gt_f32_e32 vcc, s86, v63
	v_add_f32_e32 v62, v60, v62
	v_fma_f32 v26, v26, s85, -v72
	v_cndmask_b32_e32 v63, 0, v235, vcc
	v_fmac_f32_e32 v63, 0x3fb8aa3b, v61
	v_exp_f32_e32 v61, v63
	v_cndmask_b32_e32 v63, 0, v236, vcc
	v_fma_f32 v27, v27, s85, -v72
	v_fma_f32 v28, v28, s85, -v72
	v_ldexp_f32 v61, v61, v63
	v_mul_f32_e32 v63, 0x3fb8aa3b, v54
	v_cmp_gt_f32_e32 vcc, s86, v63
	v_add_f32_e32 v62, v61, v62
	v_fma_f32 v29, v29, s85, -v72
	v_cndmask_b32_e32 v63, 0, v235, vcc
	v_fmac_f32_e32 v63, 0x3fb8aa3b, v54
	v_exp_f32_e32 v54, v63
	v_cndmask_b32_e32 v63, 0, v236, vcc
	v_fma_f32 v22, v22, s85, -v72
	v_fma_f32 v23, v23, s85, -v72
	v_ldexp_f32 v54, v54, v63
	v_mul_f32_e32 v63, 0x3fb8aa3b, v55
	v_cmp_gt_f32_e32 vcc, s86, v63
	v_add_f32_e32 v62, v54, v62
	v_fma_f32 v24, v24, s85, -v72
	v_cndmask_b32_e32 v63, 0, v235, vcc
	v_fmac_f32_e32 v63, 0x3fb8aa3b, v55
	v_exp_f32_e32 v55, v63
	v_cndmask_b32_e32 v63, 0, v236, vcc
	v_fma_f32 v25, v25, s85, -v72
	v_fma_f32 v18, v18, s85, -v72
	v_ldexp_f32 v55, v55, v63
	v_mul_f32_e32 v63, 0x3fb8aa3b, v56
	v_cmp_gt_f32_e32 vcc, s86, v63
	v_add_f32_e32 v62, v55, v62
	v_fma_f32 v19, v19, s85, -v72
	v_cndmask_b32_e32 v63, 0, v235, vcc
	v_fmac_f32_e32 v63, 0x3fb8aa3b, v56
	v_exp_f32_e32 v56, v63
	v_cndmask_b32_e32 v63, 0, v236, vcc
	v_fma_f32 v14, v14, s85, -v72
	v_fma_f32 v15, v15, s85, -v72
	v_ldexp_f32 v56, v56, v63
	v_mul_f32_e32 v63, 0x3fb8aa3b, v57
	v_cmp_gt_f32_e32 vcc, s86, v63
	v_add_f32_e32 v62, v56, v62
	v_fma_f32 v16, v16, s85, -v72
	v_cndmask_b32_e32 v63, 0, v235, vcc
	v_fmac_f32_e32 v63, 0x3fb8aa3b, v57
	v_exp_f32_e32 v57, v63
	v_cndmask_b32_e32 v63, 0, v236, vcc
	v_fma_f32 v17, v17, s85, -v72
	v_fma_f32 v8, v8, s85, -v72
	v_ldexp_f32 v57, v57, v63
	v_mul_f32_e32 v63, 0x3fb8aa3b, v50
	v_cmp_gt_f32_e32 vcc, s86, v63
	v_add_f32_e32 v62, v57, v62
	v_fma_f32 v9, v9, s85, -v72
	v_cndmask_b32_e32 v63, 0, v235, vcc
	v_fmac_f32_e32 v63, 0x3fb8aa3b, v50
	v_exp_f32_e32 v50, v63
	v_cndmask_b32_e32 v63, 0, v236, vcc
	v_fma_f32 v10, v10, s85, -v72
	v_fma_f32 v11, v11, s85, -v72
	v_ldexp_f32 v50, v50, v63
	v_mul_f32_e32 v63, 0x3fb8aa3b, v51
	v_cmp_gt_f32_e32 vcc, s86, v63
	v_add_f32_e32 v62, v50, v62
	v_fma_f32 v4, v4, s85, -v72
	v_cndmask_b32_e32 v63, 0, v235, vcc
	v_fmac_f32_e32 v63, 0x3fb8aa3b, v51
	v_exp_f32_e32 v51, v63
	v_cndmask_b32_e32 v63, 0, v236, vcc
	v_fma_f32 v5, v5, s85, -v72
	v_fma_f32 v6, v6, s85, -v72
	v_ldexp_f32 v51, v51, v63
	v_mul_f32_e32 v63, 0x3fb8aa3b, v52
	v_cmp_gt_f32_e32 vcc, s86, v63
	v_add_f32_e32 v62, v51, v62
	v_fma_f32 v7, v7, s85, -v72
	v_cndmask_b32_e32 v63, 0, v235, vcc
	v_fmac_f32_e32 v63, 0x3fb8aa3b, v52
	v_exp_f32_e32 v52, v63
	v_cndmask_b32_e32 v63, 0, v236, vcc
	v_fma_f32 v0, v0, s85, -v72
	v_fma_f32 v1, v1, s85, -v72
	v_ldexp_f32 v52, v52, v63
	v_mul_f32_e32 v63, 0x3fb8aa3b, v53
	v_cmp_gt_f32_e32 vcc, s86, v63
	v_add_f32_e32 v62, v52, v62
	v_fma_f32 v2, v2, s85, -v72
	v_cndmask_b32_e32 v63, 0, v235, vcc
	v_fmac_f32_e32 v63, 0x3fb8aa3b, v53
	v_exp_f32_e32 v53, v63
	v_cndmask_b32_e32 v63, 0, v236, vcc
	v_fma_f32 v3, v3, s85, -v72
	v_cvt_pk_bf16_f32 v66, v66, v67
	v_ldexp_f32 v53, v53, v63
	v_mul_f32_e32 v63, 0x3fb8aa3b, v46
	v_cmp_gt_f32_e32 vcc, s86, v63
	v_add_f32_e32 v62, v53, v62
	v_cvt_pk_bf16_f32 v67, v68, v69
	v_cndmask_b32_e32 v63, 0, v235, vcc
	v_fmac_f32_e32 v63, 0x3fb8aa3b, v46
	v_exp_f32_e32 v46, v63
	v_cndmask_b32_e32 v63, 0, v236, vcc
	v_cvt_pk_bf16_f32 v68, v70, v71
	v_cvt_pk_bf16_f32 v69, v64, v65
	v_ldexp_f32 v46, v46, v63
	v_mul_f32_e32 v63, 0x3fb8aa3b, v47
	v_cmp_gt_f32_e32 vcc, s86, v63
	v_add_f32_e32 v62, v46, v62
	v_cvt_pk_bf16_f32 v58, v58, v59
	v_cndmask_b32_e32 v63, 0, v235, vcc
	v_fmac_f32_e32 v63, 0x3fb8aa3b, v47
	v_exp_f32_e32 v47, v63
	v_cndmask_b32_e32 v63, 0, v236, vcc
	v_cvt_pk_bf16_f32 v59, v60, v61
	v_cvt_pk_bf16_f32 v60, v54, v55
	v_ldexp_f32 v47, v47, v63
	v_mul_f32_e32 v63, 0x3fb8aa3b, v48
	v_cmp_gt_f32_e32 vcc, s86, v63
	v_add_f32_e32 v62, v47, v62
	v_cvt_pk_bf16_f32 v61, v56, v57
	v_cndmask_b32_e32 v63, 0, v235, vcc
	v_fmac_f32_e32 v63, 0x3fb8aa3b, v48
	v_exp_f32_e32 v48, v63
	v_cndmask_b32_e32 v63, 0, v236, vcc
	v_cvt_pk_bf16_f32 v50, v50, v51
	v_cvt_pk_bf16_f32 v51, v52, v53
	v_ldexp_f32 v48, v48, v63
	v_mul_f32_e32 v63, 0x3fb8aa3b, v49
	v_cmp_gt_f32_e32 vcc, s86, v63
	v_add_f32_e32 v62, v48, v62
	v_cvt_pk_bf16_f32 v52, v46, v47
	v_cndmask_b32_e32 v63, 0, v235, vcc
	v_fmac_f32_e32 v63, 0x3fb8aa3b, v49
	v_exp_f32_e32 v49, v63
	v_cndmask_b32_e32 v63, 0, v236, vcc
	v_ldexp_f32 v49, v49, v63
	v_mul_f32_e32 v63, 0x3fb8aa3b, v42
	v_cmp_gt_f32_e32 vcc, s86, v63
	v_add_f32_e32 v62, v49, v62
	v_cvt_pk_bf16_f32 v53, v48, v49
	v_cndmask_b32_e32 v63, 0, v235, vcc
; DI unsigned cvt_pk_bf16(float lo, float hi) { const f32x2_t v = {lo, hi}; const bf16v2_t b = __builtin_convertvector(v, bf16v2_t); return __builtin_bit_cast(unsigned, b); }
; DI f32x4 mfma16(bf16x8 a, bf16x8 b, f32x4 c) { return __builtin_amdgcn_mfma_f32_16x16x32_bf16(a, b, c, 0, 0, 0); }
; DI void mem_attn_item(ldsp lds, const bf16_t* proj, int ldp, int qmcol, int gatecol, const bf16_t* kv, bf16_t* branch, int b0, int item, int tid, int wid, int lane, const bool stage = true) {
;     ...
;     float den = 0.f;
; #pragma unroll
;     for (int t = 0; t < 16; ++t)
; #pragma unroll
;         for (int j = 0; j < 4; ++j) { const float pv = exp2f((sacc[t][j] - mx) * 1.4426950408889634f); sacc[t][j] = pv; den += pv; }
;     den += __shfl_xor(den, 16); den += __shfl_xor(den, 32);
;     f32x4 oacc[4];
; #pragma unroll
;     for (int dt = 0; dt < 4; ++dt) oacc[dt] = (f32x4){0.f, 0.f, 0.f, 0.f};
; #pragma unroll
;     for (int kt = 0; kt < 8; ++kt) {
;         u32x4 pw; pw.x = cvt_pk_bf16(sacc[2 * kt][0], sacc[2 * kt][1]); pw.y = cvt_pk_bf16(sacc[2 * kt][2], sacc[2 * kt][3]);
;         pw.z = cvt_pk_bf16(sacc[2 * kt + 1][0], sacc[2 * kt + 1][1]); pw.w = cvt_pk_bf16(sacc[2 * kt + 1][2], sacc[2 * kt + 1][3]);
;         const bf16x8 pf = __builtin_bit_cast(bf16x8, pw);
;         const ldsp va = Vb + (32 * kt + quad * 4 + (li >> 2)) * KS + (li & 3) * 8;
; #pragma unroll
;         for (int dt = 0; dt < 4; ++dt) oacc[dt] = mfma16(lds_tr8(va + dt * 32, va + 16 * KS + dt * 32), pf, oacc[dt]);
;     }
	v_fmac_f32_e32 v63, 0x3fb8aa3b, v42
	v_exp_f32_e32 v42, v63
	v_cndmask_b32_e32 v63, 0, v236, vcc
	v_ldexp_f32 v42, v42, v63
	v_mul_f32_e32 v63, 0x3fb8aa3b, v43
	v_cmp_gt_f32_e32 vcc, s86, v63
	v_add_f32_e32 v62, v42, v62
	s_nop 0
	v_cndmask_b32_e32 v63, 0, v235, vcc
	v_fmac_f32_e32 v63, 0x3fb8aa3b, v43
	v_exp_f32_e32 v43, v63
	v_cndmask_b32_e32 v63, 0, v236, vcc
	v_ldexp_f32 v43, v43, v63
	v_mul_f32_e32 v63, 0x3fb8aa3b, v44
	v_cmp_gt_f32_e32 vcc, s86, v63
	v_add_f32_e32 v62, v43, v62
	v_cvt_pk_bf16_f32 v42, v42, v43
	v_cndmask_b32_e32 v63, 0, v235, vcc
	v_fmac_f32_e32 v63, 0x3fb8aa3b, v44
	v_exp_f32_e32 v44, v63
	v_cndmask_b32_e32 v63, 0, v236, vcc
	v_ldexp_f32 v44, v44, v63
	v_mul_f32_e32 v63, 0x3fb8aa3b, v45
	v_cmp_gt_f32_e32 vcc, s86, v63
	v_add_f32_e32 v62, v44, v62
	s_nop 0
	v_cndmask_b32_e32 v63, 0, v235, vcc
	v_fmac_f32_e32 v63, 0x3fb8aa3b, v45
	v_exp_f32_e32 v45, v63
	v_cndmask_b32_e32 v63, 0, v236, vcc
	v_ldexp_f32 v45, v45, v63
	v_mul_f32_e32 v63, 0x3fb8aa3b, v38
	v_cmp_gt_f32_e32 vcc, s86, v63
	v_add_f32_e32 v62, v45, v62
	v_cvt_pk_bf16_f32 v43, v44, v45
	v_cndmask_b32_e32 v63, 0, v235, vcc
	v_fmac_f32_e32 v63, 0x3fb8aa3b, v38
	v_exp_f32_e32 v38, v63
	v_cndmask_b32_e32 v63, 0, v236, vcc
	v_ldexp_f32 v38, v38, v63
	v_mul_f32_e32 v63, 0x3fb8aa3b, v39
	v_cmp_gt_f32_e32 vcc, s86, v63
	v_add_f32_e32 v62, v38, v62
	s_nop 0
	v_cndmask_b32_e32 v63, 0, v235, vcc
	v_fmac_f32_e32 v63, 0x3fb8aa3b, v39
	v_exp_f32_e32 v39, v63
	v_cndmask_b32_e32 v63, 0, v236, vcc
	v_ldexp_f32 v39, v39, v63
	v_mul_f32_e32 v63, 0x3fb8aa3b, v40
	v_cmp_gt_f32_e32 vcc, s86, v63
	v_add_f32_e32 v62, v39, v62
	v_cvt_pk_bf16_f32 v44, v38, v39
	v_cndmask_b32_e32 v63, 0, v235, vcc
	v_fmac_f32_e32 v63, 0x3fb8aa3b, v40
	v_exp_f32_e32 v40, v63
	v_cndmask_b32_e32 v63, 0, v236, vcc
	v_ldexp_f32 v40, v40, v63
	v_mul_f32_e32 v63, 0x3fb8aa3b, v41
	v_cmp_gt_f32_e32 vcc, s86, v63
	v_add_f32_e32 v62, v40, v62
	s_nop 0
	v_cndmask_b32_e32 v63, 0, v235, vcc
	v_fmac_f32_e32 v63, 0x3fb8aa3b, v41
	v_exp_f32_e32 v41, v63
	v_cndmask_b32_e32 v63, 0, v236, vcc
	v_ldexp_f32 v41, v41, v63
	v_mul_f32_e32 v63, 0x3fb8aa3b, v34
	v_cmp_gt_f32_e32 vcc, s86, v63
	v_add_f32_e32 v62, v41, v62
	v_cvt_pk_bf16_f32 v45, v40, v41
	v_cndmask_b32_e32 v63, 0, v235, vcc
	v_fmac_f32_e32 v63, 0x3fb8aa3b, v34
	v_exp_f32_e32 v34, v63
	v_cndmask_b32_e32 v63, 0, v236, vcc
	v_ldexp_f32 v34, v34, v63
	v_mul_f32_e32 v63, 0x3fb8aa3b, v35
	v_cmp_gt_f32_e32 vcc, s86, v63
	v_add_f32_e32 v62, v34, v62
	s_nop 0
	v_cndmask_b32_e32 v63, 0, v235, vcc
	v_fmac_f32_e32 v63, 0x3fb8aa3b, v35
	v_exp_f32_e32 v35, v63
	v_cndmask_b32_e32 v63, 0, v236, vcc
	v_ldexp_f32 v35, v35, v63
	v_mul_f32_e32 v63, 0x3fb8aa3b, v36
	v_cmp_gt_f32_e32 vcc, s86, v63
	v_add_f32_e32 v62, v35, v62
	v_cvt_pk_bf16_f32 v34, v34, v35
	v_cndmask_b32_e32 v63, 0, v235, vcc
	v_fmac_f32_e32 v63, 0x3fb8aa3b, v36
	v_exp_f32_e32 v36, v63
	v_cndmask_b32_e32 v63, 0, v236, vcc
	v_ldexp_f32 v36, v36, v63
	v_mul_f32_e32 v63, 0x3fb8aa3b, v37
	v_cmp_gt_f32_e32 vcc, s86, v63
	v_add_f32_e32 v62, v36, v62
	s_nop 0
	v_cndmask_b32_e32 v63, 0, v235, vcc
	v_fmac_f32_e32 v63, 0x3fb8aa3b, v37
	v_exp_f32_e32 v37, v63
	v_cndmask_b32_e32 v63, 0, v236, vcc
	v_ldexp_f32 v37, v37, v63
	v_mul_f32_e32 v63, 0x3fb8aa3b, v26
	v_cmp_gt_f32_e32 vcc, s86, v63
	v_add_f32_e32 v62, v37, v62
	v_cvt_pk_bf16_f32 v35, v36, v37
	v_cndmask_b32_e32 v63, 0, v235, vcc
	v_fmac_f32_e32 v63, 0x3fb8aa3b, v26
	v_exp_f32_e32 v26, v63
	v_cndmask_b32_e32 v63, 0, v236, vcc
	v_ldexp_f32 v26, v26, v63
	v_mul_f32_e32 v63, 0x3fb8aa3b, v27
	v_cmp_gt_f32_e32 vcc, s86, v63
	v_add_f32_e32 v62, v26, v62
	s_nop 0
	v_cndmask_b32_e32 v63, 0, v235, vcc
	v_fmac_f32_e32 v63, 0x3fb8aa3b, v27
	v_exp_f32_e32 v27, v63
	v_cndmask_b32_e32 v63, 0, v236, vcc
	v_ldexp_f32 v27, v27, v63
	v_add_f32_e32 v63, v27, v62
	v_mul_f32_e32 v62, 0x3fb8aa3b, v28
	v_cmp_gt_f32_e32 vcc, s86, v62
	v_cvt_pk_bf16_f32 v36, v26, v27
	s_nop 0
	v_cndmask_b32_e32 v62, 0, v235, vcc
	v_fmac_f32_e32 v62, 0x3fb8aa3b, v28
	v_exp_f32_e32 v28, v62
	v_cndmask_b32_e32 v62, 0, v236, vcc
	v_ldexp_f32 v62, v28, v62
	v_add_f32_e32 v28, v62, v63
	v_mul_f32_e32 v63, 0x3fb8aa3b, v29
	v_cmp_gt_f32_e32 vcc, s86, v63
	s_nop 1
	v_cndmask_b32_e32 v63, 0, v235, vcc
	v_fmac_f32_e32 v63, 0x3fb8aa3b, v29
	v_exp_f32_e32 v29, v63
	v_cndmask_b32_e32 v63, 0, v236, vcc
	v_ldexp_f32 v63, v29, v63
	v_mul_f32_e32 v29, 0x3fb8aa3b, v22
	v_cmp_gt_f32_e32 vcc, s86, v29
	v_add_f32_e32 v28, v63, v28
	v_cvt_pk_bf16_f32 v37, v62, v63
	v_cndmask_b32_e32 v29, 0, v235, vcc
	v_fmac_f32_e32 v29, 0x3fb8aa3b, v22
	v_exp_f32_e32 v22, v29
	v_cndmask_b32_e32 v29, 0, v236, vcc
	v_ldexp_f32 v22, v22, v29
	v_mul_f32_e32 v29, 0x3fb8aa3b, v23
	v_cmp_gt_f32_e32 vcc, s86, v29
	v_add_f32_e32 v28, v22, v28
	s_nop 0
	v_cndmask_b32_e32 v29, 0, v235, vcc
	v_fmac_f32_e32 v29, 0x3fb8aa3b, v23
	v_exp_f32_e32 v23, v29
	v_cndmask_b32_e32 v29, 0, v236, vcc
	v_ldexp_f32 v23, v23, v29
	v_mul_f32_e32 v29, 0x3fb8aa3b, v24
	v_cmp_gt_f32_e32 vcc, s86, v29
	v_add_f32_e32 v28, v23, v28
	v_cvt_pk_bf16_f32 v22, v22, v23
	v_cndmask_b32_e32 v29, 0, v235, vcc
	v_fmac_f32_e32 v29, 0x3fb8aa3b, v24
	v_exp_f32_e32 v24, v29
	v_cndmask_b32_e32 v29, 0, v236, vcc
	v_ldexp_f32 v24, v24, v29
	v_mul_f32_e32 v29, 0x3fb8aa3b, v25
	v_cmp_gt_f32_e32 vcc, s86, v29
	v_add_f32_e32 v28, v24, v28
	s_nop 0
	v_cndmask_b32_e32 v29, 0, v235, vcc
	v_fmac_f32_e32 v29, 0x3fb8aa3b, v25
	v_exp_f32_e32 v25, v29
	v_cndmask_b32_e32 v29, 0, v236, vcc
	v_ldexp_f32 v25, v25, v29
	v_add_f32_e32 v29, v25, v28
	v_mul_f32_e32 v28, 0x3fb8aa3b, v18
	v_cmp_gt_f32_e32 vcc, s86, v28
	v_cvt_pk_bf16_f32 v23, v24, v25
	s_nop 0
	v_cndmask_b32_e32 v28, 0, v235, vcc
	v_fmac_f32_e32 v28, 0x3fb8aa3b, v18
; DI unsigned cvt_pk_bf16(float lo, float hi) { const f32x2_t v = {lo, hi}; const bf16v2_t b = __builtin_convertvector(v, bf16v2_t); return __builtin_bit_cast(unsigned, b); }
; DI f32x4 mfma16(bf16x8 a, bf16x8 b, f32x4 c) { return __builtin_amdgcn_mfma_f32_16x16x32_bf16(a, b, c, 0, 0, 0); }
; DI void mem_attn_item(ldsp lds, const bf16_t* proj, int ldp, int qmcol, int gatecol, const bf16_t* kv, bf16_t* branch, int b0, int item, int tid, int wid, int lane, const bool stage = true) {
;     ...
;     float den = 0.f;
; #pragma unroll
;     for (int t = 0; t < 16; ++t)
; #pragma unroll
;         for (int j = 0; j < 4; ++j) { const float pv = exp2f((sacc[t][j] - mx) * 1.4426950408889634f); sacc[t][j] = pv; den += pv; }
;     den += __shfl_xor(den, 16); den += __shfl_xor(den, 32);
;     f32x4 oacc[4];
; #pragma unroll
;     for (int dt = 0; dt < 4; ++dt) oacc[dt] = (f32x4){0.f, 0.f, 0.f, 0.f};
; #pragma unroll
;     for (int kt = 0; kt < 8; ++kt) {
;         u32x4 pw; pw.x = cvt_pk_bf16(sacc[2 * kt][0], sacc[2 * kt][1]); pw.y = cvt_pk_bf16(sacc[2 * kt][2], sacc[2 * kt][3]);
;         pw.z = cvt_pk_bf16(sacc[2 * kt + 1][0], sacc[2 * kt + 1][1]); pw.w = cvt_pk_bf16(sacc[2 * kt + 1][2], sacc[2 * kt + 1][3]);
;         const bf16x8 pf = __builtin_bit_cast(bf16x8, pw);
;         const ldsp va = Vb + (32 * kt + quad * 4 + (li >> 2)) * KS + (li & 3) * 8;
; #pragma unroll
;         for (int dt = 0; dt < 4; ++dt) oacc[dt] = mfma16(lds_tr8(va + dt * 32, va + 16 * KS + dt * 32), pf, oacc[dt]);
;     }
	v_exp_f32_e32 v18, v28
	v_cndmask_b32_e32 v28, 0, v236, vcc
	v_ldexp_f32 v28, v18, v28
	v_add_f32_e32 v18, v28, v29
	v_mul_f32_e32 v29, 0x3fb8aa3b, v19
	v_cmp_gt_f32_e32 vcc, s86, v29
	s_nop 1
	v_cndmask_b32_e32 v29, 0, v235, vcc
	v_fmac_f32_e32 v29, 0x3fb8aa3b, v19
	v_exp_f32_e32 v19, v29
	v_cndmask_b32_e32 v29, 0, v236, vcc
	v_ldexp_f32 v29, v19, v29
	v_fma_f32 v19, v20, s85, -v72
	v_mul_f32_e32 v20, 0x3fb8aa3b, v19
	v_cmp_gt_f32_e32 vcc, s86, v20
	v_add_f32_e32 v18, v29, v18
	v_cvt_pk_bf16_f32 v24, v28, v29
	v_cndmask_b32_e32 v20, 0, v235, vcc
	v_fmac_f32_e32 v20, 0x3fb8aa3b, v19
	v_exp_f32_e32 v19, v20
	v_cndmask_b32_e32 v20, 0, v236, vcc
	v_ldexp_f32 v20, v19, v20
	v_fma_f32 v19, v21, s85, -v72
	v_mul_f32_e32 v21, 0x3fb8aa3b, v19
	v_cmp_gt_f32_e32 vcc, s86, v21
	ds_read_b64_tr_b16 v[72:73], v97 offset:39168
	ds_read_b64_tr_b16 v[70:71], v97 offset:36864
	ds_read_b64_tr_b16 v[108:109], v97 offset:36896
	v_cndmask_b32_e32 v21, 0, v235, vcc
	v_fmac_f32_e32 v21, 0x3fb8aa3b, v19
	v_exp_f32_e32 v19, v21
	v_cndmask_b32_e32 v21, 0, v236, vcc
	ds_read_b64_tr_b16 v[110:111], v97 offset:39200
	ds_read_b64_tr_b16 v[112:113], v97 offset:36928
	ds_read_b64_tr_b16 v[114:115], v97 offset:39232
	v_ldexp_f32 v21, v19, v21
	v_mul_f32_e32 v19, 0x3fb8aa3b, v14
	v_cmp_gt_f32_e32 vcc, s86, v19
	ds_read_b64_tr_b16 v[116:117], v97 offset:36960
	ds_read_b64_tr_b16 v[118:119], v97 offset:39264
	v_cndmask_b32_e32 v19, 0, v235, vcc
	v_fmac_f32_e32 v19, 0x3fb8aa3b, v14
	v_exp_f32_e32 v14, v19
	v_cndmask_b32_e32 v19, 0, v236, vcc
	ds_read_b64_tr_b16 v[54:55], v97 offset:41472
	ds_read_b64_tr_b16 v[56:57], v97 offset:43776
	s_waitcnt lgkmcnt(8)
	v_mfma_f32_16x16x32_bf16 v[70:73], v[70:73], v[66:69], 0
	v_ldexp_f32 v14, v14, v19
	v_mul_f32_e32 v19, 0x3fb8aa3b, v15
	v_cmp_gt_f32_e32 vcc, s86, v19
	s_waitcnt lgkmcnt(6)
	v_mfma_f32_16x16x32_bf16 v[108:111], v[108:111], v[66:69], 0
	v_cvt_pk_bf16_f32 v25, v20, v21
	v_cndmask_b32_e32 v19, 0, v235, vcc
	v_fmac_f32_e32 v19, 0x3fb8aa3b, v15
	v_exp_f32_e32 v15, v19
	v_cndmask_b32_e32 v19, 0, v236, vcc
	s_waitcnt lgkmcnt(4)
	v_mfma_f32_16x16x32_bf16 v[112:115], v[112:115], v[66:69], 0
	v_add_f32_e32 v18, v20, v18
	v_ldexp_f32 v15, v15, v19
	v_mul_f32_e32 v19, 0x3fb8aa3b, v16
	v_cmp_gt_f32_e32 vcc, s86, v19
	s_waitcnt lgkmcnt(2)
	v_mfma_f32_16x16x32_bf16 v[64:67], v[116:119], v[66:69], 0
	v_add_f32_e32 v18, v21, v18
	v_cndmask_b32_e32 v19, 0, v235, vcc
	v_fmac_f32_e32 v19, 0x3fb8aa3b, v16
	v_exp_f32_e32 v16, v19
	v_cndmask_b32_e32 v19, 0, v236, vcc
	s_waitcnt lgkmcnt(0)
	v_mfma_f32_16x16x32_bf16 v[54:57], v[54:57], v[58:61], v[70:73]
	ds_read_b64_tr_b16 v[68:69], v97 offset:41504
	s_nop 1
	ds_read_b64_tr_b16 v[70:71], v97 offset:43808
	v_ldexp_f32 v16, v16, v19
	v_mul_f32_e32 v19, 0x3fb8aa3b, v17
	v_cmp_gt_f32_e32 vcc, s86, v19
	s_waitcnt lgkmcnt(0)
	v_mfma_f32_16x16x32_bf16 v[68:71], v[68:71], v[58:61], v[108:111]
	v_cndmask_b32_e32 v19, 0, v235, vcc
	v_fmac_f32_e32 v19, 0x3fb8aa3b, v17
	v_exp_f32_e32 v17, v19
	v_cndmask_b32_e32 v19, 0, v236, vcc
	ds_read_b64_tr_b16 v[108:109], v97 offset:41536
	ds_read_b64_tr_b16 v[110:111], v97 offset:43840
	s_waitcnt lgkmcnt(0)
	v_mfma_f32_16x16x32_bf16 v[108:111], v[108:111], v[58:61], v[112:115]
	v_ldexp_f32 v17, v17, v19
	v_mul_f32_e32 v19, 0x3fb8aa3b, v8
	v_cmp_gt_f32_e32 vcc, s86, v19
	ds_read_b64_tr_b16 v[112:113], v97 offset:41568
	ds_read_b64_tr_b16 v[114:115], v97 offset:43872
	v_cndmask_b32_e32 v19, 0, v235, vcc
	v_fmac_f32_e32 v19, 0x3fb8aa3b, v8
	v_exp_f32_e32 v8, v19
	v_cndmask_b32_e32 v19, 0, v236, vcc
	ds_read_b64_tr_b16 v[46:47], v97 offset:46080
	ds_read_b64_tr_b16 v[48:49], v97 offset:48384
	s_waitcnt lgkmcnt(0)
	v_mfma_f32_16x16x32_bf16 v[46:49], v[46:49], v[50:53], v[54:57]
	v_ldexp_f32 v8, v8, v19
	v_mul_f32_e32 v19, 0x3fb8aa3b, v9
	v_cmp_gt_f32_e32 vcc, s86, v19
	ds_read_b64_tr_b16 v[54:55], v97 offset:46112
	ds_read_b64_tr_b16 v[56:57], v97 offset:48416
	v_cndmask_b32_e32 v19, 0, v235, vcc
	v_fmac_f32_e32 v19, 0x3fb8aa3b, v9
	v_exp_f32_e32 v9, v19
	v_cndmask_b32_e32 v19, 0, v236, vcc
	v_mfma_f32_16x16x32_bf16 v[58:61], v[112:115], v[58:61], v[64:67]
	s_nop 2
	ds_read_b64_tr_b16 v[64:65], v97 offset:46144
	ds_read_b64_tr_b16 v[66:67], v97 offset:48448
	v_ldexp_f32 v9, v9, v19
	v_mul_f32_e32 v19, 0x3fb8aa3b, v10
	v_cmp_gt_f32_e32 vcc, s86, v19
	s_waitcnt lgkmcnt(2)
	v_mfma_f32_16x16x32_bf16 v[54:57], v[54:57], v[50:53], v[68:71]
	s_nop 2
	ds_read_b64_tr_b16 v[68:69], v97 offset:46176
	ds_read_b64_tr_b16 v[70:71], v97 offset:48480
	v_cndmask_b32_e32 v19, 0, v235, vcc
	v_fmac_f32_e32 v19, 0x3fb8aa3b, v10
	v_exp_f32_e32 v10, v19
	v_cndmask_b32_e32 v19, 0, v236, vcc
	ds_read_b64_tr_b16 v[38:39], v97 offset:50688
	ds_read_b64_tr_b16 v[40:41], v97 offset:52992
	s_waitcnt lgkmcnt(0)
	v_mfma_f32_16x16x32_bf16 v[38:41], v[38:41], v[42:45], v[46:49]
	v_ldexp_f32 v10, v10, v19
	v_mul_f32_e32 v19, 0x3fb8aa3b, v11
	v_cmp_gt_f32_e32 vcc, s86, v19
	ds_read_b64_tr_b16 v[46:47], v97 offset:50720
	ds_read_b64_tr_b16 v[48:49], v97 offset:53024
	v_cndmask_b32_e32 v19, 0, v235, vcc
	v_fmac_f32_e32 v19, 0x3fb8aa3b, v11
	v_exp_f32_e32 v11, v19
	v_cndmask_b32_e32 v19, 0, v236, vcc
	v_mfma_f32_16x16x32_bf16 v[64:67], v[64:67], v[50:53], v[108:111]
	v_add_f32_e32 v18, v14, v18
	v_ldexp_f32 v11, v11, v19
	v_mul_f32_e32 v19, 0x3fb8aa3b, v4
	v_cmp_gt_f32_e32 vcc, s86, v19
	v_mfma_f32_16x16x32_bf16 v[50:53], v[68:71], v[50:53], v[58:61]
	v_add_f32_e32 v18, v15, v18
	v_cndmask_b32_e32 v19, 0, v235, vcc
	v_fmac_f32_e32 v19, 0x3fb8aa3b, v4
	v_exp_f32_e32 v4, v19
	v_cndmask_b32_e32 v19, 0, v236, vcc
	s_waitcnt lgkmcnt(0)
; DI unsigned cvt_pk_bf16(float lo, float hi) { const f32x2_t v = {lo, hi}; const bf16v2_t b = __builtin_convertvector(v, bf16v2_t); return __builtin_bit_cast(unsigned, b); }
; DI f32x4 mfma16(bf16x8 a, bf16x8 b, f32x4 c) { return __builtin_amdgcn_mfma_f32_16x16x32_bf16(a, b, c, 0, 0, 0); }
; DI void mem_attn_item(ldsp lds, const bf16_t* proj, int ldp, int qmcol, int gatecol, const bf16_t* kv, bf16_t* branch, int b0, int item, int tid, int wid, int lane, const bool stage = true) {
;     ...
;     float den = 0.f;
; #pragma unroll
;     for (int t = 0; t < 16; ++t)
; #pragma unroll
;         for (int j = 0; j < 4; ++j) { const float pv = exp2f((sacc[t][j] - mx) * 1.4426950408889634f); sacc[t][j] = pv; den += pv; }
;     den += __shfl_xor(den, 16); den += __shfl_xor(den, 32);
;     f32x4 oacc[4];
; #pragma unroll
;     for (int dt = 0; dt < 4; ++dt) oacc[dt] = (f32x4){0.f, 0.f, 0.f, 0.f};
; #pragma unroll
;     for (int kt = 0; kt < 8; ++kt) {
;         u32x4 pw; pw.x = cvt_pk_bf16(sacc[2 * kt][0], sacc[2 * kt][1]); pw.y = cvt_pk_bf16(sacc[2 * kt][2], sacc[2 * kt][3]);
;         pw.z = cvt_pk_bf16(sacc[2 * kt + 1][0], sacc[2 * kt + 1][1]); pw.w = cvt_pk_bf16(sacc[2 * kt + 1][2], sacc[2 * kt + 1][3]);
;         const bf16x8 pf = __builtin_bit_cast(bf16x8, pw);
;         const ldsp va = Vb + (32 * kt + quad * 4 + (li >> 2)) * KS + (li & 3) * 8;
; #pragma unroll
;         for (int dt = 0; dt < 4; ++dt) oacc[dt] = mfma16(lds_tr8(va + dt * 32, va + 16 * KS + dt * 32), pf, oacc[dt]);
;     }
	v_mfma_f32_16x16x32_bf16 v[46:49], v[46:49], v[42:45], v[54:57]
	s_nop 2
	ds_read_b64_tr_b16 v[54:55], v97 offset:50752
	ds_read_b64_tr_b16 v[56:57], v97 offset:53056
	v_ldexp_f32 v4, v4, v19
	v_mul_f32_e32 v19, 0x3fb8aa3b, v5
	v_cmp_gt_f32_e32 vcc, s86, v19
	ds_read_b64_tr_b16 v[58:59], v97 offset:50784
	ds_read_b64_tr_b16 v[60:61], v97 offset:53088
	v_cndmask_b32_e32 v19, 0, v235, vcc
	v_fmac_f32_e32 v19, 0x3fb8aa3b, v5
	v_exp_f32_e32 v5, v19
	v_cndmask_b32_e32 v19, 0, v236, vcc
	s_waitcnt lgkmcnt(2)
	v_mfma_f32_16x16x32_bf16 v[54:57], v[54:57], v[42:45], v[64:67]
	v_add_f32_e32 v18, v16, v18
	v_ldexp_f32 v5, v5, v19
	v_mul_f32_e32 v19, 0x3fb8aa3b, v6
	v_cmp_gt_f32_e32 vcc, s86, v19
	s_waitcnt lgkmcnt(0)
	v_mfma_f32_16x16x32_bf16 v[42:45], v[58:61], v[42:45], v[50:53]
	s_nop 2
	ds_read_b64_tr_b16 v[50:51], v97 offset:55296
	ds_read_b64_tr_b16 v[52:53], v97 offset:57600
	v_cndmask_b32_e32 v19, 0, v235, vcc
	v_fmac_f32_e32 v19, 0x3fb8aa3b, v6
	v_exp_f32_e32 v6, v19
	v_cndmask_b32_e32 v19, 0, v236, vcc
	s_waitcnt lgkmcnt(0)
	v_mfma_f32_16x16x32_bf16 v[38:41], v[50:53], v[34:37], v[38:41]
	ds_read_b64_tr_b16 v[50:51], v97 offset:55328
	ds_read_b64_tr_b16 v[52:53], v97 offset:57632
	v_ldexp_f32 v6, v6, v19
	v_mul_f32_e32 v19, 0x3fb8aa3b, v7
	v_cmp_gt_f32_e32 vcc, s86, v19
	s_waitcnt lgkmcnt(0)
	v_mfma_f32_16x16x32_bf16 v[46:49], v[50:53], v[34:37], v[46:49]
	v_cndmask_b32_e32 v19, 0, v235, vcc
	v_fmac_f32_e32 v19, 0x3fb8aa3b, v7
	v_exp_f32_e32 v7, v19
	v_cndmask_b32_e32 v19, 0, v236, vcc
	ds_read_b64_tr_b16 v[50:51], v97 offset:55360
	ds_read_b64_tr_b16 v[52:53], v97 offset:57664
	s_waitcnt lgkmcnt(0)
	v_mfma_f32_16x16x32_bf16 v[50:53], v[50:53], v[34:37], v[54:57]
	v_ldexp_f32 v7, v7, v19
	v_mul_f32_e32 v19, 0x3fb8aa3b, v0
	v_cmp_gt_f32_e32 vcc, s86, v19
	ds_read_b64_tr_b16 v[54:55], v97 offset:55392
	ds_read_b64_tr_b16 v[56:57], v97 offset:57696
	v_cndmask_b32_e32 v19, 0, v235, vcc
	v_fmac_f32_e32 v19, 0x3fb8aa3b, v0
	v_exp_f32_e32 v0, v19
	ds_read_b64_tr_b16 v[26:27], v97 offset:59904
	ds_read_b64_tr_b16 v[28:29], v97 offset:62208
	v_cndmask_b32_e32 v19, 0, v236, vcc
	s_waitcnt lgkmcnt(0)
	v_mfma_f32_16x16x32_bf16 v[26:29], v[26:29], v[22:25], v[38:41]
	v_ldexp_f32 v0, v0, v19
	v_mul_f32_e32 v19, 0x3fb8aa3b, v1
	v_cmp_gt_f32_e32 vcc, s86, v19
	ds_read_b64_tr_b16 v[38:39], v97 offset:59936
	ds_read_b64_tr_b16 v[40:41], v97 offset:62240
	v_cndmask_b32_e32 v19, 0, v235, vcc
	v_fmac_f32_e32 v19, 0x3fb8aa3b, v1
	v_exp_f32_e32 v1, v19
	v_mfma_f32_16x16x32_bf16 v[34:37], v[54:57], v[34:37], v[42:45]
	s_nop 2
	ds_read_b64_tr_b16 v[42:43], v97 offset:59968
	ds_read_b64_tr_b16 v[44:45], v97 offset:62272
	v_add_f32_e32 v18, v17, v18
	v_cndmask_b32_e32 v19, 0, v236, vcc
	s_waitcnt lgkmcnt(2)
	v_mfma_f32_16x16x32_bf16 v[38:41], v[38:41], v[22:25], v[46:49]
	s_nop 2
	ds_read_b64_tr_b16 v[46:47], v97 offset:60000
	ds_read_b64_tr_b16 v[48:49], v97 offset:62304
	v_add_f32_e32 v18, v8, v18
	v_ldexp_f32 v1, v1, v19
	v_mul_f32_e32 v19, 0x3fb8aa3b, v2
	v_add_f32_e32 v18, v9, v18
	v_cmp_gt_f32_e32 vcc, s86, v19
	v_add_f32_e32 v18, v10, v18
	v_add_f32_e32 v18, v11, v18
	v_cndmask_b32_e32 v19, 0, v235, vcc
	v_fmac_f32_e32 v19, 0x3fb8aa3b, v2
	s_waitcnt lgkmcnt(2)
	v_mfma_f32_16x16x32_bf16 v[42:45], v[42:45], v[22:25], v[50:53]
	v_cvt_pk_bf16_f32 v14, v14, v15
	v_cvt_pk_bf16_f32 v15, v16, v17
	v_cvt_pk_bf16_f32 v16, v8, v9
	s_waitcnt lgkmcnt(0)
	v_mfma_f32_16x16x32_bf16 v[20:23], v[46:49], v[22:25], v[34:37]
	v_cvt_pk_bf16_f32 v17, v10, v11
	ds_read_b64_tr_b16 v[8:9], v97 offset:64512
	ds_read_b64_tr_b16 v[10:11], v98 offset:29952
	ds_read_b64_tr_b16 v[36:37], v98 offset:29984
	ds_read_b64_tr_b16 v[34:35], v97 offset:64544
	v_exp_f32_e32 v2, v19
	v_cndmask_b32_e32 v19, 0, v236, vcc
	v_add_f32_e32 v18, v4, v18
	v_add_f32_e32 v18, v5, v18
	v_ldexp_f32 v2, v2, v19
	v_mul_f32_e32 v19, 0x3fb8aa3b, v3
	v_cmp_gt_f32_e32 vcc, s86, v19
	v_add_f32_e32 v18, v6, v18
	s_waitcnt lgkmcnt(2)
	v_mfma_f32_16x16x32_bf16 v[8:11], v[8:11], v[14:17], v[26:29]
	v_cndmask_b32_e32 v19, 0, v235, vcc
	v_fmac_f32_e32 v19, 0x3fb8aa3b, v3
	v_exp_f32_e32 v3, v19
	s_waitcnt lgkmcnt(0)
	v_mfma_f32_16x16x32_bf16 v[24:27], v[34:37], v[14:17], v[38:41]
	ds_read_b64_tr_b16 v[34:35], v97 offset:64576
	ds_read_b64_tr_b16 v[36:37], v98 offset:30016
	s_nop 0
	ds_read_b64_tr_b16 v[38:39], v97 offset:64608
	ds_read_b64_tr_b16 v[40:41], v98 offset:30048
	v_add_f32_e32 v18, v7, v18
	v_add_f32_e32 v18, v0, v18
	v_add_f32_e32 v18, v1, v18
	v_cndmask_b32_e32 v19, 0, v236, vcc
	v_add_f32_e32 v18, v2, v18
	v_ldexp_f32 v3, v3, v19
; DI unsigned cvt_pk_bf16(float lo, float hi) { const f32x2_t v = {lo, hi}; const bf16v2_t b = __builtin_convertvector(v, bf16v2_t); return __builtin_bit_cast(unsigned, b); }
; DI float bf_lo(unsigned u) { return __uint_as_float(u << 16); }
; DI float bf_hi(unsigned u) { return __uint_as_float(u & 0xffff0000u); }
; DI f32x4 mfma16(bf16x8 a, bf16x8 b, f32x4 c) { return __builtin_amdgcn_mfma_f32_16x16x32_bf16(a, b, c, 0, 0, 0); }
; DI float silu_f(float x) { return x / (1.0f + __expf(-x)); }
; DI void mem_attn_item(ldsp lds, const bf16_t* proj, int ldp, int qmcol, int gatecol, const bf16_t* kv, bf16_t* branch, int b0, int item, int tid, int wid, int lane, const bool stage = true) {
;     ...
;     den += __shfl_xor(den, 16); den += __shfl_xor(den, 32);
;     f32x4 oacc[4];
; #pragma unroll
;     for (int dt = 0; dt < 4; ++dt) oacc[dt] = (f32x4){0.f, 0.f, 0.f, 0.f};
; #pragma unroll
;     for (int kt = 0; kt < 8; ++kt) {
;         u32x4 pw; pw.x = cvt_pk_bf16(sacc[2 * kt][0], sacc[2 * kt][1]); pw.y = cvt_pk_bf16(sacc[2 * kt][2], sacc[2 * kt][3]);
;         pw.z = cvt_pk_bf16(sacc[2 * kt + 1][0], sacc[2 * kt + 1][1]); pw.w = cvt_pk_bf16(sacc[2 * kt + 1][2], sacc[2 * kt + 1][3]);
;         const bf16x8 pf = __builtin_bit_cast(bf16x8, pw);
;         const ldsp va = Vb + (32 * kt + quad * 4 + (li >> 2)) * KS + (li & 3) * 8;
; #pragma unroll
;         for (int dt = 0; dt < 4; ++dt) oacc[dt] = mfma16(lds_tr8(va + dt * 32, va + 16 * KS + dt * 32), pf, oacc[dt]);
;     }
;     const float inv = 1.0f / den;
;     bf16_t* dst = branch + ((size_t)(b0 + bl) * 2048 + tq) * 1024 + 768 + hm * 64 + quad * 4;
; #pragma unroll
;     for (int dt = 0; dt < 4; ++dt) {
;         const u32x2 gt = gtv[dt];
;         u32x2 o;
;         o.x = cvt_pk_bf16(oacc[dt][0] * inv * silu_f(bf_lo(gt.x)), oacc[dt][1] * inv * silu_f(bf_hi(gt.x)));
;         o.y = cvt_pk_bf16(oacc[dt][2] * inv * silu_f(bf_lo(gt.y)), oacc[dt][3] * inv * silu_f(bf_hi(gt.y)));
;         *(u32x2*)(dst + dt * 16) = o;
;     }
.Lma_join_gla:
	v_add_f32_e32 v18, v3, v18
	s_waitcnt lgkmcnt(0)
	v_mfma_f32_16x16x32_bf16 v[20:23], v[38:41], v[14:17], v[20:23]
	v_cvt_pk_bf16_f32 v40, v0, v1
	v_cvt_pk_bf16_f32 v41, v2, v3
	ds_read_b64_tr_b16 v[0:1], v98 offset:32256
	ds_read_b64_tr_b16 v[2:3], v98 offset:34560
	v_cvt_pk_bf16_f32 v38, v4, v5
	v_cvt_pk_bf16_f32 v39, v6, v7
	v_mfma_f32_16x16x32_bf16 v[34:37], v[34:37], v[14:17], v[42:45]
	ds_bpermute_b32 v19, v33, v18
	s_waitcnt lgkmcnt(0)
	v_add_f32_e32 v18, v18, v19
	v_mfma_f32_16x16x32_bf16 v[14:17], v[0:3], v[38:41], v[8:11]
	ds_read_b64_tr_b16 v[0:1], v98 offset:32288
	ds_read_b64_tr_b16 v[2:3], v98 offset:34592
	ds_bpermute_b32 v19, v96, v18
	s_waitcnt lgkmcnt(0)
	v_add_f32_e32 v18, v18, v19
	v_mfma_f32_16x16x32_bf16 v[8:11], v[0:3], v[38:41], v[24:27]
	ds_read_b64_tr_b16 v[0:1], v98 offset:32320
	ds_read_b64_tr_b16 v[2:3], v98 offset:34624
	v_div_scale_f32 v19, s[22:23], v18, v18, 1.0
	s_waitcnt lgkmcnt(0)
	v_mfma_f32_16x16x32_bf16 v[4:7], v[0:3], v[38:41], v[34:37]
	ds_read_b64_tr_b16 v[0:1], v98 offset:32352
	ds_read_b64_tr_b16 v[2:3], v98 offset:34656
	s_waitcnt vmcnt(3)
	v_and_b32_e32 v24, 0xffff0000, v92
	s_waitcnt lgkmcnt(0)
	v_mfma_f32_16x16x32_bf16 v[0:3], v[0:3], v[38:41], v[20:23]
	s_nop 2
	v_rcp_f32_e32 v20, v19
	s_nop 0
	v_fma_f32 v21, -v19, v20, 1.0
	v_fmac_f32_e32 v20, v21, v20
	v_div_scale_f32 v21, vcc, 1.0, v18, 1.0
	v_mul_f32_e32 v22, v21, v20
	v_fma_f32 v23, -v19, v22, v21
	v_fmac_f32_e32 v22, v23, v20
	v_fma_f32 v19, -v19, v22, v21
	v_lshlrev_b32_e32 v21, 16, v92
	v_div_fmas_f32 v19, v19, v20, v22
	v_mul_f32_e32 v22, 0xbfb8aa3b, v21
	v_mul_f32_e32 v23, 0xbfb8aa3b, v24
	v_exp_f32_e32 v22, v22
	v_exp_f32_e32 v23, v23
	v_div_fixup_f32 v20, v19, v18, 1.0
	v_pk_mul_f32 v[14:15], v[20:21], v[14:15] op_sel_hi:[0,1]
	v_lshlrev_b64 v[18:19], 11, v[94:95]
	v_pk_add_f32 v[22:23], v[22:23], 1.0 op_sel_hi:[1,0]
	v_lshl_add_u64 v[18:19], v[80:81], 0, v[18:19]
	v_div_scale_f32 v25, s[22:23], v23, v23, v24
	v_rcp_f32_e32 v26, v25
	s_nop 0
	v_fma_f32 v27, -v25, v26, 1.0
	v_fmac_f32_e32 v26, v27, v26
	v_div_scale_f32 v27, vcc, v24, v23, v24
	v_mul_f32_e32 v28, v27, v26
	v_fma_f32 v29, -v25, v28, v27
	v_fmac_f32_e32 v28, v29, v26
	v_fma_f32 v25, -v25, v28, v27
	v_div_fmas_f32 v25, v25, v26, v28
	v_div_fixup_f32 v23, v25, v23, v24
	v_div_scale_f32 v24, s[22:23], v22, v22, v21
	v_rcp_f32_e32 v25, v24
	s_nop 0
	v_fma_f32 v26, -v24, v25, 1.0
	v_fmac_f32_e32 v25, v26, v25
	v_div_scale_f32 v26, vcc, v21, v22, v21
	v_mul_f32_e32 v27, v26, v25
	v_fma_f32 v28, -v24, v27, v26
	v_fmac_f32_e32 v27, v28, v25
	v_fma_f32 v24, -v24, v27, v26
	v_div_fmas_f32 v24, v24, v25, v27
	v_div_fixup_f32 v22, v24, v22, v21
	v_pk_mul_f32 v[14:15], v[22:23], v[14:15]
	v_and_b32_e32 v21, 0xffff0000, v93
	v_cvt_pk_bf16_f32 v14, v14, v15
	v_lshlrev_b32_e32 v15, 16, v93
	v_mul_f32_e32 v22, 0xbfb8aa3b, v15
	v_mul_f32_e32 v23, 0xbfb8aa3b, v21
	v_exp_f32_e32 v22, v22
	v_exp_f32_e32 v23, v23
	v_pk_mul_f32 v[16:17], v[20:21], v[16:17] op_sel_hi:[0,1]
	v_pk_add_f32 v[22:23], v[22:23], 1.0 op_sel_hi:[1,0]
	s_nop 0
	v_div_scale_f32 v24, s[22:23], v23, v23, v21
	v_rcp_f32_e32 v25, v24
	s_nop 0
	v_fma_f32 v26, -v24, v25, 1.0
	v_fmac_f32_e32 v25, v26, v25
	v_div_scale_f32 v26, vcc, v21, v23, v21
	v_mul_f32_e32 v27, v26, v25
	v_fma_f32 v28, -v24, v27, v26
	v_fmac_f32_e32 v27, v28, v25
	v_fma_f32 v24, -v24, v27, v26
	v_div_fmas_f32 v24, v24, v25, v27
	v_div_fixup_f32 v23, v24, v23, v21
	v_div_scale_f32 v21, s[22:23], v22, v22, v15
	v_rcp_f32_e32 v24, v21
	s_nop 0
	v_fma_f32 v25, -v21, v24, 1.0
	v_fmac_f32_e32 v24, v25, v24
	v_div_scale_f32 v25, vcc, v15, v22, v15
	v_mul_f32_e32 v26, v25, v24
	v_fma_f32 v27, -v21, v26, v25
	v_fmac_f32_e32 v26, v27, v24
	v_fma_f32 v21, -v21, v26, v25
	v_div_fmas_f32 v21, v21, v24, v26
	v_div_fixup_f32 v22, v21, v22, v15
	v_pk_mul_f32 v[16:17], v[22:23], v[16:17]
	v_pk_mul_f32 v[8:9], v[20:21], v[8:9] op_sel_hi:[0,1]
	v_cvt_pk_bf16_f32 v15, v16, v17
	s_waitcnt vmcnt(2)
	v_lshlrev_b32_e32 v16, 16, v90
	v_and_b32_e32 v17, 0xffff0000, v90
	global_store_dwordx2 v[18:19], v[14:15], off offset:1536
	v_mul_f32_e32 v14, 0xbfb8aa3b, v16
	v_mul_f32_e32 v15, 0xbfb8aa3b, v17
	v_exp_f32_e32 v14, v14
	v_exp_f32_e32 v15, v15
	s_nop 0
	v_pk_add_f32 v[14:15], v[14:15], 1.0 op_sel_hi:[1,0]
	s_nop 0
	v_div_scale_f32 v21, s[22:23], v15, v15, v17
	v_rcp_f32_e32 v22, v21
	s_nop 0
	v_fma_f32 v23, -v21, v22, 1.0
	v_fmac_f32_e32 v22, v23, v22
	v_div_scale_f32 v23, vcc, v17, v15, v17
	v_mul_f32_e32 v24, v23, v22
	v_fma_f32 v25, -v21, v24, v23
	v_fmac_f32_e32 v24, v25, v22
	v_fma_f32 v21, -v21, v24, v23
	v_div_fmas_f32 v21, v21, v22, v24
	v_div_fixup_f32 v15, v21, v15, v17
	v_div_scale_f32 v17, s[22:23], v14, v14, v16
	v_rcp_f32_e32 v21, v17
	s_nop 0
	v_fma_f32 v22, -v17, v21, 1.0
	v_fmac_f32_e32 v21, v22, v21
	v_div_scale_f32 v22, vcc, v16, v14, v16
	v_mul_f32_e32 v23, v22, v21
	v_fma_f32 v24, -v17, v23, v22
	v_fmac_f32_e32 v23, v24, v21
	v_fma_f32 v17, -v17, v23, v22
	v_div_fmas_f32 v17, v17, v21, v23
	v_div_fixup_f32 v14, v17, v14, v16
	v_pk_mul_f32 v[8:9], v[14:15], v[8:9]
	v_and_b32_e32 v16, 0xffff0000, v91
	v_cvt_pk_bf16_f32 v8, v8, v9
	v_lshlrev_b32_e32 v9, 16, v91
	v_mul_f32_e32 v14, 0xbfb8aa3b, v9
	v_mul_f32_e32 v15, 0xbfb8aa3b, v16
	v_exp_f32_e32 v14, v14
	v_exp_f32_e32 v15, v15
	v_pk_mul_f32 v[10:11], v[20:21], v[10:11] op_sel_hi:[0,1]
	v_pk_add_f32 v[14:15], v[14:15], 1.0 op_sel_hi:[1,0]
	s_nop 0
	v_div_scale_f32 v17, s[22:23], v15, v15, v16
	v_rcp_f32_e32 v21, v17
	s_nop 0
	v_fma_f32 v22, -v17, v21, 1.0
	v_fmac_f32_e32 v21, v22, v21
	v_div_scale_f32 v22, vcc, v16, v15, v16
	v_mul_f32_e32 v23, v22, v21
	v_fma_f32 v24, -v17, v23, v22
	v_fmac_f32_e32 v23, v24, v21
	v_fma_f32 v17, -v17, v23, v22
	v_div_fmas_f32 v17, v17, v21, v23
	v_div_fixup_f32 v15, v17, v15, v16
	v_div_scale_f32 v16, s[22:23], v14, v14, v9
	v_rcp_f32_e32 v17, v16
	s_nop 0
	v_fma_f32 v21, -v16, v17, 1.0
	v_fmac_f32_e32 v17, v21, v17
	v_div_scale_f32 v21, vcc, v9, v14, v9
	v_mul_f32_e32 v22, v21, v17
	v_fma_f32 v23, -v16, v22, v21
	v_fmac_f32_e32 v22, v23, v17
	v_fma_f32 v16, -v16, v22, v21
	v_div_fmas_f32 v16, v16, v17, v22
	v_div_fixup_f32 v14, v16, v14, v9
	v_pk_mul_f32 v[10:11], v[14:15], v[10:11]
	v_pk_mul_f32 v[4:5], v[20:21], v[4:5] op_sel_hi:[0,1]
	v_cvt_pk_bf16_f32 v9, v10, v11
	s_waitcnt vmcnt(2)
; DI unsigned cvt_pk_bf16(float lo, float hi) { const f32x2_t v = {lo, hi}; const bf16v2_t b = __builtin_convertvector(v, bf16v2_t); return __builtin_bit_cast(unsigned, b); }
; DI float bf_lo(unsigned u) { return __uint_as_float(u << 16); }
; DI float bf_hi(unsigned u) { return __uint_as_float(u & 0xffff0000u); }
; DI float silu_f(float x) { return x / (1.0f + __expf(-x)); }
; DI void mem_attn_item(ldsp lds, const bf16_t* proj, int ldp, int qmcol, int gatecol, const bf16_t* kv, bf16_t* branch, int b0, int item, int tid, int wid, int lane, const bool stage = true) {
;     ...
;     const float inv = 1.0f / den;
;     bf16_t* dst = branch + ((size_t)(b0 + bl) * 2048 + tq) * 1024 + 768 + hm * 64 + quad * 4;
; #pragma unroll
;     for (int dt = 0; dt < 4; ++dt) {
;         const u32x2 gt = gtv[dt];
;         u32x2 o;
;         o.x = cvt_pk_bf16(oacc[dt][0] * inv * silu_f(bf_lo(gt.x)), oacc[dt][1] * inv * silu_f(bf_hi(gt.x)));
;         o.y = cvt_pk_bf16(oacc[dt][2] * inv * silu_f(bf_lo(gt.y)), oacc[dt][3] * inv * silu_f(bf_hi(gt.y)));
;         *(u32x2*)(dst + dt * 16) = o;
;     }
;     __syncthreads();
	v_lshlrev_b32_e32 v10, 16, v88
	v_and_b32_e32 v11, 0xffff0000, v88
	global_store_dwordx2 v[18:19], v[8:9], off offset:1568
	v_mul_f32_e32 v8, 0xbfb8aa3b, v10
	v_mul_f32_e32 v9, 0xbfb8aa3b, v11
	v_exp_f32_e32 v8, v8
	v_exp_f32_e32 v9, v9
	s_nop 0
	v_pk_add_f32 v[8:9], v[8:9], 1.0 op_sel_hi:[1,0]
	s_nop 0
	v_div_scale_f32 v14, s[22:23], v9, v9, v11
	v_rcp_f32_e32 v15, v14
	s_nop 0
	v_fma_f32 v16, -v14, v15, 1.0
	v_fmac_f32_e32 v15, v16, v15
	v_div_scale_f32 v16, vcc, v11, v9, v11
	v_mul_f32_e32 v17, v16, v15
	v_fma_f32 v21, -v14, v17, v16
	v_fmac_f32_e32 v17, v21, v15
	v_fma_f32 v14, -v14, v17, v16
	v_div_fmas_f32 v14, v14, v15, v17
	v_div_fixup_f32 v9, v14, v9, v11
	v_div_scale_f32 v11, s[22:23], v8, v8, v10
	v_rcp_f32_e32 v14, v11
	v_pk_mul_f32 v[6:7], v[20:21], v[6:7] op_sel_hi:[0,1]
	v_pk_mul_f32 v[0:1], v[20:21], v[0:1] op_sel_hi:[0,1]
	v_pk_mul_f32 v[2:3], v[20:21], v[2:3] op_sel_hi:[0,1]
	v_fma_f32 v15, -v11, v14, 1.0
	v_fmac_f32_e32 v14, v15, v14
	v_div_scale_f32 v15, vcc, v10, v8, v10
	v_mul_f32_e32 v16, v15, v14
	v_fma_f32 v17, -v11, v16, v15
	v_fmac_f32_e32 v16, v17, v14
	v_fma_f32 v11, -v11, v16, v15
	v_div_fmas_f32 v11, v11, v14, v16
	v_div_fixup_f32 v8, v11, v8, v10
	v_pk_mul_f32 v[4:5], v[8:9], v[4:5]
	v_and_b32_e32 v10, 0xffff0000, v89
	v_cvt_pk_bf16_f32 v4, v4, v5
	v_lshlrev_b32_e32 v5, 16, v89
	v_mul_f32_e32 v8, 0xbfb8aa3b, v5
	v_mul_f32_e32 v9, 0xbfb8aa3b, v10
	v_exp_f32_e32 v8, v8
	v_exp_f32_e32 v9, v9
	s_nop 0
	v_pk_add_f32 v[8:9], v[8:9], 1.0 op_sel_hi:[1,0]
	s_nop 0
	v_div_scale_f32 v11, s[22:23], v9, v9, v10
	v_rcp_f32_e32 v14, v11
	s_nop 0
	v_fma_f32 v15, -v11, v14, 1.0
	v_fmac_f32_e32 v14, v15, v14
	v_div_scale_f32 v15, vcc, v10, v9, v10
	v_mul_f32_e32 v16, v15, v14
	v_fma_f32 v17, -v11, v16, v15
	v_fmac_f32_e32 v16, v17, v14
	v_fma_f32 v11, -v11, v16, v15
	v_div_fmas_f32 v11, v11, v14, v16
	v_div_fixup_f32 v9, v11, v9, v10
	v_div_scale_f32 v10, s[22:23], v8, v8, v5
	v_rcp_f32_e32 v11, v10
	s_nop 0
	v_fma_f32 v14, -v10, v11, 1.0
	v_fmac_f32_e32 v11, v14, v11
	v_div_scale_f32 v14, vcc, v5, v8, v5
	v_mul_f32_e32 v15, v14, v11
	v_fma_f32 v16, -v10, v15, v14
	v_fmac_f32_e32 v15, v16, v11
	v_fma_f32 v10, -v10, v15, v14
	v_div_fmas_f32 v10, v10, v11, v15
	v_div_fixup_f32 v8, v10, v8, v5
	v_pk_mul_f32 v[6:7], v[8:9], v[6:7]
	s_nop 0
	v_cvt_pk_bf16_f32 v5, v6, v7
	s_waitcnt vmcnt(2)
	v_lshlrev_b32_e32 v6, 16, v86
	v_and_b32_e32 v7, 0xffff0000, v86
	global_store_dwordx2 v[18:19], v[4:5], off offset:1600
	v_mul_f32_e32 v4, 0xbfb8aa3b, v6
	v_mul_f32_e32 v5, 0xbfb8aa3b, v7
	v_exp_f32_e32 v4, v4
	v_exp_f32_e32 v5, v5
	s_nop 0
	v_pk_add_f32 v[4:5], v[4:5], 1.0 op_sel_hi:[1,0]
	s_nop 0
	v_div_scale_f32 v8, s[22:23], v5, v5, v7
	v_rcp_f32_e32 v9, v8
	s_nop 0
	v_fma_f32 v10, -v8, v9, 1.0
	v_fmac_f32_e32 v9, v10, v9
	v_div_scale_f32 v10, vcc, v7, v5, v7
	v_mul_f32_e32 v11, v10, v9
	v_fma_f32 v14, -v8, v11, v10
	v_fmac_f32_e32 v11, v14, v9
	v_fma_f32 v8, -v8, v11, v10
	v_div_fmas_f32 v8, v8, v9, v11
	v_div_fixup_f32 v5, v8, v5, v7
	v_div_scale_f32 v7, s[22:23], v4, v4, v6
	v_rcp_f32_e32 v8, v7
	s_nop 0
	v_fma_f32 v9, -v7, v8, 1.0
	v_fmac_f32_e32 v8, v9, v8
	v_div_scale_f32 v9, vcc, v6, v4, v6
	v_mul_f32_e32 v10, v9, v8
	v_fma_f32 v11, -v7, v10, v9
	v_fmac_f32_e32 v10, v11, v8
	v_fma_f32 v7, -v7, v10, v9
	v_div_fmas_f32 v7, v7, v8, v10
	v_div_fixup_f32 v4, v7, v4, v6
	v_pk_mul_f32 v[0:1], v[4:5], v[0:1]
	v_and_b32_e32 v6, 0xffff0000, v87
	v_cvt_pk_bf16_f32 v0, v0, v1
	v_lshlrev_b32_e32 v1, 16, v87
	v_mul_f32_e32 v4, 0xbfb8aa3b, v1
	v_mul_f32_e32 v5, 0xbfb8aa3b, v6
	v_exp_f32_e32 v4, v4
	v_exp_f32_e32 v5, v5
	s_nop 0
	v_pk_add_f32 v[4:5], v[4:5], 1.0 op_sel_hi:[1,0]
	s_nop 0
	v_div_scale_f32 v7, s[22:23], v5, v5, v6
	v_rcp_f32_e32 v8, v7
	s_nop 0
	v_fma_f32 v9, -v7, v8, 1.0
	v_fmac_f32_e32 v8, v9, v8
	v_div_scale_f32 v9, vcc, v6, v5, v6
	v_mul_f32_e32 v10, v9, v8
	v_fma_f32 v11, -v7, v10, v9
	v_fmac_f32_e32 v10, v11, v8
	v_fma_f32 v7, -v7, v10, v9
	v_div_fmas_f32 v7, v7, v8, v10
	v_div_fixup_f32 v5, v7, v5, v6
	v_div_scale_f32 v6, s[22:23], v4, v4, v1
	v_rcp_f32_e32 v7, v6
	s_nop 0
	v_fma_f32 v8, -v6, v7, 1.0
	v_fmac_f32_e32 v7, v8, v7
	v_div_scale_f32 v8, vcc, v1, v4, v1
	v_mul_f32_e32 v9, v8, v7
	v_fma_f32 v10, -v6, v9, v8
	v_fmac_f32_e32 v9, v10, v7
	v_fma_f32 v6, -v6, v9, v8
	v_div_fmas_f32 v6, v6, v7, v9
	v_div_fixup_f32 v4, v6, v4, v1
	v_pk_mul_f32 v[2:3], v[4:5], v[2:3]
	s_nop 0
	v_cvt_pk_bf16_f32 v1, v2, v3
	global_store_dwordx2 v[18:19], v[0:1], off offset:1632
	s_barrier
	s_cbranch_scc1 .LBB0_514
